# attention loop: split packed f32 adds into scalar adds; proj odd-unit epilogue: software-pipelined Gs/Sb loads (depth 5) with counted vmcnt
# speedup vs baseline: 1.0170x; 1.0170x over previous
; __device__ __forceinline__ unsigned cvt_pk_bf16(float lo, float hi) { const f32x2 v = {lo, hi}; const bf16x2_t b = __builtin_convertvector(v, bf16x2_t); return __builtin_bit_cast(unsigned, b); }
; __device__ __forceinline__ float bf_lo(unsigned u) { return __uint_as_float(u << 16); }
; __device__ __forceinline__ float bf_hi(unsigned u) { return __uint_as_float(u & 0xffff0000u); }
;     __device__ __forceinline__ void operator()(const f32x4 (&acc)[2][2][4][2], const Unit& u, int wr, int wc, int fr, int fq) const {
;     ...
; #pragma unroll
;         for (int ai = 0; ai < 2; ++ai)
; #pragma unroll
;             for (int bj = 0; bj < 2; ++bj)
; #pragma unroll
;                 for (int m = 0; m < 4; ++m) {
;                     const u32x4 g = *((const u32x4*)Gs + ((size_t)(tile * 16 + (ai * 2 + bj) * 4 + m) * NTHREADS + tid));
;                     f32x4 y0 = acc[ai][bj][m][0], y1 = acc[ai][bj][m][1];
;                     y0[0] *= bf_lo(g.x); y0[1] *= bf_hi(g.x); y0[2] *= bf_lo(g.y); y0[3] *= bf_hi(g.y);
;                     y1[0] *= bf_lo(g.z); y1[1] *= bf_hi(g.z); y1[2] *= bf_lo(g.w); y1[3] *= bf_hi(g.w);
;                     u32x4* sp = (u32x4*)Sb + ((size_t)(tile * 16 + (ai * 2 + bj) * 4 + m) * NTHREADS + tid);
;                     if (br != 0) { const u32x4 t = *sp;
;                         y0[0] += bf_lo(t.x); y0[1] += bf_hi(t.x); y0[2] += bf_lo(t.y); y0[3] += bf_hi(t.y); y1[0] += bf_lo(t.z); y1[1] += bf_hi(t.z); y1[2] += bf_lo(t.w); y1[3] += bf_hi(t.w); }
;                     u32x4 w; w.x = cvt_pk_bf16(y0[0], y0[1]); w.y = cvt_pk_bf16(y0[2], y0[3]); w.z = cvt_pk_bf16(y1[0], y1[1]); w.w = cvt_pk_bf16(y1[2], y1[3]);
;                     if (br != 2) *sp = w;
;                     else {
;                         *(u32x4*)(MIXPRE + (size_t)(row0 + ai * 128 + m * 16) * DM + col00 + bj * 128) = w; }
;                 }
.LBB0_305:
	s_lshl_b32 s12, s18, 4
	s_lshl_b32 s13, s12, 9
	v_add_u32_e32 v166, s13, v144
	v_lshlrev_b32_e32 v166, 4, v166
	v_lshl_add_u32 v226, s20, 8, v170
	v_lshlrev_b32_e32 v226, 11, v226
	v_lshl_add_u32 v226, v134, 1, v226
	s_mov_b64 s[12:13], s[14:15]
	s_mov_b64 s[20:21], s[34:35]
	s_mov_b64 s[44:45], s[34:35]
	s_cmp_eq_u32 s19, 0
	s_cbranch_scc1 .Lpl_br0
	s_cmp_eq_u32 s19, 1
	s_cbranch_scc1 .Lpl_br1
	global_load_dwordx4 v[152:155], v166, s[12:13]
	s_add_u32 s12, s12, 0x2000
	s_addc_u32 s13, s13, 0
	global_load_dwordx4 v[182:185], v166, s[20:21]
	s_add_u32 s20, s20, 0x2000
	s_addc_u32 s21, s21, 0
	global_load_dwordx4 v[156:159], v166, s[12:13]
	s_add_u32 s12, s12, 0x2000
	s_addc_u32 s13, s13, 0
	global_load_dwordx4 v[186:189], v166, s[20:21]
	s_add_u32 s20, s20, 0x2000
	s_addc_u32 s21, s21, 0
	global_load_dwordx4 v[160:163], v166, s[12:13]
	s_add_u32 s12, s12, 0x2000
	s_addc_u32 s13, s13, 0
	global_load_dwordx4 v[202:205], v166, s[20:21]
	s_add_u32 s20, s20, 0x2000
	s_addc_u32 s21, s21, 0
	global_load_dwordx4 v[174:177], v166, s[12:13]
	s_add_u32 s12, s12, 0x2000
	s_addc_u32 s13, s13, 0
	global_load_dwordx4 v[206:209], v166, s[20:21]
	s_add_u32 s20, s20, 0x2000
	s_addc_u32 s21, s21, 0
	global_load_dwordx4 v[178:181], v166, s[12:13]
	s_add_u32 s12, s12, 0x2000
	s_addc_u32 s13, s13, 0
	global_load_dwordx4 v[210:213], v166, s[20:21]
	s_add_u32 s20, s20, 0x2000
	s_addc_u32 s21, s21, 0
	s_waitcnt vmcnt(8)
	v_lshlrev_b32_e32 v224, 16, v152
	v_and_b32_e32 v225, 0xffff0000, v152
	v_mul_f32_e32 v132, v126, v224
	v_mul_f32_e32 v133, v127, v225
	v_lshlrev_b32_e32 v224, 16, v153
	v_and_b32_e32 v225, 0xffff0000, v153
	v_mul_f32_e32 v164, v128, v224
	v_mul_f32_e32 v165, v129, v225
	v_lshlrev_b32_e32 v224, 16, v154
	v_and_b32_e32 v225, 0xffff0000, v154
	v_mul_f32_e32 v168, v122, v224
	v_mul_f32_e32 v169, v123, v225
	v_lshlrev_b32_e32 v224, 16, v155
	v_and_b32_e32 v225, 0xffff0000, v155
	v_mul_f32_e32 v222, v124, v224
	v_mul_f32_e32 v223, v125, v225
	v_lshlrev_b32_e32 v224, 16, v182
	v_and_b32_e32 v225, 0xffff0000, v182
	v_add_f32_e32 v132, v132, v224
	v_add_f32_e32 v133, v133, v225
	v_lshlrev_b32_e32 v224, 16, v183
	v_and_b32_e32 v225, 0xffff0000, v183
	v_add_f32_e32 v164, v164, v224
	v_add_f32_e32 v165, v165, v225
	v_lshlrev_b32_e32 v224, 16, v184
	v_and_b32_e32 v225, 0xffff0000, v184
	v_add_f32_e32 v168, v168, v224
	v_add_f32_e32 v169, v169, v225
	v_lshlrev_b32_e32 v224, 16, v185
	v_and_b32_e32 v225, 0xffff0000, v185
	v_add_f32_e32 v222, v222, v224
	v_add_f32_e32 v223, v223, v225
	v_cvt_pk_bf16_f32 v214, v132, v133
	v_cvt_pk_bf16_f32 v215, v164, v165
	v_cvt_pk_bf16_f32 v216, v168, v169
	v_cvt_pk_bf16_f32 v217, v222, v223
	s_add_u32 s44, s48, 0x0
	s_addc_u32 s45, s49, 0
	global_store_dwordx4 v226, v[214:217], s[44:45]
	global_load_dwordx4 v[152:155], v166, s[12:13]
	s_add_u32 s12, s12, 0x2000
	s_addc_u32 s13, s13, 0
	global_load_dwordx4 v[182:185], v166, s[20:21]
	s_add_u32 s20, s20, 0x2000
	s_addc_u32 s21, s21, 0
	s_waitcnt vmcnt(9)
	v_lshlrev_b32_e32 v224, 16, v156
	v_and_b32_e32 v225, 0xffff0000, v156
	v_mul_f32_e32 v132, v118, v224
	v_mul_f32_e32 v133, v119, v225
	v_lshlrev_b32_e32 v224, 16, v157
	v_and_b32_e32 v225, 0xffff0000, v157
	v_mul_f32_e32 v164, v120, v224
	v_mul_f32_e32 v165, v121, v225
	v_lshlrev_b32_e32 v224, 16, v158
	v_and_b32_e32 v225, 0xffff0000, v158
	v_mul_f32_e32 v168, v114, v224
	v_mul_f32_e32 v169, v115, v225
	v_lshlrev_b32_e32 v224, 16, v159
	v_and_b32_e32 v225, 0xffff0000, v159
	v_mul_f32_e32 v222, v116, v224
	v_mul_f32_e32 v223, v117, v225
	v_lshlrev_b32_e32 v224, 16, v186
	v_and_b32_e32 v225, 0xffff0000, v186
	v_add_f32_e32 v132, v132, v224
	v_add_f32_e32 v133, v133, v225
	v_lshlrev_b32_e32 v224, 16, v187
	v_and_b32_e32 v225, 0xffff0000, v187
	v_add_f32_e32 v164, v164, v224
	v_add_f32_e32 v165, v165, v225
	v_lshlrev_b32_e32 v224, 16, v188
	v_and_b32_e32 v225, 0xffff0000, v188
	v_add_f32_e32 v168, v168, v224
	v_add_f32_e32 v169, v169, v225
	v_lshlrev_b32_e32 v224, 16, v189
	v_and_b32_e32 v225, 0xffff0000, v189
	v_add_f32_e32 v222, v222, v224
	v_add_f32_e32 v223, v223, v225
	v_cvt_pk_bf16_f32 v218, v132, v133
	v_cvt_pk_bf16_f32 v219, v164, v165
	v_cvt_pk_bf16_f32 v220, v168, v169
	v_cvt_pk_bf16_f32 v221, v222, v223
	s_add_u32 s44, s48, 0x8000
	s_addc_u32 s45, s49, 0
	global_store_dwordx4 v226, v[218:221], s[44:45]
	global_load_dwordx4 v[156:159], v166, s[12:13]
	s_add_u32 s12, s12, 0x2000
	s_addc_u32 s13, s13, 0
	global_load_dwordx4 v[186:189], v166, s[20:21]
	s_add_u32 s20, s20, 0x2000
	s_addc_u32 s21, s21, 0
	s_waitcnt vmcnt(10)
	v_lshlrev_b32_e32 v224, 16, v160
	v_and_b32_e32 v225, 0xffff0000, v160
	v_mul_f32_e32 v132, v110, v224
	v_mul_f32_e32 v133, v111, v225
	v_lshlrev_b32_e32 v224, 16, v161
	v_and_b32_e32 v225, 0xffff0000, v161
	v_mul_f32_e32 v164, v112, v224
	v_mul_f32_e32 v165, v113, v225
	v_lshlrev_b32_e32 v224, 16, v162
	v_and_b32_e32 v225, 0xffff0000, v162
	v_mul_f32_e32 v168, v106, v224
	v_mul_f32_e32 v169, v107, v225
	v_lshlrev_b32_e32 v224, 16, v163
	v_and_b32_e32 v225, 0xffff0000, v163
	v_mul_f32_e32 v222, v108, v224
	v_mul_f32_e32 v223, v109, v225
	v_lshlrev_b32_e32 v224, 16, v202
	v_and_b32_e32 v225, 0xffff0000, v202
	v_add_f32_e32 v132, v132, v224
	v_add_f32_e32 v133, v133, v225
	v_lshlrev_b32_e32 v224, 16, v203
	v_and_b32_e32 v225, 0xffff0000, v203
	v_add_f32_e32 v164, v164, v224
	v_add_f32_e32 v165, v165, v225
	v_lshlrev_b32_e32 v224, 16, v204
	v_and_b32_e32 v225, 0xffff0000, v204
	v_add_f32_e32 v168, v168, v224
	v_add_f32_e32 v169, v169, v225
	v_lshlrev_b32_e32 v224, 16, v205
	v_and_b32_e32 v225, 0xffff0000, v205
	v_add_f32_e32 v222, v222, v224
	v_add_f32_e32 v223, v223, v225
	v_cvt_pk_bf16_f32 v214, v132, v133
	v_cvt_pk_bf16_f32 v215, v164, v165
	v_cvt_pk_bf16_f32 v216, v168, v169
	v_cvt_pk_bf16_f32 v217, v222, v223
	s_add_u32 s44, s48, 0x10000
	s_addc_u32 s45, s49, 0
	global_store_dwordx4 v226, v[214:217], s[44:45]
	global_load_dwordx4 v[160:163], v166, s[12:13]
	s_add_u32 s12, s12, 0x2000
	s_addc_u32 s13, s13, 0
	global_load_dwordx4 v[202:205], v166, s[20:21]
	s_add_u32 s20, s20, 0x2000
	s_addc_u32 s21, s21, 0
	s_waitcnt vmcnt(11)
; __device__ __forceinline__ unsigned cvt_pk_bf16(float lo, float hi) { const f32x2 v = {lo, hi}; const bf16x2_t b = __builtin_convertvector(v, bf16x2_t); return __builtin_bit_cast(unsigned, b); }
; __device__ __forceinline__ float bf_lo(unsigned u) { return __uint_as_float(u << 16); }
; __device__ __forceinline__ float bf_hi(unsigned u) { return __uint_as_float(u & 0xffff0000u); }
;     __device__ __forceinline__ void operator()(const f32x4 (&acc)[2][2][4][2], const Unit& u, int wr, int wc, int fr, int fq) const {
;     ...
;         for (int ai = 0; ai < 2; ++ai)
; #pragma unroll
;             for (int bj = 0; bj < 2; ++bj)
; #pragma unroll
;                 for (int m = 0; m < 4; ++m) {
;                     const u32x4 g = *((const u32x4*)Gs + ((size_t)(tile * 16 + (ai * 2 + bj) * 4 + m) * NTHREADS + tid));
;                     f32x4 y0 = acc[ai][bj][m][0], y1 = acc[ai][bj][m][1];
;                     y0[0] *= bf_lo(g.x); y0[1] *= bf_hi(g.x); y0[2] *= bf_lo(g.y); y0[3] *= bf_hi(g.y);
;                     y1[0] *= bf_lo(g.z); y1[1] *= bf_hi(g.z); y1[2] *= bf_lo(g.w); y1[3] *= bf_hi(g.w);
;                     u32x4* sp = (u32x4*)Sb + ((size_t)(tile * 16 + (ai * 2 + bj) * 4 + m) * NTHREADS + tid);
;                     if (br != 0) { const u32x4 t = *sp;
;                         y0[0] += bf_lo(t.x); y0[1] += bf_hi(t.x); y0[2] += bf_lo(t.y); y0[3] += bf_hi(t.y); y1[0] += bf_lo(t.z); y1[1] += bf_hi(t.z); y1[2] += bf_lo(t.w); y1[3] += bf_hi(t.w); }
;                     u32x4 w; w.x = cvt_pk_bf16(y0[0], y0[1]); w.y = cvt_pk_bf16(y0[2], y0[3]); w.z = cvt_pk_bf16(y1[0], y1[1]); w.w = cvt_pk_bf16(y1[2], y1[3]);
;                     if (br != 2) *sp = w;
;                     else {
;                         *(u32x4*)(MIXPRE + (size_t)(row0 + ai * 128 + m * 16) * DM + col00 + bj * 128) = w; }
;                 }
	v_lshlrev_b32_e32 v224, 16, v174
	v_and_b32_e32 v225, 0xffff0000, v174
	v_mul_f32_e32 v132, v102, v224
	v_mul_f32_e32 v133, v103, v225
	v_lshlrev_b32_e32 v224, 16, v175
	v_and_b32_e32 v225, 0xffff0000, v175
	v_mul_f32_e32 v164, v104, v224
	v_mul_f32_e32 v165, v105, v225
	v_lshlrev_b32_e32 v224, 16, v176
	v_and_b32_e32 v225, 0xffff0000, v176
	v_mul_f32_e32 v168, v98, v224
	v_mul_f32_e32 v169, v99, v225
	v_lshlrev_b32_e32 v224, 16, v177
	v_and_b32_e32 v225, 0xffff0000, v177
	v_mul_f32_e32 v222, v100, v224
	v_mul_f32_e32 v223, v101, v225
	v_lshlrev_b32_e32 v224, 16, v206
	v_and_b32_e32 v225, 0xffff0000, v206
	v_add_f32_e32 v132, v132, v224
	v_add_f32_e32 v133, v133, v225
	v_lshlrev_b32_e32 v224, 16, v207
	v_and_b32_e32 v225, 0xffff0000, v207
	v_add_f32_e32 v164, v164, v224
	v_add_f32_e32 v165, v165, v225
	v_lshlrev_b32_e32 v224, 16, v208
	v_and_b32_e32 v225, 0xffff0000, v208
	v_add_f32_e32 v168, v168, v224
	v_add_f32_e32 v169, v169, v225
	v_lshlrev_b32_e32 v224, 16, v209
	v_and_b32_e32 v225, 0xffff0000, v209
	v_add_f32_e32 v222, v222, v224
	v_add_f32_e32 v223, v223, v225
	v_cvt_pk_bf16_f32 v218, v132, v133
	v_cvt_pk_bf16_f32 v219, v164, v165
	v_cvt_pk_bf16_f32 v220, v168, v169
	v_cvt_pk_bf16_f32 v221, v222, v223
	s_add_u32 s44, s48, 0x18000
	s_addc_u32 s45, s49, 0
	global_store_dwordx4 v226, v[218:221], s[44:45]
	global_load_dwordx4 v[174:177], v166, s[12:13]
	s_add_u32 s12, s12, 0x2000
	s_addc_u32 s13, s13, 0
	global_load_dwordx4 v[206:209], v166, s[20:21]
	s_add_u32 s20, s20, 0x2000
	s_addc_u32 s21, s21, 0
	s_waitcnt vmcnt(12)
	v_lshlrev_b32_e32 v224, 16, v178
	v_and_b32_e32 v225, 0xffff0000, v178
	v_mul_f32_e32 v132, v62, v224
	v_mul_f32_e32 v133, v63, v225
	v_lshlrev_b32_e32 v224, 16, v179
	v_and_b32_e32 v225, 0xffff0000, v179
	v_mul_f32_e32 v164, v64, v224
	v_mul_f32_e32 v165, v65, v225
	v_lshlrev_b32_e32 v224, 16, v180
	v_and_b32_e32 v225, 0xffff0000, v180
	v_mul_f32_e32 v168, v58, v224
	v_mul_f32_e32 v169, v59, v225
	v_lshlrev_b32_e32 v224, 16, v181
	v_and_b32_e32 v225, 0xffff0000, v181
	v_mul_f32_e32 v222, v60, v224
	v_mul_f32_e32 v223, v61, v225
	v_lshlrev_b32_e32 v224, 16, v210
	v_and_b32_e32 v225, 0xffff0000, v210
	v_add_f32_e32 v132, v132, v224
	v_add_f32_e32 v133, v133, v225
	v_lshlrev_b32_e32 v224, 16, v211
	v_and_b32_e32 v225, 0xffff0000, v211
	v_add_f32_e32 v164, v164, v224
	v_add_f32_e32 v165, v165, v225
	v_lshlrev_b32_e32 v224, 16, v212
	v_and_b32_e32 v225, 0xffff0000, v212
	v_add_f32_e32 v168, v168, v224
	v_add_f32_e32 v169, v169, v225
	v_lshlrev_b32_e32 v224, 16, v213
	v_and_b32_e32 v225, 0xffff0000, v213
	v_add_f32_e32 v222, v222, v224
	v_add_f32_e32 v223, v223, v225
	v_cvt_pk_bf16_f32 v214, v132, v133
	v_cvt_pk_bf16_f32 v215, v164, v165
	v_cvt_pk_bf16_f32 v216, v168, v169
	v_cvt_pk_bf16_f32 v217, v222, v223
	s_add_u32 s44, s48, 0x100
	s_addc_u32 s45, s49, 0
	global_store_dwordx4 v226, v[214:217], s[44:45]
	global_load_dwordx4 v[178:181], v166, s[12:13]
	s_add_u32 s12, s12, 0x2000
	s_addc_u32 s13, s13, 0
	global_load_dwordx4 v[210:213], v166, s[20:21]
	s_add_u32 s20, s20, 0x2000
	s_addc_u32 s21, s21, 0
	s_waitcnt vmcnt(12)
	v_lshlrev_b32_e32 v224, 16, v152
	v_and_b32_e32 v225, 0xffff0000, v152
	v_mul_f32_e32 v132, v54, v224
	v_mul_f32_e32 v133, v55, v225
	v_lshlrev_b32_e32 v224, 16, v153
	v_and_b32_e32 v225, 0xffff0000, v153
	v_mul_f32_e32 v164, v56, v224
	v_mul_f32_e32 v165, v57, v225
	v_lshlrev_b32_e32 v224, 16, v154
	v_and_b32_e32 v225, 0xffff0000, v154
	v_mul_f32_e32 v168, v50, v224
	v_mul_f32_e32 v169, v51, v225
	v_lshlrev_b32_e32 v224, 16, v155
	v_and_b32_e32 v225, 0xffff0000, v155
	v_mul_f32_e32 v222, v52, v224
	v_mul_f32_e32 v223, v53, v225
	v_lshlrev_b32_e32 v224, 16, v182
	v_and_b32_e32 v225, 0xffff0000, v182
	v_add_f32_e32 v132, v132, v224
	v_add_f32_e32 v133, v133, v225
	v_lshlrev_b32_e32 v224, 16, v183
	v_and_b32_e32 v225, 0xffff0000, v183
	v_add_f32_e32 v164, v164, v224
	v_add_f32_e32 v165, v165, v225
	v_lshlrev_b32_e32 v224, 16, v184
	v_and_b32_e32 v225, 0xffff0000, v184
	v_add_f32_e32 v168, v168, v224
	v_add_f32_e32 v169, v169, v225
	v_lshlrev_b32_e32 v224, 16, v185
	v_and_b32_e32 v225, 0xffff0000, v185
	v_add_f32_e32 v222, v222, v224
	v_add_f32_e32 v223, v223, v225
	v_cvt_pk_bf16_f32 v218, v132, v133
	v_cvt_pk_bf16_f32 v219, v164, v165
	v_cvt_pk_bf16_f32 v220, v168, v169
	v_cvt_pk_bf16_f32 v221, v222, v223
	s_add_u32 s44, s48, 0x8100
	s_addc_u32 s45, s49, 0
	global_store_dwordx4 v226, v[218:221], s[44:45]
	global_load_dwordx4 v[152:155], v166, s[12:13]
	s_add_u32 s12, s12, 0x2000
	s_addc_u32 s13, s13, 0
	global_load_dwordx4 v[182:185], v166, s[20:21]
	s_add_u32 s20, s20, 0x2000
	s_addc_u32 s21, s21, 0
	s_waitcnt vmcnt(12)
	v_lshlrev_b32_e32 v224, 16, v156
	v_and_b32_e32 v225, 0xffff0000, v156
	v_mul_f32_e32 v132, v46, v224
	v_mul_f32_e32 v133, v47, v225
	v_lshlrev_b32_e32 v224, 16, v157
	v_and_b32_e32 v225, 0xffff0000, v157
	v_mul_f32_e32 v164, v48, v224
	v_mul_f32_e32 v165, v49, v225
	v_lshlrev_b32_e32 v224, 16, v158
	v_and_b32_e32 v225, 0xffff0000, v158
	v_mul_f32_e32 v168, v42, v224
	v_mul_f32_e32 v169, v43, v225
	v_lshlrev_b32_e32 v224, 16, v159
	v_and_b32_e32 v225, 0xffff0000, v159
	v_mul_f32_e32 v222, v44, v224
	v_mul_f32_e32 v223, v45, v225
	v_lshlrev_b32_e32 v224, 16, v186
	v_and_b32_e32 v225, 0xffff0000, v186
	v_add_f32_e32 v132, v132, v224
	v_add_f32_e32 v133, v133, v225
	v_lshlrev_b32_e32 v224, 16, v187
	v_and_b32_e32 v225, 0xffff0000, v187
	v_add_f32_e32 v164, v164, v224
	v_add_f32_e32 v165, v165, v225
	v_lshlrev_b32_e32 v224, 16, v188
	v_and_b32_e32 v225, 0xffff0000, v188
	v_add_f32_e32 v168, v168, v224
	v_add_f32_e32 v169, v169, v225
	v_lshlrev_b32_e32 v224, 16, v189
	v_and_b32_e32 v225, 0xffff0000, v189
	v_add_f32_e32 v222, v222, v224
	v_add_f32_e32 v223, v223, v225
	v_cvt_pk_bf16_f32 v214, v132, v133
	v_cvt_pk_bf16_f32 v215, v164, v165
	v_cvt_pk_bf16_f32 v216, v168, v169
	v_cvt_pk_bf16_f32 v217, v222, v223
	s_add_u32 s44, s48, 0x10100
	s_addc_u32 s45, s49, 0
	global_store_dwordx4 v226, v[214:217], s[44:45]
	global_load_dwordx4 v[156:159], v166, s[12:13]
	s_add_u32 s12, s12, 0x2000
	s_addc_u32 s13, s13, 0
	global_load_dwordx4 v[186:189], v166, s[20:21]
	s_add_u32 s20, s20, 0x2000
	s_addc_u32 s21, s21, 0
	s_waitcnt vmcnt(12)
; __device__ __forceinline__ unsigned cvt_pk_bf16(float lo, float hi) { const f32x2 v = {lo, hi}; const bf16x2_t b = __builtin_convertvector(v, bf16x2_t); return __builtin_bit_cast(unsigned, b); }
; __device__ __forceinline__ float bf_lo(unsigned u) { return __uint_as_float(u << 16); }
; __device__ __forceinline__ float bf_hi(unsigned u) { return __uint_as_float(u & 0xffff0000u); }
;     __device__ __forceinline__ void operator()(const f32x4 (&acc)[2][2][4][2], const Unit& u, int wr, int wc, int fr, int fq) const {
;     ...
;         for (int ai = 0; ai < 2; ++ai)
; #pragma unroll
;             for (int bj = 0; bj < 2; ++bj)
; #pragma unroll
;                 for (int m = 0; m < 4; ++m) {
;                     const u32x4 g = *((const u32x4*)Gs + ((size_t)(tile * 16 + (ai * 2 + bj) * 4 + m) * NTHREADS + tid));
;                     f32x4 y0 = acc[ai][bj][m][0], y1 = acc[ai][bj][m][1];
;                     y0[0] *= bf_lo(g.x); y0[1] *= bf_hi(g.x); y0[2] *= bf_lo(g.y); y0[3] *= bf_hi(g.y);
;                     y1[0] *= bf_lo(g.z); y1[1] *= bf_hi(g.z); y1[2] *= bf_lo(g.w); y1[3] *= bf_hi(g.w);
;                     u32x4* sp = (u32x4*)Sb + ((size_t)(tile * 16 + (ai * 2 + bj) * 4 + m) * NTHREADS + tid);
;                     if (br != 0) { const u32x4 t = *sp;
;                         y0[0] += bf_lo(t.x); y0[1] += bf_hi(t.x); y0[2] += bf_lo(t.y); y0[3] += bf_hi(t.y); y1[0] += bf_lo(t.z); y1[1] += bf_hi(t.z); y1[2] += bf_lo(t.w); y1[3] += bf_hi(t.w); }
;                     u32x4 w; w.x = cvt_pk_bf16(y0[0], y0[1]); w.y = cvt_pk_bf16(y0[2], y0[3]); w.z = cvt_pk_bf16(y1[0], y1[1]); w.w = cvt_pk_bf16(y1[2], y1[3]);
;                     if (br != 2) *sp = w;
;                     else {
;                         *(u32x4*)(MIXPRE + (size_t)(row0 + ai * 128 + m * 16) * DM + col00 + bj * 128) = w; }
;                 }
	v_lshlrev_b32_e32 v224, 16, v160
	v_and_b32_e32 v225, 0xffff0000, v160
	v_mul_f32_e32 v132, v38, v224
	v_mul_f32_e32 v133, v39, v225
	v_lshlrev_b32_e32 v224, 16, v161
	v_and_b32_e32 v225, 0xffff0000, v161
	v_mul_f32_e32 v164, v40, v224
	v_mul_f32_e32 v165, v41, v225
	v_lshlrev_b32_e32 v224, 16, v162
	v_and_b32_e32 v225, 0xffff0000, v162
	v_mul_f32_e32 v168, v34, v224
	v_mul_f32_e32 v169, v35, v225
	v_lshlrev_b32_e32 v224, 16, v163
	v_and_b32_e32 v225, 0xffff0000, v163
	v_mul_f32_e32 v222, v36, v224
	v_mul_f32_e32 v223, v37, v225
	v_lshlrev_b32_e32 v224, 16, v202
	v_and_b32_e32 v225, 0xffff0000, v202
	v_add_f32_e32 v132, v132, v224
	v_add_f32_e32 v133, v133, v225
	v_lshlrev_b32_e32 v224, 16, v203
	v_and_b32_e32 v225, 0xffff0000, v203
	v_add_f32_e32 v164, v164, v224
	v_add_f32_e32 v165, v165, v225
	v_lshlrev_b32_e32 v224, 16, v204
	v_and_b32_e32 v225, 0xffff0000, v204
	v_add_f32_e32 v168, v168, v224
	v_add_f32_e32 v169, v169, v225
	v_lshlrev_b32_e32 v224, 16, v205
	v_and_b32_e32 v225, 0xffff0000, v205
	v_add_f32_e32 v222, v222, v224
	v_add_f32_e32 v223, v223, v225
	v_cvt_pk_bf16_f32 v218, v132, v133
	v_cvt_pk_bf16_f32 v219, v164, v165
	v_cvt_pk_bf16_f32 v220, v168, v169
	v_cvt_pk_bf16_f32 v221, v222, v223
	s_add_u32 s44, s48, 0x18100
	s_addc_u32 s45, s49, 0
	global_store_dwordx4 v226, v[218:221], s[44:45]
	global_load_dwordx4 v[160:163], v166, s[12:13]
	s_add_u32 s12, s12, 0x2000
	s_addc_u32 s13, s13, 0
	global_load_dwordx4 v[202:205], v166, s[20:21]
	s_add_u32 s20, s20, 0x2000
	s_addc_u32 s21, s21, 0
	s_waitcnt vmcnt(12)
	v_lshlrev_b32_e32 v224, 16, v174
	v_and_b32_e32 v225, 0xffff0000, v174
	v_mul_f32_e32 v132, v94, v224
	v_mul_f32_e32 v133, v95, v225
	v_lshlrev_b32_e32 v224, 16, v175
	v_and_b32_e32 v225, 0xffff0000, v175
	v_mul_f32_e32 v164, v96, v224
	v_mul_f32_e32 v165, v97, v225
	v_lshlrev_b32_e32 v224, 16, v176
	v_and_b32_e32 v225, 0xffff0000, v176
	v_mul_f32_e32 v168, v90, v224
	v_mul_f32_e32 v169, v91, v225
	v_lshlrev_b32_e32 v224, 16, v177
	v_and_b32_e32 v225, 0xffff0000, v177
	v_mul_f32_e32 v222, v92, v224
	v_mul_f32_e32 v223, v93, v225
	v_lshlrev_b32_e32 v224, 16, v206
	v_and_b32_e32 v225, 0xffff0000, v206
	v_add_f32_e32 v132, v132, v224
	v_add_f32_e32 v133, v133, v225
	v_lshlrev_b32_e32 v224, 16, v207
	v_and_b32_e32 v225, 0xffff0000, v207
	v_add_f32_e32 v164, v164, v224
	v_add_f32_e32 v165, v165, v225
	v_lshlrev_b32_e32 v224, 16, v208
	v_and_b32_e32 v225, 0xffff0000, v208
	v_add_f32_e32 v168, v168, v224
	v_add_f32_e32 v169, v169, v225
	v_lshlrev_b32_e32 v224, 16, v209
	v_and_b32_e32 v225, 0xffff0000, v209
	v_add_f32_e32 v222, v222, v224
	v_add_f32_e32 v223, v223, v225
	v_cvt_pk_bf16_f32 v214, v132, v133
	v_cvt_pk_bf16_f32 v215, v164, v165
	v_cvt_pk_bf16_f32 v216, v168, v169
	v_cvt_pk_bf16_f32 v217, v222, v223
	s_add_u32 s44, s48, 0x40000
	s_addc_u32 s45, s49, 0
	global_store_dwordx4 v226, v[214:217], s[44:45]
	global_load_dwordx4 v[174:177], v166, s[12:13]
	s_add_u32 s12, s12, 0x2000
	s_addc_u32 s13, s13, 0
	global_load_dwordx4 v[206:209], v166, s[20:21]
	s_add_u32 s20, s20, 0x2000
	s_addc_u32 s21, s21, 0
	s_waitcnt vmcnt(12)
	v_lshlrev_b32_e32 v224, 16, v178
	v_and_b32_e32 v225, 0xffff0000, v178
	v_mul_f32_e32 v132, v86, v224
	v_mul_f32_e32 v133, v87, v225
	v_lshlrev_b32_e32 v224, 16, v179
	v_and_b32_e32 v225, 0xffff0000, v179
	v_mul_f32_e32 v164, v88, v224
	v_mul_f32_e32 v165, v89, v225
	v_lshlrev_b32_e32 v224, 16, v180
	v_and_b32_e32 v225, 0xffff0000, v180
	v_mul_f32_e32 v168, v82, v224
	v_mul_f32_e32 v169, v83, v225
	v_lshlrev_b32_e32 v224, 16, v181
	v_and_b32_e32 v225, 0xffff0000, v181
	v_mul_f32_e32 v222, v84, v224
	v_mul_f32_e32 v223, v85, v225
	v_lshlrev_b32_e32 v224, 16, v210
	v_and_b32_e32 v225, 0xffff0000, v210
	v_add_f32_e32 v132, v132, v224
	v_add_f32_e32 v133, v133, v225
	v_lshlrev_b32_e32 v224, 16, v211
	v_and_b32_e32 v225, 0xffff0000, v211
	v_add_f32_e32 v164, v164, v224
	v_add_f32_e32 v165, v165, v225
	v_lshlrev_b32_e32 v224, 16, v212
	v_and_b32_e32 v225, 0xffff0000, v212
	v_add_f32_e32 v168, v168, v224
	v_add_f32_e32 v169, v169, v225
	v_lshlrev_b32_e32 v224, 16, v213
	v_and_b32_e32 v225, 0xffff0000, v213
	v_add_f32_e32 v222, v222, v224
	v_add_f32_e32 v223, v223, v225
	v_cvt_pk_bf16_f32 v218, v132, v133
	v_cvt_pk_bf16_f32 v219, v164, v165
	v_cvt_pk_bf16_f32 v220, v168, v169
	v_cvt_pk_bf16_f32 v221, v222, v223
	s_add_u32 s44, s48, 0x48000
	s_addc_u32 s45, s49, 0
	global_store_dwordx4 v226, v[218:221], s[44:45]
	global_load_dwordx4 v[178:181], v166, s[12:13]
	s_add_u32 s12, s12, 0x2000
	s_addc_u32 s13, s13, 0
	global_load_dwordx4 v[210:213], v166, s[20:21]
	s_add_u32 s20, s20, 0x2000
	s_addc_u32 s21, s21, 0
	s_waitcnt vmcnt(12)
	v_lshlrev_b32_e32 v224, 16, v152
	v_and_b32_e32 v225, 0xffff0000, v152
	v_mul_f32_e32 v132, v78, v224
	v_mul_f32_e32 v133, v79, v225
	v_lshlrev_b32_e32 v224, 16, v153
	v_and_b32_e32 v225, 0xffff0000, v153
	v_mul_f32_e32 v164, v80, v224
	v_mul_f32_e32 v165, v81, v225
	v_lshlrev_b32_e32 v224, 16, v154
	v_and_b32_e32 v225, 0xffff0000, v154
	v_mul_f32_e32 v168, v74, v224
	v_mul_f32_e32 v169, v75, v225
	v_lshlrev_b32_e32 v224, 16, v155
	v_and_b32_e32 v225, 0xffff0000, v155
	v_mul_f32_e32 v222, v76, v224
	v_mul_f32_e32 v223, v77, v225
	v_lshlrev_b32_e32 v224, 16, v182
	v_and_b32_e32 v225, 0xffff0000, v182
	v_add_f32_e32 v132, v132, v224
	v_add_f32_e32 v133, v133, v225
	v_lshlrev_b32_e32 v224, 16, v183
	v_and_b32_e32 v225, 0xffff0000, v183
	v_add_f32_e32 v164, v164, v224
	v_add_f32_e32 v165, v165, v225
	v_lshlrev_b32_e32 v224, 16, v184
	v_and_b32_e32 v225, 0xffff0000, v184
	v_add_f32_e32 v168, v168, v224
	v_add_f32_e32 v169, v169, v225
	v_lshlrev_b32_e32 v224, 16, v185
	v_and_b32_e32 v225, 0xffff0000, v185
	v_add_f32_e32 v222, v222, v224
	v_add_f32_e32 v223, v223, v225
	v_cvt_pk_bf16_f32 v214, v132, v133
	v_cvt_pk_bf16_f32 v215, v164, v165
	v_cvt_pk_bf16_f32 v216, v168, v169
	v_cvt_pk_bf16_f32 v217, v222, v223
	s_add_u32 s44, s48, 0x50000
	s_addc_u32 s45, s49, 0
	global_store_dwordx4 v226, v[214:217], s[44:45]
	global_load_dwordx4 v[152:155], v166, s[12:13]
	s_add_u32 s12, s12, 0x2000
	s_addc_u32 s13, s13, 0
	global_load_dwordx4 v[182:185], v166, s[20:21]
	s_add_u32 s20, s20, 0x2000
	s_addc_u32 s21, s21, 0
	s_waitcnt vmcnt(12)
; __device__ __forceinline__ unsigned cvt_pk_bf16(float lo, float hi) { const f32x2 v = {lo, hi}; const bf16x2_t b = __builtin_convertvector(v, bf16x2_t); return __builtin_bit_cast(unsigned, b); }
; __device__ __forceinline__ float bf_lo(unsigned u) { return __uint_as_float(u << 16); }
; __device__ __forceinline__ float bf_hi(unsigned u) { return __uint_as_float(u & 0xffff0000u); }
;     __device__ __forceinline__ void operator()(const f32x4 (&acc)[2][2][4][2], const Unit& u, int wr, int wc, int fr, int fq) const {
;     ...
;         for (int ai = 0; ai < 2; ++ai)
; #pragma unroll
;             for (int bj = 0; bj < 2; ++bj)
; #pragma unroll
;                 for (int m = 0; m < 4; ++m) {
;                     const u32x4 g = *((const u32x4*)Gs + ((size_t)(tile * 16 + (ai * 2 + bj) * 4 + m) * NTHREADS + tid));
;                     f32x4 y0 = acc[ai][bj][m][0], y1 = acc[ai][bj][m][1];
;                     y0[0] *= bf_lo(g.x); y0[1] *= bf_hi(g.x); y0[2] *= bf_lo(g.y); y0[3] *= bf_hi(g.y);
;                     y1[0] *= bf_lo(g.z); y1[1] *= bf_hi(g.z); y1[2] *= bf_lo(g.w); y1[3] *= bf_hi(g.w);
;                     u32x4* sp = (u32x4*)Sb + ((size_t)(tile * 16 + (ai * 2 + bj) * 4 + m) * NTHREADS + tid);
;                     if (br != 0) { const u32x4 t = *sp;
;                         y0[0] += bf_lo(t.x); y0[1] += bf_hi(t.x); y0[2] += bf_lo(t.y); y0[3] += bf_hi(t.y); y1[0] += bf_lo(t.z); y1[1] += bf_hi(t.z); y1[2] += bf_lo(t.w); y1[3] += bf_hi(t.w); }
;                     u32x4 w; w.x = cvt_pk_bf16(y0[0], y0[1]); w.y = cvt_pk_bf16(y0[2], y0[3]); w.z = cvt_pk_bf16(y1[0], y1[1]); w.w = cvt_pk_bf16(y1[2], y1[3]);
;                     if (br != 2) *sp = w;
;                     else {
;                         *(u32x4*)(MIXPRE + (size_t)(row0 + ai * 128 + m * 16) * DM + col00 + bj * 128) = w; }
;                 }
	v_lshlrev_b32_e32 v224, 16, v156
	v_and_b32_e32 v225, 0xffff0000, v156
	v_mul_f32_e32 v132, v70, v224
	v_mul_f32_e32 v133, v71, v225
	v_lshlrev_b32_e32 v224, 16, v157
	v_and_b32_e32 v225, 0xffff0000, v157
	v_mul_f32_e32 v164, v72, v224
	v_mul_f32_e32 v165, v73, v225
	v_lshlrev_b32_e32 v224, 16, v158
	v_and_b32_e32 v225, 0xffff0000, v158
	v_mul_f32_e32 v168, v66, v224
	v_mul_f32_e32 v169, v67, v225
	v_lshlrev_b32_e32 v224, 16, v159
	v_and_b32_e32 v225, 0xffff0000, v159
	v_mul_f32_e32 v222, v68, v224
	v_mul_f32_e32 v223, v69, v225
	v_lshlrev_b32_e32 v224, 16, v186
	v_and_b32_e32 v225, 0xffff0000, v186
	v_add_f32_e32 v132, v132, v224
	v_add_f32_e32 v133, v133, v225
	v_lshlrev_b32_e32 v224, 16, v187
	v_and_b32_e32 v225, 0xffff0000, v187
	v_add_f32_e32 v164, v164, v224
	v_add_f32_e32 v165, v165, v225
	v_lshlrev_b32_e32 v224, 16, v188
	v_and_b32_e32 v225, 0xffff0000, v188
	v_add_f32_e32 v168, v168, v224
	v_add_f32_e32 v169, v169, v225
	v_lshlrev_b32_e32 v224, 16, v189
	v_and_b32_e32 v225, 0xffff0000, v189
	v_add_f32_e32 v222, v222, v224
	v_add_f32_e32 v223, v223, v225
	v_cvt_pk_bf16_f32 v218, v132, v133
	v_cvt_pk_bf16_f32 v219, v164, v165
	v_cvt_pk_bf16_f32 v220, v168, v169
	v_cvt_pk_bf16_f32 v221, v222, v223
	s_add_u32 s44, s48, 0x58000
	s_addc_u32 s45, s49, 0
	global_store_dwordx4 v226, v[218:221], s[44:45]
	s_waitcnt vmcnt(10)
	v_lshlrev_b32_e32 v224, 16, v160
	v_and_b32_e32 v225, 0xffff0000, v160
	v_mul_f32_e32 v132, v30, v224
	v_mul_f32_e32 v133, v31, v225
	v_lshlrev_b32_e32 v224, 16, v161
	v_and_b32_e32 v225, 0xffff0000, v161
	v_mul_f32_e32 v164, v32, v224
	v_mul_f32_e32 v165, v33, v225
	v_lshlrev_b32_e32 v224, 16, v162
	v_and_b32_e32 v225, 0xffff0000, v162
	v_mul_f32_e32 v168, v26, v224
	v_mul_f32_e32 v169, v27, v225
	v_lshlrev_b32_e32 v224, 16, v163
	v_and_b32_e32 v225, 0xffff0000, v163
	v_mul_f32_e32 v222, v28, v224
	v_mul_f32_e32 v223, v29, v225
	v_lshlrev_b32_e32 v224, 16, v202
	v_and_b32_e32 v225, 0xffff0000, v202
	v_add_f32_e32 v132, v132, v224
	v_add_f32_e32 v133, v133, v225
	v_lshlrev_b32_e32 v224, 16, v203
	v_and_b32_e32 v225, 0xffff0000, v203
	v_add_f32_e32 v164, v164, v224
	v_add_f32_e32 v165, v165, v225
	v_lshlrev_b32_e32 v224, 16, v204
	v_and_b32_e32 v225, 0xffff0000, v204
	v_add_f32_e32 v168, v168, v224
	v_add_f32_e32 v169, v169, v225
	v_lshlrev_b32_e32 v224, 16, v205
	v_and_b32_e32 v225, 0xffff0000, v205
	v_add_f32_e32 v222, v222, v224
	v_add_f32_e32 v223, v223, v225
	v_cvt_pk_bf16_f32 v214, v132, v133
	v_cvt_pk_bf16_f32 v215, v164, v165
	v_cvt_pk_bf16_f32 v216, v168, v169
	v_cvt_pk_bf16_f32 v217, v222, v223
	s_add_u32 s44, s48, 0x40100
	s_addc_u32 s45, s49, 0
	global_store_dwordx4 v226, v[214:217], s[44:45]
	s_waitcnt vmcnt(8)
	v_lshlrev_b32_e32 v224, 16, v174
	v_and_b32_e32 v225, 0xffff0000, v174
	v_mul_f32_e32 v132, v22, v224
	v_mul_f32_e32 v133, v23, v225
	v_lshlrev_b32_e32 v224, 16, v175
	v_and_b32_e32 v225, 0xffff0000, v175
	v_mul_f32_e32 v164, v24, v224
	v_mul_f32_e32 v165, v25, v225
	v_lshlrev_b32_e32 v224, 16, v176
	v_and_b32_e32 v225, 0xffff0000, v176
	v_mul_f32_e32 v168, v18, v224
	v_mul_f32_e32 v169, v19, v225
	v_lshlrev_b32_e32 v224, 16, v177
	v_and_b32_e32 v225, 0xffff0000, v177
	v_mul_f32_e32 v222, v20, v224
	v_mul_f32_e32 v223, v21, v225
	v_lshlrev_b32_e32 v224, 16, v206
	v_and_b32_e32 v225, 0xffff0000, v206
	v_add_f32_e32 v132, v132, v224
	v_add_f32_e32 v133, v133, v225
	v_lshlrev_b32_e32 v224, 16, v207
	v_and_b32_e32 v225, 0xffff0000, v207
	v_add_f32_e32 v164, v164, v224
	v_add_f32_e32 v165, v165, v225
	v_lshlrev_b32_e32 v224, 16, v208
	v_and_b32_e32 v225, 0xffff0000, v208
	v_add_f32_e32 v168, v168, v224
	v_add_f32_e32 v169, v169, v225
	v_lshlrev_b32_e32 v224, 16, v209
	v_and_b32_e32 v225, 0xffff0000, v209
	v_add_f32_e32 v222, v222, v224
	v_add_f32_e32 v223, v223, v225
	v_cvt_pk_bf16_f32 v218, v132, v133
	v_cvt_pk_bf16_f32 v219, v164, v165
	v_cvt_pk_bf16_f32 v220, v168, v169
	v_cvt_pk_bf16_f32 v221, v222, v223
	s_add_u32 s44, s48, 0x48100
	s_addc_u32 s45, s49, 0
	global_store_dwordx4 v226, v[218:221], s[44:45]
	s_waitcnt vmcnt(6)
	v_lshlrev_b32_e32 v224, 16, v178
	v_and_b32_e32 v225, 0xffff0000, v178
	v_mul_f32_e32 v132, v14, v224
	v_mul_f32_e32 v133, v15, v225
	v_lshlrev_b32_e32 v224, 16, v179
	v_and_b32_e32 v225, 0xffff0000, v179
	v_mul_f32_e32 v164, v16, v224
	v_mul_f32_e32 v165, v17, v225
	v_lshlrev_b32_e32 v224, 16, v180
	v_and_b32_e32 v225, 0xffff0000, v180
	v_mul_f32_e32 v168, v10, v224
	v_mul_f32_e32 v169, v11, v225
	v_lshlrev_b32_e32 v224, 16, v181
	v_and_b32_e32 v225, 0xffff0000, v181
	v_mul_f32_e32 v222, v12, v224
	v_mul_f32_e32 v223, v13, v225
	v_lshlrev_b32_e32 v224, 16, v210
	v_and_b32_e32 v225, 0xffff0000, v210
	v_add_f32_e32 v132, v132, v224
	v_add_f32_e32 v133, v133, v225
	v_lshlrev_b32_e32 v224, 16, v211
	v_and_b32_e32 v225, 0xffff0000, v211
	v_add_f32_e32 v164, v164, v224
	v_add_f32_e32 v165, v165, v225
	v_lshlrev_b32_e32 v224, 16, v212
	v_and_b32_e32 v225, 0xffff0000, v212
	v_add_f32_e32 v168, v168, v224
	v_add_f32_e32 v169, v169, v225
	v_lshlrev_b32_e32 v224, 16, v213
	v_and_b32_e32 v225, 0xffff0000, v213
	v_add_f32_e32 v222, v222, v224
	v_add_f32_e32 v223, v223, v225
	v_cvt_pk_bf16_f32 v214, v132, v133
	v_cvt_pk_bf16_f32 v215, v164, v165
	v_cvt_pk_bf16_f32 v216, v168, v169
	v_cvt_pk_bf16_f32 v217, v222, v223
	s_add_u32 s44, s48, 0x50100
	s_addc_u32 s45, s49, 0
	global_store_dwordx4 v226, v[214:217], s[44:45]
	s_waitcnt vmcnt(4)
	v_lshlrev_b32_e32 v224, 16, v152
	v_and_b32_e32 v225, 0xffff0000, v152
	v_mul_f32_e32 v132, v6, v224
	v_mul_f32_e32 v133, v7, v225
	v_lshlrev_b32_e32 v224, 16, v153
	v_and_b32_e32 v225, 0xffff0000, v153
	v_mul_f32_e32 v164, v8, v224
	v_mul_f32_e32 v165, v9, v225
	v_lshlrev_b32_e32 v224, 16, v154
	v_and_b32_e32 v225, 0xffff0000, v154
	v_mul_f32_e32 v168, v2, v224
	v_mul_f32_e32 v169, v3, v225
	v_lshlrev_b32_e32 v224, 16, v155
	v_and_b32_e32 v225, 0xffff0000, v155
	v_mul_f32_e32 v222, v4, v224
	v_mul_f32_e32 v223, v5, v225
	v_lshlrev_b32_e32 v224, 16, v182
	v_and_b32_e32 v225, 0xffff0000, v182
	v_add_f32_e32 v132, v132, v224
	v_add_f32_e32 v133, v133, v225
	v_lshlrev_b32_e32 v224, 16, v183
	v_and_b32_e32 v225, 0xffff0000, v183
	v_add_f32_e32 v164, v164, v224
	v_add_f32_e32 v165, v165, v225
	v_lshlrev_b32_e32 v224, 16, v184
	v_and_b32_e32 v225, 0xffff0000, v184
	v_add_f32_e32 v168, v168, v224
	v_add_f32_e32 v169, v169, v225
	v_lshlrev_b32_e32 v224, 16, v185
	v_and_b32_e32 v225, 0xffff0000, v185
	v_add_f32_e32 v222, v222, v224
	v_add_f32_e32 v223, v223, v225
	v_cvt_pk_bf16_f32 v218, v132, v133
	v_cvt_pk_bf16_f32 v219, v164, v165
	v_cvt_pk_bf16_f32 v220, v168, v169
	v_cvt_pk_bf16_f32 v221, v222, v223
	s_add_u32 s44, s48, 0x58100
	s_addc_u32 s45, s49, 0
	global_store_dwordx4 v226, v[218:221], s[44:45]
	s_branch .LBB0_304
; __device__ __forceinline__ unsigned cvt_pk_bf16(float lo, float hi) { const f32x2 v = {lo, hi}; const bf16x2_t b = __builtin_convertvector(v, bf16x2_t); return __builtin_bit_cast(unsigned, b); }
; __device__ __forceinline__ float bf_lo(unsigned u) { return __uint_as_float(u << 16); }
; __device__ __forceinline__ float bf_hi(unsigned u) { return __uint_as_float(u & 0xffff0000u); }
;     __device__ __forceinline__ void operator()(const f32x4 (&acc)[2][2][4][2], const Unit& u, int wr, int wc, int fr, int fq) const {
;     ...
;         for (int ai = 0; ai < 2; ++ai)
; #pragma unroll
;             for (int bj = 0; bj < 2; ++bj)
; #pragma unroll
;                 for (int m = 0; m < 4; ++m) {
;                     const u32x4 g = *((const u32x4*)Gs + ((size_t)(tile * 16 + (ai * 2 + bj) * 4 + m) * NTHREADS + tid));
;                     f32x4 y0 = acc[ai][bj][m][0], y1 = acc[ai][bj][m][1];
;                     y0[0] *= bf_lo(g.x); y0[1] *= bf_hi(g.x); y0[2] *= bf_lo(g.y); y0[3] *= bf_hi(g.y);
;                     y1[0] *= bf_lo(g.z); y1[1] *= bf_hi(g.z); y1[2] *= bf_lo(g.w); y1[3] *= bf_hi(g.w);
;                     u32x4* sp = (u32x4*)Sb + ((size_t)(tile * 16 + (ai * 2 + bj) * 4 + m) * NTHREADS + tid);
;                     if (br != 0) { const u32x4 t = *sp;
;                         y0[0] += bf_lo(t.x); y0[1] += bf_hi(t.x); y0[2] += bf_lo(t.y); y0[3] += bf_hi(t.y); y1[0] += bf_lo(t.z); y1[1] += bf_hi(t.z); y1[2] += bf_lo(t.w); y1[3] += bf_hi(t.w); }
;                     u32x4 w; w.x = cvt_pk_bf16(y0[0], y0[1]); w.y = cvt_pk_bf16(y0[2], y0[3]); w.z = cvt_pk_bf16(y1[0], y1[1]); w.w = cvt_pk_bf16(y1[2], y1[3]);
;                     if (br != 2) *sp = w;
.Lpl_br1:
	global_load_dwordx4 v[152:155], v166, s[12:13]
	s_add_u32 s12, s12, 0x2000
	s_addc_u32 s13, s13, 0
	global_load_dwordx4 v[182:185], v166, s[20:21]
	s_add_u32 s20, s20, 0x2000
	s_addc_u32 s21, s21, 0
	global_load_dwordx4 v[156:159], v166, s[12:13]
	s_add_u32 s12, s12, 0x2000
	s_addc_u32 s13, s13, 0
	global_load_dwordx4 v[186:189], v166, s[20:21]
	s_add_u32 s20, s20, 0x2000
	s_addc_u32 s21, s21, 0
	global_load_dwordx4 v[160:163], v166, s[12:13]
	s_add_u32 s12, s12, 0x2000
	s_addc_u32 s13, s13, 0
	global_load_dwordx4 v[202:205], v166, s[20:21]
	s_add_u32 s20, s20, 0x2000
	s_addc_u32 s21, s21, 0
	global_load_dwordx4 v[174:177], v166, s[12:13]
	s_add_u32 s12, s12, 0x2000
	s_addc_u32 s13, s13, 0
	global_load_dwordx4 v[206:209], v166, s[20:21]
	s_add_u32 s20, s20, 0x2000
	s_addc_u32 s21, s21, 0
	global_load_dwordx4 v[178:181], v166, s[12:13]
	s_add_u32 s12, s12, 0x2000
	s_addc_u32 s13, s13, 0
	global_load_dwordx4 v[210:213], v166, s[20:21]
	s_add_u32 s20, s20, 0x2000
	s_addc_u32 s21, s21, 0
	s_waitcnt vmcnt(8)
	v_lshlrev_b32_e32 v224, 16, v152
	v_and_b32_e32 v225, 0xffff0000, v152
	v_mul_f32_e32 v132, v126, v224
	v_mul_f32_e32 v133, v127, v225
	v_lshlrev_b32_e32 v224, 16, v153
	v_and_b32_e32 v225, 0xffff0000, v153
	v_mul_f32_e32 v164, v128, v224
	v_mul_f32_e32 v165, v129, v225
	v_lshlrev_b32_e32 v224, 16, v154
	v_and_b32_e32 v225, 0xffff0000, v154
	v_mul_f32_e32 v168, v122, v224
	v_mul_f32_e32 v169, v123, v225
	v_lshlrev_b32_e32 v224, 16, v155
	v_and_b32_e32 v225, 0xffff0000, v155
	v_mul_f32_e32 v222, v124, v224
	v_mul_f32_e32 v223, v125, v225
	v_lshlrev_b32_e32 v224, 16, v182
	v_and_b32_e32 v225, 0xffff0000, v182
	v_add_f32_e32 v132, v132, v224
	v_add_f32_e32 v133, v133, v225
	v_lshlrev_b32_e32 v224, 16, v183
	v_and_b32_e32 v225, 0xffff0000, v183
	v_add_f32_e32 v164, v164, v224
	v_add_f32_e32 v165, v165, v225
	v_lshlrev_b32_e32 v224, 16, v184
	v_and_b32_e32 v225, 0xffff0000, v184
	v_add_f32_e32 v168, v168, v224
	v_add_f32_e32 v169, v169, v225
	v_lshlrev_b32_e32 v224, 16, v185
	v_and_b32_e32 v225, 0xffff0000, v185
	v_add_f32_e32 v222, v222, v224
	v_add_f32_e32 v223, v223, v225
	v_cvt_pk_bf16_f32 v214, v132, v133
	v_cvt_pk_bf16_f32 v215, v164, v165
	v_cvt_pk_bf16_f32 v216, v168, v169
	v_cvt_pk_bf16_f32 v217, v222, v223
	global_store_dwordx4 v166, v[214:217], s[44:45]
	s_add_u32 s44, s44, 0x2000
	s_addc_u32 s45, s45, 0
	global_load_dwordx4 v[152:155], v166, s[12:13]
	s_add_u32 s12, s12, 0x2000
	s_addc_u32 s13, s13, 0
	global_load_dwordx4 v[182:185], v166, s[20:21]
	s_add_u32 s20, s20, 0x2000
	s_addc_u32 s21, s21, 0
	s_waitcnt vmcnt(9)
	v_lshlrev_b32_e32 v224, 16, v156
	v_and_b32_e32 v225, 0xffff0000, v156
	v_mul_f32_e32 v132, v118, v224
	v_mul_f32_e32 v133, v119, v225
	v_lshlrev_b32_e32 v224, 16, v157
	v_and_b32_e32 v225, 0xffff0000, v157
	v_mul_f32_e32 v164, v120, v224
	v_mul_f32_e32 v165, v121, v225
	v_lshlrev_b32_e32 v224, 16, v158
	v_and_b32_e32 v225, 0xffff0000, v158
	v_mul_f32_e32 v168, v114, v224
	v_mul_f32_e32 v169, v115, v225
	v_lshlrev_b32_e32 v224, 16, v159
	v_and_b32_e32 v225, 0xffff0000, v159
	v_mul_f32_e32 v222, v116, v224
	v_mul_f32_e32 v223, v117, v225
	v_lshlrev_b32_e32 v224, 16, v186
	v_and_b32_e32 v225, 0xffff0000, v186
	v_add_f32_e32 v132, v132, v224
	v_add_f32_e32 v133, v133, v225
	v_lshlrev_b32_e32 v224, 16, v187
	v_and_b32_e32 v225, 0xffff0000, v187
	v_add_f32_e32 v164, v164, v224
	v_add_f32_e32 v165, v165, v225
	v_lshlrev_b32_e32 v224, 16, v188
	v_and_b32_e32 v225, 0xffff0000, v188
	v_add_f32_e32 v168, v168, v224
	v_add_f32_e32 v169, v169, v225
	v_lshlrev_b32_e32 v224, 16, v189
	v_and_b32_e32 v225, 0xffff0000, v189
	v_add_f32_e32 v222, v222, v224
	v_add_f32_e32 v223, v223, v225
	v_cvt_pk_bf16_f32 v218, v132, v133
	v_cvt_pk_bf16_f32 v219, v164, v165
	v_cvt_pk_bf16_f32 v220, v168, v169
	v_cvt_pk_bf16_f32 v221, v222, v223
	global_store_dwordx4 v166, v[218:221], s[44:45]
	s_add_u32 s44, s44, 0x2000
	s_addc_u32 s45, s45, 0
	global_load_dwordx4 v[156:159], v166, s[12:13]
	s_add_u32 s12, s12, 0x2000
	s_addc_u32 s13, s13, 0
	global_load_dwordx4 v[186:189], v166, s[20:21]
	s_add_u32 s20, s20, 0x2000
	s_addc_u32 s21, s21, 0
	s_waitcnt vmcnt(10)
	v_lshlrev_b32_e32 v224, 16, v160
	v_and_b32_e32 v225, 0xffff0000, v160
	v_mul_f32_e32 v132, v110, v224
	v_mul_f32_e32 v133, v111, v225
	v_lshlrev_b32_e32 v224, 16, v161
	v_and_b32_e32 v225, 0xffff0000, v161
	v_mul_f32_e32 v164, v112, v224
	v_mul_f32_e32 v165, v113, v225
	v_lshlrev_b32_e32 v224, 16, v162
	v_and_b32_e32 v225, 0xffff0000, v162
	v_mul_f32_e32 v168, v106, v224
	v_mul_f32_e32 v169, v107, v225
	v_lshlrev_b32_e32 v224, 16, v163
	v_and_b32_e32 v225, 0xffff0000, v163
	v_mul_f32_e32 v222, v108, v224
	v_mul_f32_e32 v223, v109, v225
	v_lshlrev_b32_e32 v224, 16, v202
	v_and_b32_e32 v225, 0xffff0000, v202
	v_add_f32_e32 v132, v132, v224
	v_add_f32_e32 v133, v133, v225
	v_lshlrev_b32_e32 v224, 16, v203
	v_and_b32_e32 v225, 0xffff0000, v203
	v_add_f32_e32 v164, v164, v224
	v_add_f32_e32 v165, v165, v225
	v_lshlrev_b32_e32 v224, 16, v204
	v_and_b32_e32 v225, 0xffff0000, v204
	v_add_f32_e32 v168, v168, v224
	v_add_f32_e32 v169, v169, v225
	v_lshlrev_b32_e32 v224, 16, v205
	v_and_b32_e32 v225, 0xffff0000, v205
	v_add_f32_e32 v222, v222, v224
	v_add_f32_e32 v223, v223, v225
	v_cvt_pk_bf16_f32 v214, v132, v133
	v_cvt_pk_bf16_f32 v215, v164, v165
	v_cvt_pk_bf16_f32 v216, v168, v169
	v_cvt_pk_bf16_f32 v217, v222, v223
	global_store_dwordx4 v166, v[214:217], s[44:45]
	s_add_u32 s44, s44, 0x2000
	s_addc_u32 s45, s45, 0
	global_load_dwordx4 v[160:163], v166, s[12:13]
	s_add_u32 s12, s12, 0x2000
	s_addc_u32 s13, s13, 0
	global_load_dwordx4 v[202:205], v166, s[20:21]
	s_add_u32 s20, s20, 0x2000
	s_addc_u32 s21, s21, 0
	s_waitcnt vmcnt(11)
; __device__ __forceinline__ unsigned cvt_pk_bf16(float lo, float hi) { const f32x2 v = {lo, hi}; const bf16x2_t b = __builtin_convertvector(v, bf16x2_t); return __builtin_bit_cast(unsigned, b); }
; __device__ __forceinline__ float bf_lo(unsigned u) { return __uint_as_float(u << 16); }
; __device__ __forceinline__ float bf_hi(unsigned u) { return __uint_as_float(u & 0xffff0000u); }
;     __device__ __forceinline__ void operator()(const f32x4 (&acc)[2][2][4][2], const Unit& u, int wr, int wc, int fr, int fq) const {
;     ...
;         for (int ai = 0; ai < 2; ++ai)
; #pragma unroll
;             for (int bj = 0; bj < 2; ++bj)
; #pragma unroll
;                 for (int m = 0; m < 4; ++m) {
;                     const u32x4 g = *((const u32x4*)Gs + ((size_t)(tile * 16 + (ai * 2 + bj) * 4 + m) * NTHREADS + tid));
;                     f32x4 y0 = acc[ai][bj][m][0], y1 = acc[ai][bj][m][1];
;                     y0[0] *= bf_lo(g.x); y0[1] *= bf_hi(g.x); y0[2] *= bf_lo(g.y); y0[3] *= bf_hi(g.y);
;                     y1[0] *= bf_lo(g.z); y1[1] *= bf_hi(g.z); y1[2] *= bf_lo(g.w); y1[3] *= bf_hi(g.w);
;                     u32x4* sp = (u32x4*)Sb + ((size_t)(tile * 16 + (ai * 2 + bj) * 4 + m) * NTHREADS + tid);
;                     if (br != 0) { const u32x4 t = *sp;
;                         y0[0] += bf_lo(t.x); y0[1] += bf_hi(t.x); y0[2] += bf_lo(t.y); y0[3] += bf_hi(t.y); y1[0] += bf_lo(t.z); y1[1] += bf_hi(t.z); y1[2] += bf_lo(t.w); y1[3] += bf_hi(t.w); }
;                     u32x4 w; w.x = cvt_pk_bf16(y0[0], y0[1]); w.y = cvt_pk_bf16(y0[2], y0[3]); w.z = cvt_pk_bf16(y1[0], y1[1]); w.w = cvt_pk_bf16(y1[2], y1[3]);
;                     if (br != 2) *sp = w;
	v_lshlrev_b32_e32 v224, 16, v174
	v_and_b32_e32 v225, 0xffff0000, v174
	v_mul_f32_e32 v132, v102, v224
	v_mul_f32_e32 v133, v103, v225
	v_lshlrev_b32_e32 v224, 16, v175
	v_and_b32_e32 v225, 0xffff0000, v175
	v_mul_f32_e32 v164, v104, v224
	v_mul_f32_e32 v165, v105, v225
	v_lshlrev_b32_e32 v224, 16, v176
	v_and_b32_e32 v225, 0xffff0000, v176
	v_mul_f32_e32 v168, v98, v224
	v_mul_f32_e32 v169, v99, v225
	v_lshlrev_b32_e32 v224, 16, v177
	v_and_b32_e32 v225, 0xffff0000, v177
	v_mul_f32_e32 v222, v100, v224
	v_mul_f32_e32 v223, v101, v225
	v_lshlrev_b32_e32 v224, 16, v206
	v_and_b32_e32 v225, 0xffff0000, v206
	v_add_f32_e32 v132, v132, v224
	v_add_f32_e32 v133, v133, v225
	v_lshlrev_b32_e32 v224, 16, v207
	v_and_b32_e32 v225, 0xffff0000, v207
	v_add_f32_e32 v164, v164, v224
	v_add_f32_e32 v165, v165, v225
	v_lshlrev_b32_e32 v224, 16, v208
	v_and_b32_e32 v225, 0xffff0000, v208
	v_add_f32_e32 v168, v168, v224
	v_add_f32_e32 v169, v169, v225
	v_lshlrev_b32_e32 v224, 16, v209
	v_and_b32_e32 v225, 0xffff0000, v209
	v_add_f32_e32 v222, v222, v224
	v_add_f32_e32 v223, v223, v225
	v_cvt_pk_bf16_f32 v218, v132, v133
	v_cvt_pk_bf16_f32 v219, v164, v165
	v_cvt_pk_bf16_f32 v220, v168, v169
	v_cvt_pk_bf16_f32 v221, v222, v223
	global_store_dwordx4 v166, v[218:221], s[44:45]
	s_add_u32 s44, s44, 0x2000
	s_addc_u32 s45, s45, 0
	global_load_dwordx4 v[174:177], v166, s[12:13]
	s_add_u32 s12, s12, 0x2000
	s_addc_u32 s13, s13, 0
	global_load_dwordx4 v[206:209], v166, s[20:21]
	s_add_u32 s20, s20, 0x2000
	s_addc_u32 s21, s21, 0
	s_waitcnt vmcnt(12)
	v_lshlrev_b32_e32 v224, 16, v178
	v_and_b32_e32 v225, 0xffff0000, v178
	v_mul_f32_e32 v132, v62, v224
	v_mul_f32_e32 v133, v63, v225
	v_lshlrev_b32_e32 v224, 16, v179
	v_and_b32_e32 v225, 0xffff0000, v179
	v_mul_f32_e32 v164, v64, v224
	v_mul_f32_e32 v165, v65, v225
	v_lshlrev_b32_e32 v224, 16, v180
	v_and_b32_e32 v225, 0xffff0000, v180
	v_mul_f32_e32 v168, v58, v224
	v_mul_f32_e32 v169, v59, v225
	v_lshlrev_b32_e32 v224, 16, v181
	v_and_b32_e32 v225, 0xffff0000, v181
	v_mul_f32_e32 v222, v60, v224
	v_mul_f32_e32 v223, v61, v225
	v_lshlrev_b32_e32 v224, 16, v210
	v_and_b32_e32 v225, 0xffff0000, v210
	v_add_f32_e32 v132, v132, v224
	v_add_f32_e32 v133, v133, v225
	v_lshlrev_b32_e32 v224, 16, v211
	v_and_b32_e32 v225, 0xffff0000, v211
	v_add_f32_e32 v164, v164, v224
	v_add_f32_e32 v165, v165, v225
	v_lshlrev_b32_e32 v224, 16, v212
	v_and_b32_e32 v225, 0xffff0000, v212
	v_add_f32_e32 v168, v168, v224
	v_add_f32_e32 v169, v169, v225
	v_lshlrev_b32_e32 v224, 16, v213
	v_and_b32_e32 v225, 0xffff0000, v213
	v_add_f32_e32 v222, v222, v224
	v_add_f32_e32 v223, v223, v225
	v_cvt_pk_bf16_f32 v214, v132, v133
	v_cvt_pk_bf16_f32 v215, v164, v165
	v_cvt_pk_bf16_f32 v216, v168, v169
	v_cvt_pk_bf16_f32 v217, v222, v223
	global_store_dwordx4 v166, v[214:217], s[44:45]
	s_add_u32 s44, s44, 0x2000
	s_addc_u32 s45, s45, 0
	global_load_dwordx4 v[178:181], v166, s[12:13]
	s_add_u32 s12, s12, 0x2000
	s_addc_u32 s13, s13, 0
	global_load_dwordx4 v[210:213], v166, s[20:21]
	s_add_u32 s20, s20, 0x2000
	s_addc_u32 s21, s21, 0
	s_waitcnt vmcnt(12)
	v_lshlrev_b32_e32 v224, 16, v152
	v_and_b32_e32 v225, 0xffff0000, v152
	v_mul_f32_e32 v132, v54, v224
	v_mul_f32_e32 v133, v55, v225
	v_lshlrev_b32_e32 v224, 16, v153
	v_and_b32_e32 v225, 0xffff0000, v153
	v_mul_f32_e32 v164, v56, v224
	v_mul_f32_e32 v165, v57, v225
	v_lshlrev_b32_e32 v224, 16, v154
	v_and_b32_e32 v225, 0xffff0000, v154
	v_mul_f32_e32 v168, v50, v224
	v_mul_f32_e32 v169, v51, v225
	v_lshlrev_b32_e32 v224, 16, v155
	v_and_b32_e32 v225, 0xffff0000, v155
	v_mul_f32_e32 v222, v52, v224
	v_mul_f32_e32 v223, v53, v225
	v_lshlrev_b32_e32 v224, 16, v182
	v_and_b32_e32 v225, 0xffff0000, v182
	v_add_f32_e32 v132, v132, v224
	v_add_f32_e32 v133, v133, v225
	v_lshlrev_b32_e32 v224, 16, v183
	v_and_b32_e32 v225, 0xffff0000, v183
	v_add_f32_e32 v164, v164, v224
	v_add_f32_e32 v165, v165, v225
	v_lshlrev_b32_e32 v224, 16, v184
	v_and_b32_e32 v225, 0xffff0000, v184
	v_add_f32_e32 v168, v168, v224
	v_add_f32_e32 v169, v169, v225
	v_lshlrev_b32_e32 v224, 16, v185
	v_and_b32_e32 v225, 0xffff0000, v185
	v_add_f32_e32 v222, v222, v224
	v_add_f32_e32 v223, v223, v225
	v_cvt_pk_bf16_f32 v218, v132, v133
	v_cvt_pk_bf16_f32 v219, v164, v165
	v_cvt_pk_bf16_f32 v220, v168, v169
	v_cvt_pk_bf16_f32 v221, v222, v223
	global_store_dwordx4 v166, v[218:221], s[44:45]
	s_add_u32 s44, s44, 0x2000
	s_addc_u32 s45, s45, 0
	global_load_dwordx4 v[152:155], v166, s[12:13]
	s_add_u32 s12, s12, 0x2000
	s_addc_u32 s13, s13, 0
	global_load_dwordx4 v[182:185], v166, s[20:21]
	s_add_u32 s20, s20, 0x2000
	s_addc_u32 s21, s21, 0
	s_waitcnt vmcnt(12)
	v_lshlrev_b32_e32 v224, 16, v156
	v_and_b32_e32 v225, 0xffff0000, v156
	v_mul_f32_e32 v132, v46, v224
	v_mul_f32_e32 v133, v47, v225
	v_lshlrev_b32_e32 v224, 16, v157
	v_and_b32_e32 v225, 0xffff0000, v157
	v_mul_f32_e32 v164, v48, v224
	v_mul_f32_e32 v165, v49, v225
	v_lshlrev_b32_e32 v224, 16, v158
	v_and_b32_e32 v225, 0xffff0000, v158
	v_mul_f32_e32 v168, v42, v224
	v_mul_f32_e32 v169, v43, v225
	v_lshlrev_b32_e32 v224, 16, v159
	v_and_b32_e32 v225, 0xffff0000, v159
	v_mul_f32_e32 v222, v44, v224
	v_mul_f32_e32 v223, v45, v225
	v_lshlrev_b32_e32 v224, 16, v186
	v_and_b32_e32 v225, 0xffff0000, v186
	v_add_f32_e32 v132, v132, v224
	v_add_f32_e32 v133, v133, v225
	v_lshlrev_b32_e32 v224, 16, v187
	v_and_b32_e32 v225, 0xffff0000, v187
	v_add_f32_e32 v164, v164, v224
	v_add_f32_e32 v165, v165, v225
	v_lshlrev_b32_e32 v224, 16, v188
	v_and_b32_e32 v225, 0xffff0000, v188
	v_add_f32_e32 v168, v168, v224
	v_add_f32_e32 v169, v169, v225
	v_lshlrev_b32_e32 v224, 16, v189
	v_and_b32_e32 v225, 0xffff0000, v189
	v_add_f32_e32 v222, v222, v224
	v_add_f32_e32 v223, v223, v225
	v_cvt_pk_bf16_f32 v214, v132, v133
	v_cvt_pk_bf16_f32 v215, v164, v165
	v_cvt_pk_bf16_f32 v216, v168, v169
	v_cvt_pk_bf16_f32 v217, v222, v223
	global_store_dwordx4 v166, v[214:217], s[44:45]
	s_add_u32 s44, s44, 0x2000
	s_addc_u32 s45, s45, 0
	global_load_dwordx4 v[156:159], v166, s[12:13]
	s_add_u32 s12, s12, 0x2000
	s_addc_u32 s13, s13, 0
	global_load_dwordx4 v[186:189], v166, s[20:21]
	s_add_u32 s20, s20, 0x2000
	s_addc_u32 s21, s21, 0
	s_waitcnt vmcnt(12)
; __device__ __forceinline__ unsigned cvt_pk_bf16(float lo, float hi) { const f32x2 v = {lo, hi}; const bf16x2_t b = __builtin_convertvector(v, bf16x2_t); return __builtin_bit_cast(unsigned, b); }
; __device__ __forceinline__ float bf_lo(unsigned u) { return __uint_as_float(u << 16); }
; __device__ __forceinline__ float bf_hi(unsigned u) { return __uint_as_float(u & 0xffff0000u); }
;     __device__ __forceinline__ void operator()(const f32x4 (&acc)[2][2][4][2], const Unit& u, int wr, int wc, int fr, int fq) const {
;     ...
;         for (int ai = 0; ai < 2; ++ai)
; #pragma unroll
;             for (int bj = 0; bj < 2; ++bj)
; #pragma unroll
;                 for (int m = 0; m < 4; ++m) {
;                     const u32x4 g = *((const u32x4*)Gs + ((size_t)(tile * 16 + (ai * 2 + bj) * 4 + m) * NTHREADS + tid));
;                     f32x4 y0 = acc[ai][bj][m][0], y1 = acc[ai][bj][m][1];
;                     y0[0] *= bf_lo(g.x); y0[1] *= bf_hi(g.x); y0[2] *= bf_lo(g.y); y0[3] *= bf_hi(g.y);
;                     y1[0] *= bf_lo(g.z); y1[1] *= bf_hi(g.z); y1[2] *= bf_lo(g.w); y1[3] *= bf_hi(g.w);
;                     u32x4* sp = (u32x4*)Sb + ((size_t)(tile * 16 + (ai * 2 + bj) * 4 + m) * NTHREADS + tid);
;                     if (br != 0) { const u32x4 t = *sp;
;                         y0[0] += bf_lo(t.x); y0[1] += bf_hi(t.x); y0[2] += bf_lo(t.y); y0[3] += bf_hi(t.y); y1[0] += bf_lo(t.z); y1[1] += bf_hi(t.z); y1[2] += bf_lo(t.w); y1[3] += bf_hi(t.w); }
;                     u32x4 w; w.x = cvt_pk_bf16(y0[0], y0[1]); w.y = cvt_pk_bf16(y0[2], y0[3]); w.z = cvt_pk_bf16(y1[0], y1[1]); w.w = cvt_pk_bf16(y1[2], y1[3]);
;                     if (br != 2) *sp = w;
	v_lshlrev_b32_e32 v224, 16, v160
	v_and_b32_e32 v225, 0xffff0000, v160
	v_mul_f32_e32 v132, v38, v224
	v_mul_f32_e32 v133, v39, v225
	v_lshlrev_b32_e32 v224, 16, v161
	v_and_b32_e32 v225, 0xffff0000, v161
	v_mul_f32_e32 v164, v40, v224
	v_mul_f32_e32 v165, v41, v225
	v_lshlrev_b32_e32 v224, 16, v162
	v_and_b32_e32 v225, 0xffff0000, v162
	v_mul_f32_e32 v168, v34, v224
	v_mul_f32_e32 v169, v35, v225
	v_lshlrev_b32_e32 v224, 16, v163
	v_and_b32_e32 v225, 0xffff0000, v163
	v_mul_f32_e32 v222, v36, v224
	v_mul_f32_e32 v223, v37, v225
	v_lshlrev_b32_e32 v224, 16, v202
	v_and_b32_e32 v225, 0xffff0000, v202
	v_add_f32_e32 v132, v132, v224
	v_add_f32_e32 v133, v133, v225
	v_lshlrev_b32_e32 v224, 16, v203
	v_and_b32_e32 v225, 0xffff0000, v203
	v_add_f32_e32 v164, v164, v224
	v_add_f32_e32 v165, v165, v225
	v_lshlrev_b32_e32 v224, 16, v204
	v_and_b32_e32 v225, 0xffff0000, v204
	v_add_f32_e32 v168, v168, v224
	v_add_f32_e32 v169, v169, v225
	v_lshlrev_b32_e32 v224, 16, v205
	v_and_b32_e32 v225, 0xffff0000, v205
	v_add_f32_e32 v222, v222, v224
	v_add_f32_e32 v223, v223, v225
	v_cvt_pk_bf16_f32 v218, v132, v133
	v_cvt_pk_bf16_f32 v219, v164, v165
	v_cvt_pk_bf16_f32 v220, v168, v169
	v_cvt_pk_bf16_f32 v221, v222, v223
	global_store_dwordx4 v166, v[218:221], s[44:45]
	s_add_u32 s44, s44, 0x2000
	s_addc_u32 s45, s45, 0
	global_load_dwordx4 v[160:163], v166, s[12:13]
	s_add_u32 s12, s12, 0x2000
	s_addc_u32 s13, s13, 0
	global_load_dwordx4 v[202:205], v166, s[20:21]
	s_add_u32 s20, s20, 0x2000
	s_addc_u32 s21, s21, 0
	s_waitcnt vmcnt(12)
	v_lshlrev_b32_e32 v224, 16, v174
	v_and_b32_e32 v225, 0xffff0000, v174
	v_mul_f32_e32 v132, v94, v224
	v_mul_f32_e32 v133, v95, v225
	v_lshlrev_b32_e32 v224, 16, v175
	v_and_b32_e32 v225, 0xffff0000, v175
	v_mul_f32_e32 v164, v96, v224
	v_mul_f32_e32 v165, v97, v225
	v_lshlrev_b32_e32 v224, 16, v176
	v_and_b32_e32 v225, 0xffff0000, v176
	v_mul_f32_e32 v168, v90, v224
	v_mul_f32_e32 v169, v91, v225
	v_lshlrev_b32_e32 v224, 16, v177
	v_and_b32_e32 v225, 0xffff0000, v177
	v_mul_f32_e32 v222, v92, v224
	v_mul_f32_e32 v223, v93, v225
	v_lshlrev_b32_e32 v224, 16, v206
	v_and_b32_e32 v225, 0xffff0000, v206
	v_add_f32_e32 v132, v132, v224
	v_add_f32_e32 v133, v133, v225
	v_lshlrev_b32_e32 v224, 16, v207
	v_and_b32_e32 v225, 0xffff0000, v207
	v_add_f32_e32 v164, v164, v224
	v_add_f32_e32 v165, v165, v225
	v_lshlrev_b32_e32 v224, 16, v208
	v_and_b32_e32 v225, 0xffff0000, v208
	v_add_f32_e32 v168, v168, v224
	v_add_f32_e32 v169, v169, v225
	v_lshlrev_b32_e32 v224, 16, v209
	v_and_b32_e32 v225, 0xffff0000, v209
	v_add_f32_e32 v222, v222, v224
	v_add_f32_e32 v223, v223, v225
	v_cvt_pk_bf16_f32 v214, v132, v133
	v_cvt_pk_bf16_f32 v215, v164, v165
	v_cvt_pk_bf16_f32 v216, v168, v169
	v_cvt_pk_bf16_f32 v217, v222, v223
	global_store_dwordx4 v166, v[214:217], s[44:45]
	s_add_u32 s44, s44, 0x2000
	s_addc_u32 s45, s45, 0
	global_load_dwordx4 v[174:177], v166, s[12:13]
	s_add_u32 s12, s12, 0x2000
	s_addc_u32 s13, s13, 0
	global_load_dwordx4 v[206:209], v166, s[20:21]
	s_add_u32 s20, s20, 0x2000
	s_addc_u32 s21, s21, 0
	s_waitcnt vmcnt(12)
	v_lshlrev_b32_e32 v224, 16, v178
	v_and_b32_e32 v225, 0xffff0000, v178
	v_mul_f32_e32 v132, v86, v224
	v_mul_f32_e32 v133, v87, v225
	v_lshlrev_b32_e32 v224, 16, v179
	v_and_b32_e32 v225, 0xffff0000, v179
	v_mul_f32_e32 v164, v88, v224
	v_mul_f32_e32 v165, v89, v225
	v_lshlrev_b32_e32 v224, 16, v180
	v_and_b32_e32 v225, 0xffff0000, v180
	v_mul_f32_e32 v168, v82, v224
	v_mul_f32_e32 v169, v83, v225
	v_lshlrev_b32_e32 v224, 16, v181
	v_and_b32_e32 v225, 0xffff0000, v181
	v_mul_f32_e32 v222, v84, v224
	v_mul_f32_e32 v223, v85, v225
	v_lshlrev_b32_e32 v224, 16, v210
	v_and_b32_e32 v225, 0xffff0000, v210
	v_add_f32_e32 v132, v132, v224
	v_add_f32_e32 v133, v133, v225
	v_lshlrev_b32_e32 v224, 16, v211
	v_and_b32_e32 v225, 0xffff0000, v211
	v_add_f32_e32 v164, v164, v224
	v_add_f32_e32 v165, v165, v225
	v_lshlrev_b32_e32 v224, 16, v212
	v_and_b32_e32 v225, 0xffff0000, v212
	v_add_f32_e32 v168, v168, v224
	v_add_f32_e32 v169, v169, v225
	v_lshlrev_b32_e32 v224, 16, v213
	v_and_b32_e32 v225, 0xffff0000, v213
	v_add_f32_e32 v222, v222, v224
	v_add_f32_e32 v223, v223, v225
	v_cvt_pk_bf16_f32 v218, v132, v133
	v_cvt_pk_bf16_f32 v219, v164, v165
	v_cvt_pk_bf16_f32 v220, v168, v169
	v_cvt_pk_bf16_f32 v221, v222, v223
	global_store_dwordx4 v166, v[218:221], s[44:45]
	s_add_u32 s44, s44, 0x2000
	s_addc_u32 s45, s45, 0
	global_load_dwordx4 v[178:181], v166, s[12:13]
	s_add_u32 s12, s12, 0x2000
	s_addc_u32 s13, s13, 0
	global_load_dwordx4 v[210:213], v166, s[20:21]
	s_add_u32 s20, s20, 0x2000
	s_addc_u32 s21, s21, 0
	s_waitcnt vmcnt(12)
	v_lshlrev_b32_e32 v224, 16, v152
	v_and_b32_e32 v225, 0xffff0000, v152
	v_mul_f32_e32 v132, v78, v224
	v_mul_f32_e32 v133, v79, v225
	v_lshlrev_b32_e32 v224, 16, v153
	v_and_b32_e32 v225, 0xffff0000, v153
	v_mul_f32_e32 v164, v80, v224
	v_mul_f32_e32 v165, v81, v225
	v_lshlrev_b32_e32 v224, 16, v154
	v_and_b32_e32 v225, 0xffff0000, v154
	v_mul_f32_e32 v168, v74, v224
	v_mul_f32_e32 v169, v75, v225
	v_lshlrev_b32_e32 v224, 16, v155
	v_and_b32_e32 v225, 0xffff0000, v155
	v_mul_f32_e32 v222, v76, v224
	v_mul_f32_e32 v223, v77, v225
	v_lshlrev_b32_e32 v224, 16, v182
	v_and_b32_e32 v225, 0xffff0000, v182
	v_add_f32_e32 v132, v132, v224
	v_add_f32_e32 v133, v133, v225
	v_lshlrev_b32_e32 v224, 16, v183
	v_and_b32_e32 v225, 0xffff0000, v183
	v_add_f32_e32 v164, v164, v224
	v_add_f32_e32 v165, v165, v225
	v_lshlrev_b32_e32 v224, 16, v184
	v_and_b32_e32 v225, 0xffff0000, v184
	v_add_f32_e32 v168, v168, v224
	v_add_f32_e32 v169, v169, v225
	v_lshlrev_b32_e32 v224, 16, v185
	v_and_b32_e32 v225, 0xffff0000, v185
	v_add_f32_e32 v222, v222, v224
	v_add_f32_e32 v223, v223, v225
	v_cvt_pk_bf16_f32 v214, v132, v133
	v_cvt_pk_bf16_f32 v215, v164, v165
	v_cvt_pk_bf16_f32 v216, v168, v169
	v_cvt_pk_bf16_f32 v217, v222, v223
	global_store_dwordx4 v166, v[214:217], s[44:45]
	s_add_u32 s44, s44, 0x2000
	s_addc_u32 s45, s45, 0
	global_load_dwordx4 v[152:155], v166, s[12:13]
	s_add_u32 s12, s12, 0x2000
	s_addc_u32 s13, s13, 0
	global_load_dwordx4 v[182:185], v166, s[20:21]
	s_add_u32 s20, s20, 0x2000
	s_addc_u32 s21, s21, 0
	s_waitcnt vmcnt(12)
; __device__ __forceinline__ unsigned cvt_pk_bf16(float lo, float hi) { const f32x2 v = {lo, hi}; const bf16x2_t b = __builtin_convertvector(v, bf16x2_t); return __builtin_bit_cast(unsigned, b); }
; __device__ __forceinline__ float bf_lo(unsigned u) { return __uint_as_float(u << 16); }
; __device__ __forceinline__ float bf_hi(unsigned u) { return __uint_as_float(u & 0xffff0000u); }
;     __device__ __forceinline__ void operator()(const f32x4 (&acc)[2][2][4][2], const Unit& u, int wr, int wc, int fr, int fq) const {
;     ...
;         for (int ai = 0; ai < 2; ++ai)
; #pragma unroll
;             for (int bj = 0; bj < 2; ++bj)
; #pragma unroll
;                 for (int m = 0; m < 4; ++m) {
;                     const u32x4 g = *((const u32x4*)Gs + ((size_t)(tile * 16 + (ai * 2 + bj) * 4 + m) * NTHREADS + tid));
;                     f32x4 y0 = acc[ai][bj][m][0], y1 = acc[ai][bj][m][1];
;                     y0[0] *= bf_lo(g.x); y0[1] *= bf_hi(g.x); y0[2] *= bf_lo(g.y); y0[3] *= bf_hi(g.y);
;                     y1[0] *= bf_lo(g.z); y1[1] *= bf_hi(g.z); y1[2] *= bf_lo(g.w); y1[3] *= bf_hi(g.w);
;                     u32x4* sp = (u32x4*)Sb + ((size_t)(tile * 16 + (ai * 2 + bj) * 4 + m) * NTHREADS + tid);
;                     if (br != 0) { const u32x4 t = *sp;
;                         y0[0] += bf_lo(t.x); y0[1] += bf_hi(t.x); y0[2] += bf_lo(t.y); y0[3] += bf_hi(t.y); y1[0] += bf_lo(t.z); y1[1] += bf_hi(t.z); y1[2] += bf_lo(t.w); y1[3] += bf_hi(t.w); }
;                     u32x4 w; w.x = cvt_pk_bf16(y0[0], y0[1]); w.y = cvt_pk_bf16(y0[2], y0[3]); w.z = cvt_pk_bf16(y1[0], y1[1]); w.w = cvt_pk_bf16(y1[2], y1[3]);
;                     if (br != 2) *sp = w;
	v_lshlrev_b32_e32 v224, 16, v156
	v_and_b32_e32 v225, 0xffff0000, v156
	v_mul_f32_e32 v132, v70, v224
	v_mul_f32_e32 v133, v71, v225
	v_lshlrev_b32_e32 v224, 16, v157
	v_and_b32_e32 v225, 0xffff0000, v157
	v_mul_f32_e32 v164, v72, v224
	v_mul_f32_e32 v165, v73, v225
	v_lshlrev_b32_e32 v224, 16, v158
	v_and_b32_e32 v225, 0xffff0000, v158
	v_mul_f32_e32 v168, v66, v224
	v_mul_f32_e32 v169, v67, v225
	v_lshlrev_b32_e32 v224, 16, v159
	v_and_b32_e32 v225, 0xffff0000, v159
	v_mul_f32_e32 v222, v68, v224
	v_mul_f32_e32 v223, v69, v225
	v_lshlrev_b32_e32 v224, 16, v186
	v_and_b32_e32 v225, 0xffff0000, v186
	v_add_f32_e32 v132, v132, v224
	v_add_f32_e32 v133, v133, v225
	v_lshlrev_b32_e32 v224, 16, v187
	v_and_b32_e32 v225, 0xffff0000, v187
	v_add_f32_e32 v164, v164, v224
	v_add_f32_e32 v165, v165, v225
	v_lshlrev_b32_e32 v224, 16, v188
	v_and_b32_e32 v225, 0xffff0000, v188
	v_add_f32_e32 v168, v168, v224
	v_add_f32_e32 v169, v169, v225
	v_lshlrev_b32_e32 v224, 16, v189
	v_and_b32_e32 v225, 0xffff0000, v189
	v_add_f32_e32 v222, v222, v224
	v_add_f32_e32 v223, v223, v225
	v_cvt_pk_bf16_f32 v218, v132, v133
	v_cvt_pk_bf16_f32 v219, v164, v165
	v_cvt_pk_bf16_f32 v220, v168, v169
	v_cvt_pk_bf16_f32 v221, v222, v223
	global_store_dwordx4 v166, v[218:221], s[44:45]
	s_add_u32 s44, s44, 0x2000
	s_addc_u32 s45, s45, 0
	s_waitcnt vmcnt(10)
	v_lshlrev_b32_e32 v224, 16, v160
	v_and_b32_e32 v225, 0xffff0000, v160
	v_mul_f32_e32 v132, v30, v224
	v_mul_f32_e32 v133, v31, v225
	v_lshlrev_b32_e32 v224, 16, v161
	v_and_b32_e32 v225, 0xffff0000, v161
	v_mul_f32_e32 v164, v32, v224
	v_mul_f32_e32 v165, v33, v225
	v_lshlrev_b32_e32 v224, 16, v162
	v_and_b32_e32 v225, 0xffff0000, v162
	v_mul_f32_e32 v168, v26, v224
	v_mul_f32_e32 v169, v27, v225
	v_lshlrev_b32_e32 v224, 16, v163
	v_and_b32_e32 v225, 0xffff0000, v163
	v_mul_f32_e32 v222, v28, v224
	v_mul_f32_e32 v223, v29, v225
	v_lshlrev_b32_e32 v224, 16, v202
	v_and_b32_e32 v225, 0xffff0000, v202
	v_add_f32_e32 v132, v132, v224
	v_add_f32_e32 v133, v133, v225
	v_lshlrev_b32_e32 v224, 16, v203
	v_and_b32_e32 v225, 0xffff0000, v203
	v_add_f32_e32 v164, v164, v224
	v_add_f32_e32 v165, v165, v225
	v_lshlrev_b32_e32 v224, 16, v204
	v_and_b32_e32 v225, 0xffff0000, v204
	v_add_f32_e32 v168, v168, v224
	v_add_f32_e32 v169, v169, v225
	v_lshlrev_b32_e32 v224, 16, v205
	v_and_b32_e32 v225, 0xffff0000, v205
	v_add_f32_e32 v222, v222, v224
	v_add_f32_e32 v223, v223, v225
	v_cvt_pk_bf16_f32 v214, v132, v133
	v_cvt_pk_bf16_f32 v215, v164, v165
	v_cvt_pk_bf16_f32 v216, v168, v169
	v_cvt_pk_bf16_f32 v217, v222, v223
	global_store_dwordx4 v166, v[214:217], s[44:45]
	s_add_u32 s44, s44, 0x2000
	s_addc_u32 s45, s45, 0
	s_waitcnt vmcnt(8)
	v_lshlrev_b32_e32 v224, 16, v174
	v_and_b32_e32 v225, 0xffff0000, v174
	v_mul_f32_e32 v132, v22, v224
	v_mul_f32_e32 v133, v23, v225
	v_lshlrev_b32_e32 v224, 16, v175
	v_and_b32_e32 v225, 0xffff0000, v175
	v_mul_f32_e32 v164, v24, v224
	v_mul_f32_e32 v165, v25, v225
	v_lshlrev_b32_e32 v224, 16, v176
	v_and_b32_e32 v225, 0xffff0000, v176
	v_mul_f32_e32 v168, v18, v224
	v_mul_f32_e32 v169, v19, v225
	v_lshlrev_b32_e32 v224, 16, v177
	v_and_b32_e32 v225, 0xffff0000, v177
	v_mul_f32_e32 v222, v20, v224
	v_mul_f32_e32 v223, v21, v225
	v_lshlrev_b32_e32 v224, 16, v206
	v_and_b32_e32 v225, 0xffff0000, v206
	v_add_f32_e32 v132, v132, v224
	v_add_f32_e32 v133, v133, v225
	v_lshlrev_b32_e32 v224, 16, v207
	v_and_b32_e32 v225, 0xffff0000, v207
	v_add_f32_e32 v164, v164, v224
	v_add_f32_e32 v165, v165, v225
	v_lshlrev_b32_e32 v224, 16, v208
	v_and_b32_e32 v225, 0xffff0000, v208
	v_add_f32_e32 v168, v168, v224
	v_add_f32_e32 v169, v169, v225
	v_lshlrev_b32_e32 v224, 16, v209
	v_and_b32_e32 v225, 0xffff0000, v209
	v_add_f32_e32 v222, v222, v224
	v_add_f32_e32 v223, v223, v225
	v_cvt_pk_bf16_f32 v218, v132, v133
	v_cvt_pk_bf16_f32 v219, v164, v165
	v_cvt_pk_bf16_f32 v220, v168, v169
	v_cvt_pk_bf16_f32 v221, v222, v223
	global_store_dwordx4 v166, v[218:221], s[44:45]
	s_add_u32 s44, s44, 0x2000
	s_addc_u32 s45, s45, 0
	s_waitcnt vmcnt(6)
	v_lshlrev_b32_e32 v224, 16, v178
	v_and_b32_e32 v225, 0xffff0000, v178
	v_mul_f32_e32 v132, v14, v224
	v_mul_f32_e32 v133, v15, v225
	v_lshlrev_b32_e32 v224, 16, v179
	v_and_b32_e32 v225, 0xffff0000, v179
	v_mul_f32_e32 v164, v16, v224
	v_mul_f32_e32 v165, v17, v225
	v_lshlrev_b32_e32 v224, 16, v180
	v_and_b32_e32 v225, 0xffff0000, v180
	v_mul_f32_e32 v168, v10, v224
	v_mul_f32_e32 v169, v11, v225
	v_lshlrev_b32_e32 v224, 16, v181
	v_and_b32_e32 v225, 0xffff0000, v181
	v_mul_f32_e32 v222, v12, v224
	v_mul_f32_e32 v223, v13, v225
	v_lshlrev_b32_e32 v224, 16, v210
	v_and_b32_e32 v225, 0xffff0000, v210
	v_add_f32_e32 v132, v132, v224
	v_add_f32_e32 v133, v133, v225
	v_lshlrev_b32_e32 v224, 16, v211
	v_and_b32_e32 v225, 0xffff0000, v211
	v_add_f32_e32 v164, v164, v224
	v_add_f32_e32 v165, v165, v225
	v_lshlrev_b32_e32 v224, 16, v212
	v_and_b32_e32 v225, 0xffff0000, v212
	v_add_f32_e32 v168, v168, v224
	v_add_f32_e32 v169, v169, v225
	v_lshlrev_b32_e32 v224, 16, v213
	v_and_b32_e32 v225, 0xffff0000, v213
	v_add_f32_e32 v222, v222, v224
	v_add_f32_e32 v223, v223, v225
	v_cvt_pk_bf16_f32 v214, v132, v133
	v_cvt_pk_bf16_f32 v215, v164, v165
	v_cvt_pk_bf16_f32 v216, v168, v169
	v_cvt_pk_bf16_f32 v217, v222, v223
	global_store_dwordx4 v166, v[214:217], s[44:45]
	s_add_u32 s44, s44, 0x2000
	s_addc_u32 s45, s45, 0
	s_waitcnt vmcnt(4)
	v_lshlrev_b32_e32 v224, 16, v152
	v_and_b32_e32 v225, 0xffff0000, v152
	v_mul_f32_e32 v132, v6, v224
	v_mul_f32_e32 v133, v7, v225
	v_lshlrev_b32_e32 v224, 16, v153
	v_and_b32_e32 v225, 0xffff0000, v153
	v_mul_f32_e32 v164, v8, v224
	v_mul_f32_e32 v165, v9, v225
	v_lshlrev_b32_e32 v224, 16, v154
	v_and_b32_e32 v225, 0xffff0000, v154
	v_mul_f32_e32 v168, v2, v224
	v_mul_f32_e32 v169, v3, v225
	v_lshlrev_b32_e32 v224, 16, v155
	v_and_b32_e32 v225, 0xffff0000, v155
	v_mul_f32_e32 v222, v4, v224
	v_mul_f32_e32 v223, v5, v225
	v_lshlrev_b32_e32 v224, 16, v182
	v_and_b32_e32 v225, 0xffff0000, v182
	v_add_f32_e32 v132, v132, v224
	v_add_f32_e32 v133, v133, v225
	v_lshlrev_b32_e32 v224, 16, v183
	v_and_b32_e32 v225, 0xffff0000, v183
	v_add_f32_e32 v164, v164, v224
	v_add_f32_e32 v165, v165, v225
	v_lshlrev_b32_e32 v224, 16, v184
	v_and_b32_e32 v225, 0xffff0000, v184
	v_add_f32_e32 v168, v168, v224
	v_add_f32_e32 v169, v169, v225
	v_lshlrev_b32_e32 v224, 16, v185
	v_and_b32_e32 v225, 0xffff0000, v185
	v_add_f32_e32 v222, v222, v224
	v_add_f32_e32 v223, v223, v225
	v_cvt_pk_bf16_f32 v218, v132, v133
	v_cvt_pk_bf16_f32 v219, v164, v165
	v_cvt_pk_bf16_f32 v220, v168, v169
	v_cvt_pk_bf16_f32 v221, v222, v223
	global_store_dwordx4 v166, v[218:221], s[44:45]
	s_add_u32 s44, s44, 0x2000
	s_addc_u32 s45, s45, 0
	s_branch .LBB0_304
; __device__ __forceinline__ unsigned cvt_pk_bf16(float lo, float hi) { const f32x2 v = {lo, hi}; const bf16x2_t b = __builtin_convertvector(v, bf16x2_t); return __builtin_bit_cast(unsigned, b); }
; __device__ __forceinline__ float bf_lo(unsigned u) { return __uint_as_float(u << 16); }
; __device__ __forceinline__ float bf_hi(unsigned u) { return __uint_as_float(u & 0xffff0000u); }
;     __device__ __forceinline__ void operator()(const f32x4 (&acc)[2][2][4][2], const Unit& u, int wr, int wc, int fr, int fq) const {
;     ...
;         for (int ai = 0; ai < 2; ++ai)
; #pragma unroll
;             for (int bj = 0; bj < 2; ++bj)
; #pragma unroll
;                 for (int m = 0; m < 4; ++m) {
;                     const u32x4 g = *((const u32x4*)Gs + ((size_t)(tile * 16 + (ai * 2 + bj) * 4 + m) * NTHREADS + tid));
;                     f32x4 y0 = acc[ai][bj][m][0], y1 = acc[ai][bj][m][1];
;                     y0[0] *= bf_lo(g.x); y0[1] *= bf_hi(g.x); y0[2] *= bf_lo(g.y); y0[3] *= bf_hi(g.y);
;                     y1[0] *= bf_lo(g.z); y1[1] *= bf_hi(g.z); y1[2] *= bf_lo(g.w); y1[3] *= bf_hi(g.w);
;                     u32x4* sp = (u32x4*)Sb + ((size_t)(tile * 16 + (ai * 2 + bj) * 4 + m) * NTHREADS + tid);
;                     if (br != 0) { const u32x4 t = *sp;
;                         y0[0] += bf_lo(t.x); y0[1] += bf_hi(t.x); y0[2] += bf_lo(t.y); y0[3] += bf_hi(t.y); y1[0] += bf_lo(t.z); y1[1] += bf_hi(t.z); y1[2] += bf_lo(t.w); y1[3] += bf_hi(t.w); }
;                     u32x4 w; w.x = cvt_pk_bf16(y0[0], y0[1]); w.y = cvt_pk_bf16(y0[2], y0[3]); w.z = cvt_pk_bf16(y1[0], y1[1]); w.w = cvt_pk_bf16(y1[2], y1[3]);
;                     if (br != 2) *sp = w;
.Lpl_br0:
	global_load_dwordx4 v[152:155], v166, s[12:13]
	s_add_u32 s12, s12, 0x2000
	s_addc_u32 s13, s13, 0
	global_load_dwordx4 v[156:159], v166, s[12:13]
	s_add_u32 s12, s12, 0x2000
	s_addc_u32 s13, s13, 0
	global_load_dwordx4 v[160:163], v166, s[12:13]
	s_add_u32 s12, s12, 0x2000
	s_addc_u32 s13, s13, 0
	global_load_dwordx4 v[174:177], v166, s[12:13]
	s_add_u32 s12, s12, 0x2000
	s_addc_u32 s13, s13, 0
	global_load_dwordx4 v[178:181], v166, s[12:13]
	s_add_u32 s12, s12, 0x2000
	s_addc_u32 s13, s13, 0
	s_waitcnt vmcnt(4)
	v_lshlrev_b32_e32 v224, 16, v152
	v_and_b32_e32 v225, 0xffff0000, v152
	v_mul_f32_e32 v132, v126, v224
	v_mul_f32_e32 v133, v127, v225
	v_lshlrev_b32_e32 v224, 16, v153
	v_and_b32_e32 v225, 0xffff0000, v153
	v_mul_f32_e32 v164, v128, v224
	v_mul_f32_e32 v165, v129, v225
	v_lshlrev_b32_e32 v224, 16, v154
	v_and_b32_e32 v225, 0xffff0000, v154
	v_mul_f32_e32 v168, v122, v224
	v_mul_f32_e32 v169, v123, v225
	v_lshlrev_b32_e32 v224, 16, v155
	v_and_b32_e32 v225, 0xffff0000, v155
	v_mul_f32_e32 v222, v124, v224
	v_mul_f32_e32 v223, v125, v225
	v_cvt_pk_bf16_f32 v214, v132, v133
	v_cvt_pk_bf16_f32 v215, v164, v165
	v_cvt_pk_bf16_f32 v216, v168, v169
	v_cvt_pk_bf16_f32 v217, v222, v223
	global_store_dwordx4 v166, v[214:217], s[44:45]
	s_add_u32 s44, s44, 0x2000
	s_addc_u32 s45, s45, 0
	global_load_dwordx4 v[152:155], v166, s[12:13]
	s_add_u32 s12, s12, 0x2000
	s_addc_u32 s13, s13, 0
	s_waitcnt vmcnt(5)
	v_lshlrev_b32_e32 v224, 16, v156
	v_and_b32_e32 v225, 0xffff0000, v156
	v_mul_f32_e32 v132, v118, v224
	v_mul_f32_e32 v133, v119, v225
	v_lshlrev_b32_e32 v224, 16, v157
	v_and_b32_e32 v225, 0xffff0000, v157
	v_mul_f32_e32 v164, v120, v224
	v_mul_f32_e32 v165, v121, v225
	v_lshlrev_b32_e32 v224, 16, v158
	v_and_b32_e32 v225, 0xffff0000, v158
	v_mul_f32_e32 v168, v114, v224
	v_mul_f32_e32 v169, v115, v225
	v_lshlrev_b32_e32 v224, 16, v159
	v_and_b32_e32 v225, 0xffff0000, v159
	v_mul_f32_e32 v222, v116, v224
	v_mul_f32_e32 v223, v117, v225
	v_cvt_pk_bf16_f32 v218, v132, v133
	v_cvt_pk_bf16_f32 v219, v164, v165
	v_cvt_pk_bf16_f32 v220, v168, v169
	v_cvt_pk_bf16_f32 v221, v222, v223
	global_store_dwordx4 v166, v[218:221], s[44:45]
	s_add_u32 s44, s44, 0x2000
	s_addc_u32 s45, s45, 0
	global_load_dwordx4 v[156:159], v166, s[12:13]
	s_add_u32 s12, s12, 0x2000
	s_addc_u32 s13, s13, 0
	s_waitcnt vmcnt(6)
	v_lshlrev_b32_e32 v224, 16, v160
	v_and_b32_e32 v225, 0xffff0000, v160
	v_mul_f32_e32 v132, v110, v224
	v_mul_f32_e32 v133, v111, v225
	v_lshlrev_b32_e32 v224, 16, v161
	v_and_b32_e32 v225, 0xffff0000, v161
	v_mul_f32_e32 v164, v112, v224
	v_mul_f32_e32 v165, v113, v225
	v_lshlrev_b32_e32 v224, 16, v162
	v_and_b32_e32 v225, 0xffff0000, v162
	v_mul_f32_e32 v168, v106, v224
	v_mul_f32_e32 v169, v107, v225
	v_lshlrev_b32_e32 v224, 16, v163
	v_and_b32_e32 v225, 0xffff0000, v163
	v_mul_f32_e32 v222, v108, v224
	v_mul_f32_e32 v223, v109, v225
	v_cvt_pk_bf16_f32 v214, v132, v133
	v_cvt_pk_bf16_f32 v215, v164, v165
	v_cvt_pk_bf16_f32 v216, v168, v169
	v_cvt_pk_bf16_f32 v217, v222, v223
	global_store_dwordx4 v166, v[214:217], s[44:45]
	s_add_u32 s44, s44, 0x2000
	s_addc_u32 s45, s45, 0
	global_load_dwordx4 v[160:163], v166, s[12:13]
	s_add_u32 s12, s12, 0x2000
	s_addc_u32 s13, s13, 0
	s_waitcnt vmcnt(7)
	v_lshlrev_b32_e32 v224, 16, v174
	v_and_b32_e32 v225, 0xffff0000, v174
	v_mul_f32_e32 v132, v102, v224
	v_mul_f32_e32 v133, v103, v225
	v_lshlrev_b32_e32 v224, 16, v175
	v_and_b32_e32 v225, 0xffff0000, v175
	v_mul_f32_e32 v164, v104, v224
	v_mul_f32_e32 v165, v105, v225
	v_lshlrev_b32_e32 v224, 16, v176
	v_and_b32_e32 v225, 0xffff0000, v176
	v_mul_f32_e32 v168, v98, v224
	v_mul_f32_e32 v169, v99, v225
	v_lshlrev_b32_e32 v224, 16, v177
	v_and_b32_e32 v225, 0xffff0000, v177
	v_mul_f32_e32 v222, v100, v224
	v_mul_f32_e32 v223, v101, v225
	v_cvt_pk_bf16_f32 v218, v132, v133
	v_cvt_pk_bf16_f32 v219, v164, v165
	v_cvt_pk_bf16_f32 v220, v168, v169
	v_cvt_pk_bf16_f32 v221, v222, v223
	global_store_dwordx4 v166, v[218:221], s[44:45]
	s_add_u32 s44, s44, 0x2000
	s_addc_u32 s45, s45, 0
	global_load_dwordx4 v[174:177], v166, s[12:13]
	s_add_u32 s12, s12, 0x2000
	s_addc_u32 s13, s13, 0
	s_waitcnt vmcnt(8)
	v_lshlrev_b32_e32 v224, 16, v178
	v_and_b32_e32 v225, 0xffff0000, v178
	v_mul_f32_e32 v132, v62, v224
	v_mul_f32_e32 v133, v63, v225
	v_lshlrev_b32_e32 v224, 16, v179
	v_and_b32_e32 v225, 0xffff0000, v179
	v_mul_f32_e32 v164, v64, v224
	v_mul_f32_e32 v165, v65, v225
	v_lshlrev_b32_e32 v224, 16, v180
	v_and_b32_e32 v225, 0xffff0000, v180
	v_mul_f32_e32 v168, v58, v224
	v_mul_f32_e32 v169, v59, v225
	v_lshlrev_b32_e32 v224, 16, v181
	v_and_b32_e32 v225, 0xffff0000, v181
	v_mul_f32_e32 v222, v60, v224
	v_mul_f32_e32 v223, v61, v225
	v_cvt_pk_bf16_f32 v214, v132, v133
	v_cvt_pk_bf16_f32 v215, v164, v165
	v_cvt_pk_bf16_f32 v216, v168, v169
	v_cvt_pk_bf16_f32 v217, v222, v223
	global_store_dwordx4 v166, v[214:217], s[44:45]
	s_add_u32 s44, s44, 0x2000
	s_addc_u32 s45, s45, 0
	global_load_dwordx4 v[178:181], v166, s[12:13]
	s_add_u32 s12, s12, 0x2000
	s_addc_u32 s13, s13, 0
	s_waitcnt vmcnt(8)
	v_lshlrev_b32_e32 v224, 16, v152
	v_and_b32_e32 v225, 0xffff0000, v152
	v_mul_f32_e32 v132, v54, v224
	v_mul_f32_e32 v133, v55, v225
	v_lshlrev_b32_e32 v224, 16, v153
	v_and_b32_e32 v225, 0xffff0000, v153
	v_mul_f32_e32 v164, v56, v224
	v_mul_f32_e32 v165, v57, v225
	v_lshlrev_b32_e32 v224, 16, v154
	v_and_b32_e32 v225, 0xffff0000, v154
	v_mul_f32_e32 v168, v50, v224
	v_mul_f32_e32 v169, v51, v225
	v_lshlrev_b32_e32 v224, 16, v155
	v_and_b32_e32 v225, 0xffff0000, v155
	v_mul_f32_e32 v222, v52, v224
	v_mul_f32_e32 v223, v53, v225
	v_cvt_pk_bf16_f32 v218, v132, v133
	v_cvt_pk_bf16_f32 v219, v164, v165
	v_cvt_pk_bf16_f32 v220, v168, v169
	v_cvt_pk_bf16_f32 v221, v222, v223
	global_store_dwordx4 v166, v[218:221], s[44:45]
	s_add_u32 s44, s44, 0x2000
	s_addc_u32 s45, s45, 0
	global_load_dwordx4 v[152:155], v166, s[12:13]
	s_add_u32 s12, s12, 0x2000
	s_addc_u32 s13, s13, 0
	s_waitcnt vmcnt(8)
; __device__ __forceinline__ unsigned cvt_pk_bf16(float lo, float hi) { const f32x2 v = {lo, hi}; const bf16x2_t b = __builtin_convertvector(v, bf16x2_t); return __builtin_bit_cast(unsigned, b); }
; __device__ __forceinline__ float bf_lo(unsigned u) { return __uint_as_float(u << 16); }
; __device__ __forceinline__ float bf_hi(unsigned u) { return __uint_as_float(u & 0xffff0000u); }
;     __device__ __forceinline__ void operator()(const f32x4 (&acc)[2][2][4][2], const Unit& u, int wr, int wc, int fr, int fq) const {
;     ...
;         for (int ai = 0; ai < 2; ++ai)
; #pragma unroll
;             for (int bj = 0; bj < 2; ++bj)
; #pragma unroll
;                 for (int m = 0; m < 4; ++m) {
;                     const u32x4 g = *((const u32x4*)Gs + ((size_t)(tile * 16 + (ai * 2 + bj) * 4 + m) * NTHREADS + tid));
;                     f32x4 y0 = acc[ai][bj][m][0], y1 = acc[ai][bj][m][1];
;                     y0[0] *= bf_lo(g.x); y0[1] *= bf_hi(g.x); y0[2] *= bf_lo(g.y); y0[3] *= bf_hi(g.y);
;                     y1[0] *= bf_lo(g.z); y1[1] *= bf_hi(g.z); y1[2] *= bf_lo(g.w); y1[3] *= bf_hi(g.w);
;                     u32x4* sp = (u32x4*)Sb + ((size_t)(tile * 16 + (ai * 2 + bj) * 4 + m) * NTHREADS + tid);
;                     if (br != 0) { const u32x4 t = *sp;
;                         y0[0] += bf_lo(t.x); y0[1] += bf_hi(t.x); y0[2] += bf_lo(t.y); y0[3] += bf_hi(t.y); y1[0] += bf_lo(t.z); y1[1] += bf_hi(t.z); y1[2] += bf_lo(t.w); y1[3] += bf_hi(t.w); }
;                     u32x4 w; w.x = cvt_pk_bf16(y0[0], y0[1]); w.y = cvt_pk_bf16(y0[2], y0[3]); w.z = cvt_pk_bf16(y1[0], y1[1]); w.w = cvt_pk_bf16(y1[2], y1[3]);
;                     if (br != 2) *sp = w;
	v_lshlrev_b32_e32 v224, 16, v156
	v_and_b32_e32 v225, 0xffff0000, v156
	v_mul_f32_e32 v132, v46, v224
	v_mul_f32_e32 v133, v47, v225
	v_lshlrev_b32_e32 v224, 16, v157
	v_and_b32_e32 v225, 0xffff0000, v157
	v_mul_f32_e32 v164, v48, v224
	v_mul_f32_e32 v165, v49, v225
	v_lshlrev_b32_e32 v224, 16, v158
	v_and_b32_e32 v225, 0xffff0000, v158
	v_mul_f32_e32 v168, v42, v224
	v_mul_f32_e32 v169, v43, v225
	v_lshlrev_b32_e32 v224, 16, v159
	v_and_b32_e32 v225, 0xffff0000, v159
	v_mul_f32_e32 v222, v44, v224
	v_mul_f32_e32 v223, v45, v225
	v_cvt_pk_bf16_f32 v214, v132, v133
	v_cvt_pk_bf16_f32 v215, v164, v165
	v_cvt_pk_bf16_f32 v216, v168, v169
	v_cvt_pk_bf16_f32 v217, v222, v223
	global_store_dwordx4 v166, v[214:217], s[44:45]
	s_add_u32 s44, s44, 0x2000
	s_addc_u32 s45, s45, 0
	global_load_dwordx4 v[156:159], v166, s[12:13]
	s_add_u32 s12, s12, 0x2000
	s_addc_u32 s13, s13, 0
	s_waitcnt vmcnt(8)
	v_lshlrev_b32_e32 v224, 16, v160
	v_and_b32_e32 v225, 0xffff0000, v160
	v_mul_f32_e32 v132, v38, v224
	v_mul_f32_e32 v133, v39, v225
	v_lshlrev_b32_e32 v224, 16, v161
	v_and_b32_e32 v225, 0xffff0000, v161
	v_mul_f32_e32 v164, v40, v224
	v_mul_f32_e32 v165, v41, v225
	v_lshlrev_b32_e32 v224, 16, v162
	v_and_b32_e32 v225, 0xffff0000, v162
	v_mul_f32_e32 v168, v34, v224
	v_mul_f32_e32 v169, v35, v225
	v_lshlrev_b32_e32 v224, 16, v163
	v_and_b32_e32 v225, 0xffff0000, v163
	v_mul_f32_e32 v222, v36, v224
	v_mul_f32_e32 v223, v37, v225
	v_cvt_pk_bf16_f32 v218, v132, v133
	v_cvt_pk_bf16_f32 v219, v164, v165
	v_cvt_pk_bf16_f32 v220, v168, v169
	v_cvt_pk_bf16_f32 v221, v222, v223
	global_store_dwordx4 v166, v[218:221], s[44:45]
	s_add_u32 s44, s44, 0x2000
	s_addc_u32 s45, s45, 0
	global_load_dwordx4 v[160:163], v166, s[12:13]
	s_add_u32 s12, s12, 0x2000
	s_addc_u32 s13, s13, 0
	s_waitcnt vmcnt(8)
	v_lshlrev_b32_e32 v224, 16, v174
	v_and_b32_e32 v225, 0xffff0000, v174
	v_mul_f32_e32 v132, v94, v224
	v_mul_f32_e32 v133, v95, v225
	v_lshlrev_b32_e32 v224, 16, v175
	v_and_b32_e32 v225, 0xffff0000, v175
	v_mul_f32_e32 v164, v96, v224
	v_mul_f32_e32 v165, v97, v225
	v_lshlrev_b32_e32 v224, 16, v176
	v_and_b32_e32 v225, 0xffff0000, v176
	v_mul_f32_e32 v168, v90, v224
	v_mul_f32_e32 v169, v91, v225
	v_lshlrev_b32_e32 v224, 16, v177
	v_and_b32_e32 v225, 0xffff0000, v177
	v_mul_f32_e32 v222, v92, v224
	v_mul_f32_e32 v223, v93, v225
	v_cvt_pk_bf16_f32 v214, v132, v133
	v_cvt_pk_bf16_f32 v215, v164, v165
	v_cvt_pk_bf16_f32 v216, v168, v169
	v_cvt_pk_bf16_f32 v217, v222, v223
	global_store_dwordx4 v166, v[214:217], s[44:45]
	s_add_u32 s44, s44, 0x2000
	s_addc_u32 s45, s45, 0
	global_load_dwordx4 v[174:177], v166, s[12:13]
	s_add_u32 s12, s12, 0x2000
	s_addc_u32 s13, s13, 0
	s_waitcnt vmcnt(8)
	v_lshlrev_b32_e32 v224, 16, v178
	v_and_b32_e32 v225, 0xffff0000, v178
	v_mul_f32_e32 v132, v86, v224
	v_mul_f32_e32 v133, v87, v225
	v_lshlrev_b32_e32 v224, 16, v179
	v_and_b32_e32 v225, 0xffff0000, v179
	v_mul_f32_e32 v164, v88, v224
	v_mul_f32_e32 v165, v89, v225
	v_lshlrev_b32_e32 v224, 16, v180
	v_and_b32_e32 v225, 0xffff0000, v180
	v_mul_f32_e32 v168, v82, v224
	v_mul_f32_e32 v169, v83, v225
	v_lshlrev_b32_e32 v224, 16, v181
	v_and_b32_e32 v225, 0xffff0000, v181
	v_mul_f32_e32 v222, v84, v224
	v_mul_f32_e32 v223, v85, v225
	v_cvt_pk_bf16_f32 v218, v132, v133
	v_cvt_pk_bf16_f32 v219, v164, v165
	v_cvt_pk_bf16_f32 v220, v168, v169
	v_cvt_pk_bf16_f32 v221, v222, v223
	global_store_dwordx4 v166, v[218:221], s[44:45]
	s_add_u32 s44, s44, 0x2000
	s_addc_u32 s45, s45, 0
	global_load_dwordx4 v[178:181], v166, s[12:13]
	s_add_u32 s12, s12, 0x2000
	s_addc_u32 s13, s13, 0
	s_waitcnt vmcnt(8)
	v_lshlrev_b32_e32 v224, 16, v152
	v_and_b32_e32 v225, 0xffff0000, v152
	v_mul_f32_e32 v132, v78, v224
	v_mul_f32_e32 v133, v79, v225
	v_lshlrev_b32_e32 v224, 16, v153
	v_and_b32_e32 v225, 0xffff0000, v153
	v_mul_f32_e32 v164, v80, v224
	v_mul_f32_e32 v165, v81, v225
	v_lshlrev_b32_e32 v224, 16, v154
	v_and_b32_e32 v225, 0xffff0000, v154
	v_mul_f32_e32 v168, v74, v224
	v_mul_f32_e32 v169, v75, v225
	v_lshlrev_b32_e32 v224, 16, v155
	v_and_b32_e32 v225, 0xffff0000, v155
	v_mul_f32_e32 v222, v76, v224
	v_mul_f32_e32 v223, v77, v225
	v_cvt_pk_bf16_f32 v214, v132, v133
	v_cvt_pk_bf16_f32 v215, v164, v165
	v_cvt_pk_bf16_f32 v216, v168, v169
	v_cvt_pk_bf16_f32 v217, v222, v223
	global_store_dwordx4 v166, v[214:217], s[44:45]
	s_add_u32 s44, s44, 0x2000
	s_addc_u32 s45, s45, 0
	global_load_dwordx4 v[152:155], v166, s[12:13]
	s_add_u32 s12, s12, 0x2000
	s_addc_u32 s13, s13, 0
	s_waitcnt vmcnt(8)
; __device__ __forceinline__ unsigned cvt_pk_bf16(float lo, float hi) { const f32x2 v = {lo, hi}; const bf16x2_t b = __builtin_convertvector(v, bf16x2_t); return __builtin_bit_cast(unsigned, b); }
; __device__ __forceinline__ float bf_lo(unsigned u) { return __uint_as_float(u << 16); }
; __device__ __forceinline__ float bf_hi(unsigned u) { return __uint_as_float(u & 0xffff0000u); }
;     __device__ __forceinline__ void operator()(const f32x4 (&acc)[2][2][4][2], const Unit& u, int wr, int wc, int fr, int fq) const {
;     ...
;         for (int ai = 0; ai < 2; ++ai)
; #pragma unroll
;             for (int bj = 0; bj < 2; ++bj)
; #pragma unroll
;                 for (int m = 0; m < 4; ++m) {
;                     const u32x4 g = *((const u32x4*)Gs + ((size_t)(tile * 16 + (ai * 2 + bj) * 4 + m) * NTHREADS + tid));
;                     f32x4 y0 = acc[ai][bj][m][0], y1 = acc[ai][bj][m][1];
;                     y0[0] *= bf_lo(g.x); y0[1] *= bf_hi(g.x); y0[2] *= bf_lo(g.y); y0[3] *= bf_hi(g.y);
;                     y1[0] *= bf_lo(g.z); y1[1] *= bf_hi(g.z); y1[2] *= bf_lo(g.w); y1[3] *= bf_hi(g.w);
;                     u32x4* sp = (u32x4*)Sb + ((size_t)(tile * 16 + (ai * 2 + bj) * 4 + m) * NTHREADS + tid);
;                     if (br != 0) { const u32x4 t = *sp;
;                         y0[0] += bf_lo(t.x); y0[1] += bf_hi(t.x); y0[2] += bf_lo(t.y); y0[3] += bf_hi(t.y); y1[0] += bf_lo(t.z); y1[1] += bf_hi(t.z); y1[2] += bf_lo(t.w); y1[3] += bf_hi(t.w); }
;                     u32x4 w; w.x = cvt_pk_bf16(y0[0], y0[1]); w.y = cvt_pk_bf16(y0[2], y0[3]); w.z = cvt_pk_bf16(y1[0], y1[1]); w.w = cvt_pk_bf16(y1[2], y1[3]);
;                     if (br != 2) *sp = w;
	v_lshlrev_b32_e32 v224, 16, v156
	v_and_b32_e32 v225, 0xffff0000, v156
	v_mul_f32_e32 v132, v70, v224
	v_mul_f32_e32 v133, v71, v225
	v_lshlrev_b32_e32 v224, 16, v157
	v_and_b32_e32 v225, 0xffff0000, v157
	v_mul_f32_e32 v164, v72, v224
	v_mul_f32_e32 v165, v73, v225
	v_lshlrev_b32_e32 v224, 16, v158
	v_and_b32_e32 v225, 0xffff0000, v158
	v_mul_f32_e32 v168, v66, v224
	v_mul_f32_e32 v169, v67, v225
	v_lshlrev_b32_e32 v224, 16, v159
	v_and_b32_e32 v225, 0xffff0000, v159
	v_mul_f32_e32 v222, v68, v224
	v_mul_f32_e32 v223, v69, v225
	v_cvt_pk_bf16_f32 v218, v132, v133
	v_cvt_pk_bf16_f32 v219, v164, v165
	v_cvt_pk_bf16_f32 v220, v168, v169
	v_cvt_pk_bf16_f32 v221, v222, v223
	global_store_dwordx4 v166, v[218:221], s[44:45]
	s_add_u32 s44, s44, 0x2000
	s_addc_u32 s45, s45, 0
	s_waitcnt vmcnt(7)
	v_lshlrev_b32_e32 v224, 16, v160
	v_and_b32_e32 v225, 0xffff0000, v160
	v_mul_f32_e32 v132, v30, v224
	v_mul_f32_e32 v133, v31, v225
	v_lshlrev_b32_e32 v224, 16, v161
	v_and_b32_e32 v225, 0xffff0000, v161
	v_mul_f32_e32 v164, v32, v224
	v_mul_f32_e32 v165, v33, v225
	v_lshlrev_b32_e32 v224, 16, v162
	v_and_b32_e32 v225, 0xffff0000, v162
	v_mul_f32_e32 v168, v26, v224
	v_mul_f32_e32 v169, v27, v225
	v_lshlrev_b32_e32 v224, 16, v163
	v_and_b32_e32 v225, 0xffff0000, v163
	v_mul_f32_e32 v222, v28, v224
	v_mul_f32_e32 v223, v29, v225
	v_cvt_pk_bf16_f32 v214, v132, v133
	v_cvt_pk_bf16_f32 v215, v164, v165
	v_cvt_pk_bf16_f32 v216, v168, v169
	v_cvt_pk_bf16_f32 v217, v222, v223
	global_store_dwordx4 v166, v[214:217], s[44:45]
	s_add_u32 s44, s44, 0x2000
	s_addc_u32 s45, s45, 0
	s_waitcnt vmcnt(6)
	v_lshlrev_b32_e32 v224, 16, v174
	v_and_b32_e32 v225, 0xffff0000, v174
	v_mul_f32_e32 v132, v22, v224
	v_mul_f32_e32 v133, v23, v225
	v_lshlrev_b32_e32 v224, 16, v175
	v_and_b32_e32 v225, 0xffff0000, v175
	v_mul_f32_e32 v164, v24, v224
	v_mul_f32_e32 v165, v25, v225
	v_lshlrev_b32_e32 v224, 16, v176
	v_and_b32_e32 v225, 0xffff0000, v176
	v_mul_f32_e32 v168, v18, v224
	v_mul_f32_e32 v169, v19, v225
	v_lshlrev_b32_e32 v224, 16, v177
	v_and_b32_e32 v225, 0xffff0000, v177
	v_mul_f32_e32 v222, v20, v224
	v_mul_f32_e32 v223, v21, v225
	v_cvt_pk_bf16_f32 v218, v132, v133
	v_cvt_pk_bf16_f32 v219, v164, v165
	v_cvt_pk_bf16_f32 v220, v168, v169
	v_cvt_pk_bf16_f32 v221, v222, v223
	global_store_dwordx4 v166, v[218:221], s[44:45]
	s_add_u32 s44, s44, 0x2000
	s_addc_u32 s45, s45, 0
	s_waitcnt vmcnt(5)
	v_lshlrev_b32_e32 v224, 16, v178
	v_and_b32_e32 v225, 0xffff0000, v178
	v_mul_f32_e32 v132, v14, v224
	v_mul_f32_e32 v133, v15, v225
	v_lshlrev_b32_e32 v224, 16, v179
	v_and_b32_e32 v225, 0xffff0000, v179
	v_mul_f32_e32 v164, v16, v224
	v_mul_f32_e32 v165, v17, v225
	v_lshlrev_b32_e32 v224, 16, v180
	v_and_b32_e32 v225, 0xffff0000, v180
	v_mul_f32_e32 v168, v10, v224
	v_mul_f32_e32 v169, v11, v225
	v_lshlrev_b32_e32 v224, 16, v181
	v_and_b32_e32 v225, 0xffff0000, v181
	v_mul_f32_e32 v222, v12, v224
	v_mul_f32_e32 v223, v13, v225
	v_cvt_pk_bf16_f32 v214, v132, v133
	v_cvt_pk_bf16_f32 v215, v164, v165
	v_cvt_pk_bf16_f32 v216, v168, v169
	v_cvt_pk_bf16_f32 v217, v222, v223
	global_store_dwordx4 v166, v[214:217], s[44:45]
	s_add_u32 s44, s44, 0x2000
	s_addc_u32 s45, s45, 0
	s_waitcnt vmcnt(4)
	v_lshlrev_b32_e32 v224, 16, v152
	v_and_b32_e32 v225, 0xffff0000, v152
	v_mul_f32_e32 v132, v6, v224
	v_mul_f32_e32 v133, v7, v225
	v_lshlrev_b32_e32 v224, 16, v153
	v_and_b32_e32 v225, 0xffff0000, v153
	v_mul_f32_e32 v164, v8, v224
	v_mul_f32_e32 v165, v9, v225
	v_lshlrev_b32_e32 v224, 16, v154
	v_and_b32_e32 v225, 0xffff0000, v154
	v_mul_f32_e32 v168, v2, v224
	v_mul_f32_e32 v169, v3, v225
	v_lshlrev_b32_e32 v224, 16, v155
	v_and_b32_e32 v225, 0xffff0000, v155
	v_mul_f32_e32 v222, v4, v224
	v_mul_f32_e32 v223, v5, v225
	v_cvt_pk_bf16_f32 v218, v132, v133
	v_cvt_pk_bf16_f32 v219, v164, v165
	v_cvt_pk_bf16_f32 v220, v168, v169
	v_cvt_pk_bf16_f32 v221, v222, v223
	global_store_dwordx4 v166, v[218:221], s[44:45]
	s_add_u32 s44, s44, 0x2000
	s_addc_u32 s45, s45, 0
	s_branch .LBB0_304

; template <bool STORE> __device__ __forceinline__ void attn_unit(LAS unsigned char* lds, bf16_t* Q, const bf16_t* Kg, const bf16_t* VT, const float* subg, float lam, float outscale, int unit, const int wave_s) {
;     ...
;     f32x16 o[4]; o[0] = f32x16{}; o[1] = f32x16{}; o[2] = f32x16{}; o[3] = f32x16{};
;     float mref = sself + 6.0f, lsum = 0.f;
;     const int koff = q * 256 + (((map * 8 + hi) ^ (q & 15)) << 4), voff = AT_VOFF + q * 128 + ((hi ^ ((q >> 1) & 7)) << 4);
;     const float qposf = (float)(qrow0 + q - 4 * hi);
;     f32x16 x0, x1, n0, n1;
.LBB0_581:
	v_lshlrev_b32_e32 v0, 7, v3
	v_lshrrev_b32_e32 v3, 1, v219
	v_bitop3_b32 v2, v2, v3, 7 bitop3:0x78
	s_lshr_b32 s16, s12, 6
	v_lshl_or_b32 v215, v2, 4, v0
	s_waitcnt lgkmcnt(0)
	s_barrier
	s_cmpk_lt_u32 s12, 0xc0
	s_mov_b64 s[12:13], 0xf80
	v_or_b32_e32 v214, 0x10000, v215
	v_lshl_add_u64 v[174:175], v[182:183], 0, s[12:13]
	v_add_f32_e32 v167, v166, v166
	v_add_u32_e32 v204, 0, v214
	v_lshl_add_u64 v[176:177], v[172:173], 1, v[174:175]
	v_fma_f32 v185, 2.0, v166, v167
	v_xor_b32_e32 v203, 0x10020, v215
	v_xor_b32_e32 v202, 0x10040, v215
	v_xor_b32_e32 v179, 0x10060, v215
	s_cbranch_scc1 .LBB0_605
	v_xor_b32_e32 v0, 0x10020, v215
	v_readlane_b32 s12, v253, 23
	v_mov_b32_e32 v184, v166
	v_mov_b32_e32 v2, v167
	v_mov_b32_e32 v3, v185
	v_add_u32_e32 v220, 0, v0
	v_xor_b32_e32 v0, 0x10040, v215
	s_add_i32 s12, s34, s12
	v_add_f32_e32 v186, v184, v2
	v_add_f32_e32 v187, v185, v3
	v_add_u32_e32 v221, 0, v0
	v_xor_b32_e32 v0, 0x10060, v215
	v_add_u32_e32 v2, s12, v216
	v_add_u32_e32 v222, 0, v0
	v_ashrrev_i32_e32 v3, 31, v2
	v_add_u32_e32 v0, s19, v218
	v_lshlrev_b64 v[188:189], 11, v[2:3]
	v_lshlrev_b64 v[2:3], 15, v[0:1]
	v_lshl_or_b32 v2, v217, 4, v2
	v_mov_b32_e32 v14, v1
	v_mov_b32_e32 v15, v1
	v_add_f32_e32 v168, v187, v187
	s_and_b32 s12, s18, 0x700
	v_lshl_add_u64 v[190:191], s[34:35], 1, v[2:3]
	v_mov_b32_e32 v0, v1
	v_mov_b32_e32 v2, v1
	v_mov_b32_e32 v3, v1
	v_mov_b32_e32 v4, v1
	v_mov_b32_e32 v5, v1
	v_mov_b32_e32 v6, v1
	v_mov_b32_e32 v7, v1
	v_mov_b32_e32 v8, v1
	v_mov_b32_e32 v9, v1
	v_mov_b32_e32 v10, v1
	v_mov_b32_e32 v11, v1
	v_mov_b32_e32 v12, v1
	v_mov_b32_e32 v13, v1
	v_mov_b64_e32 v[78:79], v[14:15]
	v_mov_b64_e32 v[62:63], v[14:15]
	v_mov_b64_e32 v[46:47], v[14:15]
	v_mov_b64_e32 v[30:31], v[14:15]
	v_fmac_f32_e32 v168, 2.0, v187
	v_or3_b32 v188, v188, s12, v178
	s_mov_b32 s20, 0
	v_mov_b32_e32 v184, 0
	s_mov_b32 s21, 0x14000
	s_movk_i32 s28, 0x80
	v_mov_b64_e32 v[76:77], v[12:13]
	v_mov_b64_e32 v[74:75], v[10:11]
	v_mov_b64_e32 v[72:73], v[8:9]
	v_mov_b64_e32 v[70:71], v[6:7]
	v_mov_b64_e32 v[68:69], v[4:5]
	v_mov_b64_e32 v[66:67], v[2:3]
	v_mov_b64_e32 v[64:65], v[0:1]
	v_mov_b64_e32 v[60:61], v[12:13]
	v_mov_b64_e32 v[58:59], v[10:11]
	v_mov_b64_e32 v[56:57], v[8:9]
	v_mov_b64_e32 v[54:55], v[6:7]
	v_mov_b64_e32 v[52:53], v[4:5]
	v_mov_b64_e32 v[50:51], v[2:3]
	v_mov_b64_e32 v[48:49], v[0:1]
	v_mov_b64_e32 v[44:45], v[12:13]
	v_mov_b64_e32 v[42:43], v[10:11]
	v_mov_b64_e32 v[40:41], v[8:9]
	v_mov_b64_e32 v[38:39], v[6:7]
	v_mov_b64_e32 v[36:37], v[4:5]
	v_mov_b64_e32 v[34:35], v[2:3]
	v_mov_b64_e32 v[32:33], v[0:1]
	v_mov_b64_e32 v[28:29], v[12:13]
	v_mov_b64_e32 v[26:27], v[10:11]
	v_mov_b64_e32 v[24:25], v[8:9]
	v_mov_b64_e32 v[22:23], v[6:7]
	v_mov_b64_e32 v[20:21], v[4:5]
	v_mov_b64_e32 v[18:19], v[2:3]
	v_mov_b64_e32 v[16:17], v[0:1]

.LBB0_589:
	s_add_i32 s30, s21, 0xffff0000
	s_and_b32 s30, s30, 0xc000
	s_add_i32 s42, s30, 0
	v_add_u32_e32 v0, s42, v210
	s_sub_i32 s43, s28, 64
	ds_read_b128 v[6:9], v0
	ds_read_b128 v[10:13], v0 offset:8192
	v_cvt_f32_u32_e32 v0, s43
	v_add_u32_e32 v14, s42, v211
	ds_read_b128 v[224:227], v14
	ds_read_b128 v[228:231], v14 offset:8192
	s_add_i32 s36, s21, 0xfffec000
	v_sub_f32_e32 v0, v0, v205
	v_fma_f32 v112, v166, v0, -v169
	v_add_f32_e32 v128, v168, v112
	v_add_f32_e32 v118, v186, v128
	v_add_f32_e32 v119, v187, v128
	v_add_f32_e32 v116, v186, v112
	v_add_f32_e32 v117, v187, v112
	v_add_f32_e32 v126, v186, v119
	v_add_f32_e32 v127, v187, v119
	v_add_f32_e32 v114, v166, v128
	v_add_f32_e32 v115, v167, v128
	v_add_f32_e32 v140, v186, v127
	v_add_f32_e32 v141, v187, v127
	v_add_f32_e32 v122, v166, v119
	v_add_f32_e32 v123, v167, v119
	v_add_f32_e32 v124, v186, v117
	v_add_f32_e32 v125, v187, v117
	v_add_f32_e32 v138, v166, v127
	v_add_f32_e32 v139, v167, v127
	v_add_f32_e32 v142, v166, v141
	v_add_f32_e32 v143, v167, v141
	v_add_f32_e32 v240, v186, v141
	v_add_f32_e32 v120, v166, v117
	v_add_f32_e32 v121, v167, v117
	v_add_f32_e32 v234, v186, v125
	v_add_f32_e32 v235, v187, v125
	v_mov_b32_e32 v129, v114
	v_mov_b32_e32 v130, v115
	v_mov_b32_e32 v131, v118
	v_mov_b32_e32 v132, v119
	v_mov_b32_e32 v133, v122
	v_mov_b32_e32 v134, v123
	v_mov_b32_e32 v135, v126
	v_mov_b32_e32 v136, v127
	v_mov_b32_e32 v137, v138
	v_mov_b32_e32 v138, v139
	v_mov_b32_e32 v139, v140
	v_mov_b32_e32 v140, v141
	v_mov_b32_e32 v141, v142
	v_mov_b32_e32 v142, v143
	v_mov_b32_e32 v143, v240
	v_add_f32_e32 v14, v166, v112
	v_add_f32_e32 v15, v167, v112
	v_add_f32_e32 v232, v166, v125
	v_add_f32_e32 v233, v167, v125
	v_add_f32_e32 v236, v166, v235
	v_add_f32_e32 v237, v167, v235
	v_add_f32_e32 v238, v186, v235
	v_mov_b32_e32 v113, v14
	v_mov_b32_e32 v114, v15
	v_mov_b32_e32 v115, v116
	v_mov_b32_e32 v116, v117
	v_mov_b32_e32 v117, v120
	v_mov_b32_e32 v118, v121
	v_mov_b32_e32 v119, v124
	v_mov_b32_e32 v120, v125
	v_mov_b32_e32 v121, v232
	v_mov_b32_e32 v122, v233
	v_mov_b32_e32 v123, v234
	v_mov_b32_e32 v124, v235
	v_mov_b32_e32 v125, v236
	v_mov_b32_e32 v126, v237
	v_mov_b32_e32 v127, v238
	s_waitcnt lgkmcnt(2)
	v_mfma_f32_32x32x16_bf16 v[128:143], v[10:13], v[144:147], v[128:143]
	v_add_u32_e32 v0, s42, v212
	s_and_b32 s36, s36, 0x8000
	v_exp_f32_e32 v96, v96
	v_exp_f32_e32 v14, v97
	v_exp_f32_e32 v80, v80
	v_exp_f32_e32 v98, v98
	v_exp_f32_e32 v82, v82
	v_mfma_f32_32x32x16_bf16 v[112:127], v[6:9], v[144:147], v[112:127]
	ds_read_b128 v[6:9], v0
	ds_read_b128 v[10:13], v0 offset:8192
	v_add_u32_e32 v0, s42, v213
	v_exp_f32_e32 v248, v99
	v_exp_f32_e32 v250, v83
	v_exp_f32_e32 v83, v84
	v_exp_f32_e32 v84, v86
	v_exp_f32_e32 v196, v103
	s_waitcnt lgkmcnt(3)
	v_mfma_f32_32x32x16_bf16 v[112:127], v[224:227], v[148:151], v[112:127]
	ds_read_b128 v[224:227], v0
	ds_read_b128 v[232:235], v0 offset:8192
	v_add_u32_e32 v0, s36, v204
	ds_read_b128 v[236:239], v0
	ds_read_b128 v[240:243], v0 offset:4096
	v_exp_f32_e32 v86, v106
	v_exp_f32_e32 v198, v105
	v_exp_f32_e32 v106, v89
	v_exp_f32_e32 v164, v107
	s_waitcnt lgkmcnt(6)
	v_mfma_f32_32x32x16_bf16 v[128:143], v[228:231], v[148:151], v[128:143]
	ds_read_b128 v[228:231], v0 offset:8192
	ds_read_b128 v[244:247], v0 offset:12288
	v_exp_f32_e32 v0, v81
	v_exp_f32_e32 v81, v104
	v_exp_f32_e32 v104, v87
	v_exp_f32_e32 v87, v90
	v_exp_f32_e32 v160, v91
	v_exp_f32_e32 v89, v92
	s_waitcnt lgkmcnt(7)
	v_mfma_f32_32x32x16_bf16 v[112:127], v[6:9], v[152:155], v[112:127]
	v_exp_f32_e32 v8, v100
	v_exp_f32_e32 v9, v102
	v_exp_f32_e32 v90, v110
	v_exp_f32_e32 v91, v94
	v_exp_f32_e32 v162, v109
	v_exp_f32_e32 v200, v111
	v_exp_f32_e32 v110, v95
	s_waitcnt lgkmcnt(6)
	v_mfma_f32_32x32x16_bf16 v[128:143], v[10:13], v[152:155], v[128:143]
	v_cvt_pk_bf16_f32 v6, v96, v14
	v_add_f32_e32 v15, v96, v80
	v_add_f32_e32 v249, v98, v82
	v_add_f32_e32 v197, v9, v84
	v_add_f32_e32 v165, v86, v87
	v_add_f32_e32 v201, v90, v91
	v_cvt_pk_bf16_f32 v7, v98, v248
	s_waitcnt lgkmcnt(5)
	v_mfma_f32_32x32x16_bf16 v[112:127], v[224:227], v[156:159], v[112:127]
	v_exp_f32_e32 v224, v101
	v_exp_f32_e32 v226, v85
	v_exp_f32_e32 v85, v88
	v_exp_f32_e32 v88, v108
	v_exp_f32_e32 v108, v93
	v_add_f32_e32 v225, v8, v83
	v_add_f32_e32 v199, v81, v85
	s_waitcnt lgkmcnt(4)
	v_mfma_f32_32x32x16_bf16 v[128:143], v[232:235], v[156:159], v[128:143]
	v_add_f32_e32 v163, v88, v89
	v_cvt_pk_bf16_f32 v8, v8, v224
	v_cvt_pk_bf16_f32 v9, v9, v196
	v_cvt_pk_bf16_f32 v10, v81, v198
	v_cvt_pk_bf16_f32 v11, v86, v164
	v_cvt_pk_bf16_f32 v12, v88, v162
	v_cvt_pk_bf16_f32 v13, v90, v200
	v_cvt_pk_bf16_f32 v80, v80, v0
	v_cvt_pk_bf16_f32 v81, v82, v250
	v_cvt_pk_bf16_f32 v82, v83, v226
	v_cvt_pk_bf16_f32 v83, v84, v104
	v_cvt_pk_bf16_f32 v84, v85, v106
	v_cvt_pk_bf16_f32 v85, v87, v160
	v_cvt_pk_bf16_f32 v86, v89, v108
	v_cvt_pk_bf16_f32 v87, v91, v110
	v_add_f32_e32 v14, v14, v0
	v_add_f32_e32 v15, v15, v1
	v_add_u32_e32 v100, s36, v220
	v_add_f32_e32 v15, v14, v15
	v_mov_b32_e32 v251, v15
	v_add_f32_e32 v14, v248, v250
	v_add_f32_e32 v15, v249, v251
	s_waitcnt lgkmcnt(3)
	v_mfma_f32_32x32x16_bf16 v[64:79], v[236:239], v[6:9], v[64:79]
	v_add_f32_e32 v15, v14, v15
	v_mov_b32_e32 v227, v15
	v_add_f32_e32 v14, v224, v226
	v_add_f32_e32 v15, v225, v227
	ds_read_b128 v[88:91], v100
	ds_read_b128 v[92:95], v100 offset:4096
	ds_read_b128 v[96:99], v100 offset:8192
	ds_read_b128 v[100:103], v100 offset:12288
	v_add_f32_e32 v15, v14, v15
	v_mov_b32_e32 v105, v15
	v_add_f32_e32 v14, v196, v104
	v_add_f32_e32 v15, v197, v105
	s_waitcnt lgkmcnt(6)
	v_mfma_f32_32x32x16_bf16 v[48:63], v[240:243], v[6:9], v[48:63]
	v_add_f32_e32 v15, v14, v15
	v_mov_b32_e32 v107, v15
	v_add_f32_e32 v14, v198, v106
	v_add_f32_e32 v15, v199, v107
	s_nop 0
	v_add_f32_e32 v15, v14, v15
	v_mov_b32_e32 v161, v15
	v_add_f32_e32 v14, v164, v160
	v_add_f32_e32 v15, v165, v161
	s_waitcnt lgkmcnt(5)
	v_mfma_f32_32x32x16_bf16 v[32:47], v[228:231], v[6:9], v[32:47]
	v_add_f32_e32 v15, v14, v15
	v_mov_b32_e32 v109, v15
	v_add_f32_e32 v14, v162, v108
	v_add_f32_e32 v15, v163, v109
	s_nop 0
	v_add_f32_e32 v15, v14, v15
	v_mov_b32_e32 v111, v15
	v_add_f32_e32 v14, v200, v110
	v_add_f32_e32 v15, v201, v111
	s_waitcnt lgkmcnt(4)
	v_mfma_f32_32x32x16_bf16 v[16:31], v[244:247], v[6:9], v[16:31]
	v_add_f32_e32 v0, v14, v15
	v_add_f32_e32 v6, v184, v0
	s_waitcnt lgkmcnt(3)
	v_mfma_f32_32x32x16_bf16 v[64:79], v[88:91], v[10:13], v[64:79]
	v_add_u32_e32 v0, s36, v221
	s_waitcnt lgkmcnt(2)
	v_mfma_f32_32x32x16_bf16 v[48:63], v[92:95], v[10:13], v[48:63]
	s_waitcnt lgkmcnt(1)
	v_mfma_f32_32x32x16_bf16 v[32:47], v[96:99], v[10:13], v[32:47]
	ds_read_b128 v[88:91], v0
	ds_read_b128 v[92:95], v0 offset:4096
	ds_read_b128 v[96:99], v0 offset:8192
	ds_read_b128 v[104:107], v0 offset:12288
	s_waitcnt lgkmcnt(4)
	v_mfma_f32_32x32x16_bf16 v[16:31], v[100:103], v[10:13], v[16:31]
	v_add_u32_e32 v0, s36, v222
	ds_read_b128 v[8:11], v0
	ds_read_b128 v[12:15], v0 offset:4096
	s_waitcnt lgkmcnt(5)
	v_mfma_f32_32x32x16_bf16 v[64:79], v[88:91], v[80:83], v[64:79]
	ds_read_b128 v[88:91], v0 offset:8192
	ds_read_b128 v[100:103], v0 offset:12288
	v_max_f32_e32 v0, v113, v113
	v_max_f32_e32 v7, v129, v129
	v_max_f32_e32 v0, v0, v7
	v_max3_f32 v7, v112, v128, v114
	v_max3_f32 v0, v0, v115, v131
	v_max3_f32 v7, v7, v130, v116
	v_max3_f32 v0, v0, v117, v133
	s_waitcnt lgkmcnt(6)
	v_mfma_f32_32x32x16_bf16 v[48:63], v[92:95], v[80:83], v[48:63]
	v_max3_f32 v7, v7, v132, v118
	v_max3_f32 v0, v0, v119, v135
	v_max3_f32 v7, v7, v134, v120
	v_max3_f32 v0, v0, v121, v137
	v_max3_f32 v7, v7, v136, v122
	v_max3_f32 v0, v0, v123, v139
	v_max3_f32 v7, v7, v138, v124
	s_waitcnt lgkmcnt(5)
	v_mfma_f32_32x32x16_bf16 v[32:47], v[96:99], v[80:83], v[32:47]
	v_max3_f32 v0, v0, v125, v141
	v_max3_f32 v7, v7, v140, v126
	v_max3_f32 v0, v0, v127, v143
	v_max3_f32 v0, v7, v142, v0
	v_mov_b32_e32 v7, v0
	s_nop 1
	v_permlane32_swap_b32_e32 v0, v7
	s_waitcnt lgkmcnt(4)
	v_mfma_f32_32x32x16_bf16 v[16:31], v[104:107], v[80:83], v[16:31]
	s_waitcnt lgkmcnt(3)
	v_mfma_f32_32x32x16_bf16 v[64:79], v[8:11], v[84:87], v[64:79]
	v_max_f32_e32 v7, v7, v7
	v_max_f32_e32 v0, v0, v0
	v_max_f32_e32 v0, v0, v7
	v_cmp_lt_f32_e32 vcc, s93, v0
	s_waitcnt lgkmcnt(2)
	v_mfma_f32_32x32x16_bf16 v[48:63], v[12:15], v[84:87], v[48:63]
	s_waitcnt lgkmcnt(1)
	v_mfma_f32_32x32x16_bf16 v[32:47], v[88:91], v[84:87], v[32:47]
	s_waitcnt lgkmcnt(0)
	v_mfma_f32_32x32x16_bf16 v[16:31], v[100:103], v[84:87], v[16:31]
	s_cbranch_vccz .LBB0_591
	v_max_f32_e32 v0, v0, v0
	v_max_f32_e32 v7, 0, v0
	v_exp_f32_e64 v0, -v7
	v_add_f32_e32 v169, v169, v7
	v_sub_f32_e32 v127, v127, v7
	v_sub_f32_e32 v126, v126, v7
	v_pk_mul_f32 v[78:79], v[78:79], v[0:1] op_sel_hi:[1,0]
	v_pk_mul_f32 v[76:77], v[76:77], v[0:1] op_sel_hi:[1,0]
	v_pk_mul_f32 v[74:75], v[74:75], v[0:1] op_sel_hi:[1,0]
	v_pk_mul_f32 v[72:73], v[72:73], v[0:1] op_sel_hi:[1,0]
	v_pk_mul_f32 v[70:71], v[70:71], v[0:1] op_sel_hi:[1,0]
	v_pk_mul_f32 v[68:69], v[68:69], v[0:1] op_sel_hi:[1,0]
	v_pk_mul_f32 v[66:67], v[66:67], v[0:1] op_sel_hi:[1,0]
	v_pk_mul_f32 v[64:65], v[64:65], v[0:1] op_sel_hi:[1,0]
	v_pk_mul_f32 v[62:63], v[62:63], v[0:1] op_sel_hi:[1,0]
	v_pk_mul_f32 v[60:61], v[60:61], v[0:1] op_sel_hi:[1,0]
	v_pk_mul_f32 v[58:59], v[58:59], v[0:1] op_sel_hi:[1,0]
	v_pk_mul_f32 v[56:57], v[56:57], v[0:1] op_sel_hi:[1,0]
	v_pk_mul_f32 v[54:55], v[54:55], v[0:1] op_sel_hi:[1,0]
	v_pk_mul_f32 v[52:53], v[52:53], v[0:1] op_sel_hi:[1,0]
	v_pk_mul_f32 v[50:51], v[50:51], v[0:1] op_sel_hi:[1,0]
	v_pk_mul_f32 v[48:49], v[48:49], v[0:1] op_sel_hi:[1,0]
	v_pk_mul_f32 v[46:47], v[0:1], v[46:47] op_sel_hi:[0,1]
	v_pk_mul_f32 v[44:45], v[0:1], v[44:45] op_sel_hi:[0,1]
	v_pk_mul_f32 v[42:43], v[0:1], v[42:43] op_sel_hi:[0,1]
	v_pk_mul_f32 v[40:41], v[0:1], v[40:41] op_sel_hi:[0,1]
	v_pk_mul_f32 v[38:39], v[0:1], v[38:39] op_sel_hi:[0,1]
	v_pk_mul_f32 v[36:37], v[0:1], v[36:37] op_sel_hi:[0,1]
	v_pk_mul_f32 v[34:35], v[0:1], v[34:35] op_sel_hi:[0,1]
	v_pk_mul_f32 v[32:33], v[0:1], v[32:33] op_sel_hi:[0,1]
	v_pk_mul_f32 v[30:31], v[0:1], v[30:31] op_sel_hi:[0,1]
	v_pk_mul_f32 v[28:29], v[0:1], v[28:29] op_sel_hi:[0,1]
	v_pk_mul_f32 v[26:27], v[0:1], v[26:27] op_sel_hi:[0,1]
	v_pk_mul_f32 v[24:25], v[0:1], v[24:25] op_sel_hi:[0,1]
	v_pk_mul_f32 v[22:23], v[0:1], v[22:23] op_sel_hi:[0,1]
	v_pk_mul_f32 v[20:21], v[0:1], v[20:21] op_sel_hi:[0,1]
	v_pk_mul_f32 v[18:19], v[0:1], v[18:19] op_sel_hi:[0,1]
	v_pk_mul_f32 v[16:17], v[0:1], v[16:17] op_sel_hi:[0,1]
	v_sub_f32_e32 v125, v125, v7
	v_sub_f32_e32 v124, v124, v7
	v_sub_f32_e32 v123, v123, v7
	v_sub_f32_e32 v122, v122, v7
	v_sub_f32_e32 v121, v121, v7
	v_sub_f32_e32 v120, v120, v7
	v_sub_f32_e32 v119, v119, v7
	v_sub_f32_e32 v118, v118, v7
	v_sub_f32_e32 v117, v117, v7
	v_sub_f32_e32 v116, v116, v7
	v_sub_f32_e32 v115, v115, v7
	v_sub_f32_e32 v114, v114, v7
	v_sub_f32_e32 v113, v113, v7
	v_sub_f32_e32 v112, v112, v7
	v_sub_f32_e32 v143, v143, v7
	v_sub_f32_e32 v142, v142, v7
	v_sub_f32_e32 v141, v141, v7
	v_sub_f32_e32 v140, v140, v7
	v_sub_f32_e32 v139, v139, v7
	v_sub_f32_e32 v138, v138, v7
	v_sub_f32_e32 v137, v137, v7
	v_sub_f32_e32 v136, v136, v7
	v_sub_f32_e32 v135, v135, v7
	v_sub_f32_e32 v134, v134, v7
	v_sub_f32_e32 v133, v133, v7
	v_sub_f32_e32 v132, v132, v7
	v_sub_f32_e32 v131, v131, v7
	v_sub_f32_e32 v130, v130, v7
	v_sub_f32_e32 v129, v129, v7
	v_sub_f32_e32 v128, v128, v7
	v_mul_f32_e32 v6, v6, v0

.LBB0_595:
	s_add_i32 s36, s21, 0xffff4000
	s_and_b32 s36, s36, 0x8000
	s_add_i32 s36, s36, 0
	v_add_u32_e32 v0, s36, v210
	ds_read_b128 v[2:5], v0
	ds_read_b128 v[8:11], v0 offset:8192
	v_cvt_f32_u32_e32 v0, s28
	v_add_u32_e32 v7, s36, v211
	ds_read_b128 v[12:15], v7
	ds_read_b128 v[224:227], v7 offset:8192
	v_sub_f32_e32 v0, v0, v205
	v_fma_f32 v96, v166, v0, -v169
	v_add_f32_e32 v80, v168, v96
	v_add_f32_e32 v86, v186, v96
	v_add_f32_e32 v87, v187, v96
	v_add_f32_e32 v88, v186, v80
	v_add_f32_e32 v89, v187, v80
	v_add_f32_e32 v94, v186, v87
	v_add_f32_e32 v95, v187, v87
	v_add_f32_e32 v160, v186, v89
	v_add_f32_e32 v161, v187, v89
	v_add_f32_e32 v108, v186, v95
	v_add_f32_e32 v109, v187, v95
	v_add_f32_e32 v82, v166, v96
	v_add_f32_e32 v83, v167, v96
	v_add_f32_e32 v90, v166, v87
	v_add_f32_e32 v91, v167, v87
	v_add_f32_e32 v106, v166, v95
	v_add_f32_e32 v107, v167, v95
	v_add_f32_e32 v164, v186, v161
	v_add_f32_e32 v165, v187, v161
	v_add_f32_e32 v110, v166, v109
	v_add_f32_e32 v111, v167, v109
	v_add_f32_e32 v196, v186, v109
	v_add_f32_e32 v84, v166, v80
	v_add_f32_e32 v85, v167, v80
	v_add_f32_e32 v92, v166, v89
	v_add_f32_e32 v93, v167, v89
	v_mov_b32_e32 v97, v82
	v_mov_b32_e32 v98, v83
	v_mov_b32_e32 v99, v86
	v_mov_b32_e32 v100, v87
	v_mov_b32_e32 v101, v90
	v_mov_b32_e32 v102, v91
	v_mov_b32_e32 v103, v94
	v_mov_b32_e32 v104, v95
	v_mov_b32_e32 v105, v106
	v_mov_b32_e32 v106, v107
	v_mov_b32_e32 v107, v108
	v_mov_b32_e32 v108, v109
	v_mov_b32_e32 v109, v110
	v_mov_b32_e32 v110, v111
	v_mov_b32_e32 v111, v196
	v_add_f32_e32 v94, v166, v165
	v_add_f32_e32 v95, v167, v165
	v_add_f32_e32 v162, v166, v161
	v_add_f32_e32 v163, v167, v161
	v_add_f32_e32 v196, v186, v165
	v_mov_b32_e32 v81, v84
	v_mov_b32_e32 v82, v85
	v_mov_b32_e32 v83, v88
	v_mov_b32_e32 v84, v89
	v_mov_b32_e32 v85, v92
	v_mov_b32_e32 v86, v93
	v_mov_b32_e32 v87, v160
	v_mov_b32_e32 v88, v161
	v_mov_b32_e32 v89, v162
	v_mov_b32_e32 v90, v163
	v_mov_b32_e32 v91, v164
	v_mov_b32_e32 v92, v165
	v_mov_b32_e32 v93, v94
	v_mov_b32_e32 v94, v95
	v_mov_b32_e32 v95, v196
	s_waitcnt lgkmcnt(3)
	v_mfma_f32_32x32x16_bf16 v[96:111], v[2:5], v[144:147], v[96:111]
	v_add_u32_e32 v0, s36, v212
	v_exp_f32_e32 v7, v112
	v_exp_f32_e32 v112, v128
	v_exp_f32_e32 v160, v129
	v_exp_f32_e32 v116, v116
	v_exp_f32_e32 v128, v132
	v_exp_f32_e32 v132, v115
	s_waitcnt lgkmcnt(2)
	v_mfma_f32_32x32x16_bf16 v[80:95], v[8:11], v[144:147], v[80:95]
	ds_read_b128 v[2:5], v0
	ds_read_b128 v[8:11], v0 offset:8192
	v_add_u32_e32 v0, s36, v213
	v_exp_f32_e32 v162, v131
	v_exp_f32_e32 v115, v134
	v_exp_f32_e32 v134, v117
	v_exp_f32_e32 v164, v133
	v_exp_f32_e32 v198, v119
	s_waitcnt lgkmcnt(3)
	v_mfma_f32_32x32x16_bf16 v[96:111], v[12:15], v[148:151], v[96:111]
	ds_read_b128 v[12:15], v0
	ds_read_b128 v[228:231], v0 offset:8192
	v_add_u32_e32 v0, s30, v204
	ds_read_b128 v[232:235], v0
	ds_read_b128 v[236:239], v0 offset:4096
	v_exp_f32_e32 v117, v136
	v_exp_f32_e32 v196, v135
	v_exp_f32_e32 v136, v121
	v_exp_f32_e32 v200, v137
	s_waitcnt lgkmcnt(6)
	v_mfma_f32_32x32x16_bf16 v[80:95], v[224:227], v[148:151], v[80:95]
	ds_read_b128 v[224:227], v0 offset:8192
	ds_read_b128 v[240:243], v0 offset:12288
	v_exp_f32_e32 v0, v113
	v_exp_f32_e32 v113, v114
	v_exp_f32_e32 v114, v130
	v_exp_f32_e32 v244, v139
	v_exp_f32_e32 v119, v140
	v_exp_f32_e32 v140, v125
	s_waitcnt lgkmcnt(7)
	v_mfma_f32_32x32x16_bf16 v[96:111], v[2:5], v[152:155], v[96:111]
	v_exp_f32_e32 v5, v118
	v_exp_f32_e32 v118, v138
	v_exp_f32_e32 v138, v123
	v_exp_f32_e32 v246, v141
	v_exp_f32_e32 v248, v143
	v_add_f32_e32 v161, v112, v7
	v_add_f32_e32 v163, v114, v113
	s_waitcnt lgkmcnt(6)
	v_mfma_f32_32x32x16_bf16 v[80:95], v[8:11], v[152:155], v[80:95]
	v_add_f32_e32 v165, v128, v116
	v_add_f32_e32 v197, v115, v5
	v_cvt_pk_bf16_f32 v2, v7, v0
	v_cvt_pk_bf16_f32 v3, v113, v132
	v_cvt_pk_bf16_f32 v4, v116, v134
	v_cvt_pk_bf16_f32 v5, v5, v198
	v_cvt_pk_bf16_f32 v113, v118, v244
	s_waitcnt lgkmcnt(5)
	v_mfma_f32_32x32x16_bf16 v[96:111], v[12:15], v[156:159], v[96:111]
	v_exp_f32_e32 v12, v120
	v_exp_f32_e32 v13, v122
	v_exp_f32_e32 v14, v124
	v_exp_f32_e32 v15, v126
	v_exp_f32_e32 v120, v142
	v_exp_f32_e32 v142, v127
	v_add_f32_e32 v201, v117, v12
	s_waitcnt lgkmcnt(4)
	v_mfma_f32_32x32x16_bf16 v[80:95], v[228:231], v[156:159], v[80:95]
	v_add_f32_e32 v245, v118, v13
	v_add_f32_e32 v247, v119, v14
	v_add_f32_e32 v249, v120, v15
	v_cvt_pk_bf16_f32 v8, v12, v136
	v_cvt_pk_bf16_f32 v9, v13, v138
	v_cvt_pk_bf16_f32 v10, v14, v140
	v_cvt_pk_bf16_f32 v11, v15, v142
	v_cvt_pk_bf16_f32 v12, v112, v160
	v_cvt_pk_bf16_f32 v13, v114, v162
	v_cvt_pk_bf16_f32 v14, v128, v164
	v_cvt_pk_bf16_f32 v15, v115, v196
	v_cvt_pk_bf16_f32 v112, v117, v200
	v_cvt_pk_bf16_f32 v114, v119, v246
	v_cvt_pk_bf16_f32 v115, v120, v248
	v_add_f32_e32 v160, v160, v0
	v_add_f32_e32 v161, v161, v1
	v_add_u32_e32 v7, s30, v220
	v_add_f32_e32 v161, v160, v161
	v_add_f32_e32 v160, v160, v160
	v_mov_b32_e32 v133, v161
	v_add_f32_e32 v132, v162, v132
	v_add_f32_e32 v133, v163, v133
	s_waitcnt lgkmcnt(3)
	v_mfma_f32_32x32x16_bf16 v[64:79], v[232:235], v[2:5], v[64:79]
	v_add_f32_e32 v133, v132, v133
	v_mov_b32_e32 v135, v133
	v_add_f32_e32 v132, v164, v134
	v_add_f32_e32 v133, v165, v135
	ds_read_b128 v[116:119], v7
	ds_read_b128 v[120:123], v7 offset:4096
	ds_read_b128 v[124:127], v7 offset:8192
	ds_read_b128 v[128:131], v7 offset:12288
	v_add_f32_e32 v133, v132, v133
	v_mov_b32_e32 v199, v133
	v_add_f32_e32 v132, v196, v198
	v_add_f32_e32 v133, v197, v199
	s_waitcnt lgkmcnt(6)
	v_mfma_f32_32x32x16_bf16 v[48:63], v[236:239], v[2:5], v[48:63]
	v_add_f32_e32 v133, v132, v133
	v_mov_b32_e32 v137, v133
	v_add_f32_e32 v132, v200, v136
	v_add_f32_e32 v133, v201, v137
	s_nop 0
	v_add_f32_e32 v133, v132, v133
	v_mov_b32_e32 v139, v133
	v_add_f32_e32 v132, v244, v138
	v_add_f32_e32 v133, v245, v139
	s_waitcnt lgkmcnt(5)
	v_mfma_f32_32x32x16_bf16 v[32:47], v[224:227], v[2:5], v[32:47]
	v_add_f32_e32 v133, v132, v133
	v_mov_b32_e32 v141, v133
	v_add_f32_e32 v132, v246, v140
	v_add_f32_e32 v133, v247, v141
	s_nop 0
	v_add_f32_e32 v133, v132, v133
	v_mov_b32_e32 v143, v133
	v_add_f32_e32 v132, v248, v142
	v_add_f32_e32 v133, v249, v143
	s_waitcnt lgkmcnt(4)
	v_mfma_f32_32x32x16_bf16 v[16:31], v[240:243], v[2:5], v[16:31]
	v_add_f32_e32 v0, v132, v133
	v_add_f32_e32 v184, v6, v0
	s_waitcnt lgkmcnt(3)
	v_mfma_f32_32x32x16_bf16 v[64:79], v[116:119], v[8:11], v[64:79]
	v_add_u32_e32 v0, s30, v221
	s_waitcnt lgkmcnt(2)
	v_mfma_f32_32x32x16_bf16 v[48:63], v[120:123], v[8:11], v[48:63]
	s_waitcnt lgkmcnt(1)
	v_mfma_f32_32x32x16_bf16 v[32:47], v[124:127], v[8:11], v[32:47]
	ds_read_b128 v[2:5], v0
	ds_read_b128 v[116:119], v0 offset:4096
	ds_read_b128 v[120:123], v0 offset:8192
	ds_read_b128 v[124:127], v0 offset:12288
	s_waitcnt lgkmcnt(4)
	v_mfma_f32_32x32x16_bf16 v[16:31], v[128:131], v[8:11], v[16:31]
	v_add_u32_e32 v0, s30, v222
	ds_read_b128 v[6:9], v0
	ds_read_b128 v[128:131], v0 offset:4096
	s_waitcnt lgkmcnt(5)
	v_mfma_f32_32x32x16_bf16 v[64:79], v[2:5], v[12:15], v[64:79]
	ds_read_b128 v[2:5], v0 offset:8192
	ds_read_b128 v[132:135], v0 offset:12288
	v_max_f32_e32 v0, v97, v97
	v_max_f32_e32 v10, v81, v81
	v_max_f32_e32 v0, v0, v10
	v_max3_f32 v10, v96, v80, v98
	v_max3_f32 v0, v0, v99, v83
	v_max3_f32 v10, v10, v82, v100
	v_max3_f32 v0, v0, v101, v85
	s_waitcnt lgkmcnt(6)
	v_mfma_f32_32x32x16_bf16 v[48:63], v[116:119], v[12:15], v[48:63]
	v_max3_f32 v10, v10, v84, v102
	v_max3_f32 v0, v0, v103, v87
	v_max3_f32 v10, v10, v86, v104
	v_max3_f32 v0, v0, v105, v89
	v_max3_f32 v10, v10, v88, v106
	v_max3_f32 v0, v0, v107, v91
	v_max3_f32 v10, v10, v90, v108
	s_waitcnt lgkmcnt(5)
	v_mfma_f32_32x32x16_bf16 v[32:47], v[120:123], v[12:15], v[32:47]
	v_max3_f32 v0, v0, v109, v93
	v_max3_f32 v10, v10, v92, v110
	v_max3_f32 v0, v0, v111, v95
	v_max3_f32 v0, v10, v94, v0
	v_mov_b32_e32 v10, v0
	s_nop 1
	v_permlane32_swap_b32_e32 v0, v10
	s_waitcnt lgkmcnt(4)
	v_mfma_f32_32x32x16_bf16 v[16:31], v[124:127], v[12:15], v[16:31]
	s_waitcnt lgkmcnt(3)
	v_mfma_f32_32x32x16_bf16 v[64:79], v[6:9], v[112:115], v[64:79]
	v_max_f32_e32 v0, v0, v0
	s_waitcnt lgkmcnt(2)
	v_mfma_f32_32x32x16_bf16 v[48:63], v[128:131], v[112:115], v[48:63]
	s_waitcnt lgkmcnt(1)
	v_mfma_f32_32x32x16_bf16 v[32:47], v[2:5], v[112:115], v[32:47]
	v_max_f32_e32 v2, v10, v10
	v_max_f32_e32 v0, v0, v2
	v_cmp_lt_f32_e32 vcc, s93, v0
	s_waitcnt lgkmcnt(0)
	v_mfma_f32_32x32x16_bf16 v[16:31], v[132:135], v[112:115], v[16:31]
	s_cbranch_vccz .LBB0_597
	v_max_f32_e32 v0, v0, v0
	v_max_f32_e32 v2, 0, v0
	v_exp_f32_e64 v0, -v2
	v_add_f32_e32 v169, v169, v2
	v_sub_f32_e32 v111, v111, v2
	v_sub_f32_e32 v110, v110, v2
	v_pk_mul_f32 v[78:79], v[78:79], v[0:1] op_sel_hi:[1,0]
	v_pk_mul_f32 v[76:77], v[76:77], v[0:1] op_sel_hi:[1,0]
	v_pk_mul_f32 v[74:75], v[74:75], v[0:1] op_sel_hi:[1,0]
	v_pk_mul_f32 v[72:73], v[72:73], v[0:1] op_sel_hi:[1,0]
	v_pk_mul_f32 v[70:71], v[70:71], v[0:1] op_sel_hi:[1,0]
	v_pk_mul_f32 v[68:69], v[68:69], v[0:1] op_sel_hi:[1,0]
	v_pk_mul_f32 v[66:67], v[66:67], v[0:1] op_sel_hi:[1,0]
	v_pk_mul_f32 v[64:65], v[64:65], v[0:1] op_sel_hi:[1,0]
	v_pk_mul_f32 v[62:63], v[62:63], v[0:1] op_sel_hi:[1,0]
	v_pk_mul_f32 v[60:61], v[60:61], v[0:1] op_sel_hi:[1,0]
	v_pk_mul_f32 v[58:59], v[58:59], v[0:1] op_sel_hi:[1,0]
	v_pk_mul_f32 v[56:57], v[56:57], v[0:1] op_sel_hi:[1,0]
	v_pk_mul_f32 v[54:55], v[54:55], v[0:1] op_sel_hi:[1,0]
	v_pk_mul_f32 v[52:53], v[52:53], v[0:1] op_sel_hi:[1,0]
	v_pk_mul_f32 v[50:51], v[50:51], v[0:1] op_sel_hi:[1,0]
	v_pk_mul_f32 v[48:49], v[48:49], v[0:1] op_sel_hi:[1,0]
	v_pk_mul_f32 v[46:47], v[0:1], v[46:47] op_sel_hi:[0,1]
	v_pk_mul_f32 v[44:45], v[0:1], v[44:45] op_sel_hi:[0,1]
	v_pk_mul_f32 v[42:43], v[0:1], v[42:43] op_sel_hi:[0,1]
	v_pk_mul_f32 v[40:41], v[0:1], v[40:41] op_sel_hi:[0,1]
	v_pk_mul_f32 v[38:39], v[0:1], v[38:39] op_sel_hi:[0,1]
	v_pk_mul_f32 v[36:37], v[0:1], v[36:37] op_sel_hi:[0,1]
	v_pk_mul_f32 v[34:35], v[0:1], v[34:35] op_sel_hi:[0,1]
	v_pk_mul_f32 v[32:33], v[0:1], v[32:33] op_sel_hi:[0,1]
	v_pk_mul_f32 v[30:31], v[0:1], v[30:31] op_sel_hi:[0,1]
	v_pk_mul_f32 v[28:29], v[0:1], v[28:29] op_sel_hi:[0,1]
	v_pk_mul_f32 v[26:27], v[0:1], v[26:27] op_sel_hi:[0,1]
	v_pk_mul_f32 v[24:25], v[0:1], v[24:25] op_sel_hi:[0,1]
	v_pk_mul_f32 v[22:23], v[0:1], v[22:23] op_sel_hi:[0,1]
	v_pk_mul_f32 v[20:21], v[0:1], v[20:21] op_sel_hi:[0,1]
	v_pk_mul_f32 v[18:19], v[0:1], v[18:19] op_sel_hi:[0,1]
	v_pk_mul_f32 v[16:17], v[0:1], v[16:17] op_sel_hi:[0,1]
	v_sub_f32_e32 v109, v109, v2
	v_sub_f32_e32 v108, v108, v2
	v_sub_f32_e32 v107, v107, v2
	v_sub_f32_e32 v106, v106, v2
	v_sub_f32_e32 v105, v105, v2
	v_sub_f32_e32 v104, v104, v2
	v_sub_f32_e32 v103, v103, v2
	v_sub_f32_e32 v102, v102, v2
	v_sub_f32_e32 v101, v101, v2
	v_sub_f32_e32 v100, v100, v2
	v_sub_f32_e32 v99, v99, v2
	v_sub_f32_e32 v98, v98, v2
	v_sub_f32_e32 v97, v97, v2
	v_sub_f32_e32 v96, v96, v2
	v_sub_f32_e32 v95, v95, v2
	v_sub_f32_e32 v94, v94, v2
	v_sub_f32_e32 v93, v93, v2
	v_sub_f32_e32 v92, v92, v2
	v_sub_f32_e32 v91, v91, v2
	v_sub_f32_e32 v90, v90, v2
	v_sub_f32_e32 v89, v89, v2
	v_sub_f32_e32 v88, v88, v2
	v_sub_f32_e32 v87, v87, v2
	v_sub_f32_e32 v86, v86, v2
	v_sub_f32_e32 v85, v85, v2
	v_sub_f32_e32 v84, v84, v2
	v_sub_f32_e32 v83, v83, v2
	v_sub_f32_e32 v82, v82, v2
	v_sub_f32_e32 v81, v81, v2
	v_sub_f32_e32 v80, v80, v2
	v_mul_f32_e32 v184, v184, v0

.LBB0_613:
	s_lshl_b32 s16, s42, 14
	s_and_b32 s16, s16, 0xc000
	s_add_i32 s16, s16, 0
	v_add_u32_e32 v0, s16, v210
	s_lshl_b32 s21, s42, 6
	ds_read_b128 v[2:5], v0
	ds_read_b128 v[6:9], v0 offset:8192
	v_cvt_f32_u32_e32 v0, s21
	v_fma_f32 v15, 2.0, v167, v185
	v_add_u32_e32 v10, s16, v211
	v_fma_f32 v113, 2.0, v185, v15
	v_sub_f32_e32 v0, v0, v205
	ds_read_b128 v[186:189], v10
	ds_read_b128 v[220:223], v10 offset:8192
	v_fma_f32 v11, v166, v0, -v169
	v_fmac_f32_e32 v113, 2.0, v15
	v_mov_b32_e32 v10, v166
	v_mov_b32_e32 v112, v167
	v_add_f32_e32 v112, v10, v112
	v_add_f32_e32 v113, v11, v113
	v_mov_b32_e32 v0, v11
	v_mov_b32_e32 v14, v113
	v_add_f32_e32 v118, v14, v112
	v_add_f32_e32 v119, v15, v113
	v_mov_b32_e32 v14, v112
	v_add_f32_e32 v120, v14, v0
	v_add_f32_e32 v121, v15, v0
	v_add_f32_e32 v136, v14, v119
	v_add_f32_e32 v137, v15, v119
	v_add_f32_e32 v126, v14, v121
	v_add_f32_e32 v127, v15, v121
	v_add_f32_e32 v114, v166, v0
	v_add_f32_e32 v115, v167, v0
	v_add_f32_e32 v162, v14, v127
	v_add_f32_e32 v163, v15, v127
	v_add_f32_e32 v14, v14, v137
	v_add_f32_e32 v15, v15, v137
	v_add_f32_e32 v116, v166, v113
	v_add_f32_e32 v117, v167, v113
	v_add_f32_e32 v122, v166, v121
	v_add_f32_e32 v123, v167, v121
	v_add_f32_e32 v124, v166, v119
	v_add_f32_e32 v125, v167, v119
	v_add_f32_e32 v138, v166, v137
	v_add_f32_e32 v139, v167, v137
	v_add_f32_e32 v142, v166, v15
	v_add_f32_e32 v143, v167, v15
	v_add_f32_e32 v196, v112, v15
	s_lshl_b32 s20, s30, 14
	v_add_f32_e32 v160, v166, v127
	v_add_f32_e32 v161, v167, v127
	v_add_f32_e32 v164, v166, v163
	v_add_f32_e32 v165, v167, v163
	v_add_f32_e32 v190, v112, v163
	v_mov_b32_e32 v128, v113
	v_mov_b32_e32 v129, v116
	v_mov_b32_e32 v130, v117
	v_mov_b32_e32 v131, v118
	v_mov_b32_e32 v132, v119
	v_mov_b32_e32 v133, v124
	v_mov_b32_e32 v134, v125
	v_mov_b32_e32 v135, v136
	v_mov_b32_e32 v136, v137
	v_mov_b32_e32 v137, v138
	v_mov_b32_e32 v138, v139
	v_mov_b32_e32 v139, v14
	v_mov_b32_e32 v140, v15
	v_mov_b32_e32 v141, v142
	v_mov_b32_e32 v142, v143
	v_mov_b32_e32 v143, v196
	v_mov_b32_e32 v112, v11
	v_mov_b32_e32 v113, v114
	v_mov_b32_e32 v114, v115
	v_mov_b32_e32 v115, v120
	v_mov_b32_e32 v116, v121
	v_mov_b32_e32 v117, v122
	v_mov_b32_e32 v118, v123
	v_mov_b32_e32 v119, v126
	v_mov_b32_e32 v120, v127
	v_mov_b32_e32 v121, v160
	v_mov_b32_e32 v122, v161
	v_mov_b32_e32 v123, v162
	v_mov_b32_e32 v124, v163
	v_mov_b32_e32 v125, v164
	v_mov_b32_e32 v126, v165
	v_mov_b32_e32 v127, v190
	s_waitcnt lgkmcnt(2)
	v_mfma_f32_32x32x16_bf16 v[128:143], v[6:9], v[144:147], v[128:143]
	v_add_u32_e32 v0, s16, v212
	v_exp_f32_e32 v13, v96
	v_exp_f32_e32 v96, v80
	v_exp_f32_e32 v161, v82
	v_exp_f32_e32 v10, v81
	v_exp_f32_e32 v160, v99
	v_exp_f32_e32 v14, v83
	v_mfma_f32_32x32x16_bf16 v[112:127], v[2:5], v[144:147], v[112:127]
	ds_read_b128 v[2:5], v0
	ds_read_b128 v[6:9], v0 offset:8192
	v_add_u32_e32 v0, s16, v213
	s_and_b32 s16, s20, 0x8000
	v_exp_f32_e32 v99, v84
	v_exp_f32_e32 v164, v101
	v_exp_f32_e32 v162, v85
	v_exp_f32_e32 v101, v88
	s_waitcnt lgkmcnt(3)
	v_mfma_f32_32x32x16_bf16 v[112:127], v[186:189], v[148:151], v[112:127]
	ds_read_b128 v[186:189], v0
	ds_read_b128 v[224:227], v0 offset:8192
	v_exp_f32_e32 v196, v105
	v_exp_f32_e32 v190, v89
	v_exp_f32_e32 v200, v107
	v_exp_f32_e32 v198, v91
	v_exp_f32_e32 v105, v92
	v_exp_f32_e32 v107, v94
	s_waitcnt lgkmcnt(4)
	v_mfma_f32_32x32x16_bf16 v[128:143], v[220:223], v[148:151], v[128:143]
	v_exp_f32_e32 v240, v93
	v_exp_f32_e32 v244, v95
	s_add_i32 s16, s16, 0
	v_add_u32_e32 v0, s16, v214
	ds_read_b128 v[220:223], v0
	ds_read_b128 v[228:231], v0 offset:4096
	ds_read_b128 v[232:235], v0 offset:8192
	ds_read_b128 v[236:239], v0 offset:12288
	v_exp_f32_e32 v98, v98
	v_exp_f32_e32 v0, v97
	s_waitcnt lgkmcnt(7)
	v_mfma_f32_32x32x16_bf16 v[112:127], v[2:5], v[152:155], v[112:127]
	v_exp_f32_e32 v4, v100
	v_exp_f32_e32 v100, v86
	v_exp_f32_e32 v5, v102
	v_exp_f32_e32 v97, v104
	v_exp_f32_e32 v102, v106
	v_exp_f32_e32 v104, v108
	v_exp_f32_e32 v106, v110
	s_waitcnt lgkmcnt(6)
	v_mfma_f32_32x32x16_bf16 v[128:143], v[6:9], v[152:155], v[128:143]
	v_exp_f32_e32 v242, v109
	v_exp_f32_e32 v246, v111
	v_add_f32_e32 v11, v96, v13
	v_add_f32_e32 v15, v161, v98
	v_add_f32_e32 v163, v99, v4
	v_add_f32_e32 v191, v101, v97
	v_add_f32_e32 v241, v105, v104
	s_waitcnt lgkmcnt(5)
	v_mfma_f32_32x32x16_bf16 v[112:127], v[186:189], v[156:159], v[112:127]
	v_exp_f32_e32 v188, v103
	v_exp_f32_e32 v186, v87
	v_exp_f32_e32 v103, v90
	v_mov_b64_e32 v[80:81], v[128:129]
	v_mov_b64_e32 v[82:83], v[130:131]
	v_mov_b64_e32 v[84:85], v[132:133]
	v_mov_b64_e32 v[86:87], v[134:135]
	v_mov_b64_e32 v[88:89], v[136:137]
	v_mov_b64_e32 v[90:91], v[138:139]
	v_mov_b64_e32 v[92:93], v[140:141]
	v_mov_b64_e32 v[94:95], v[142:143]
	v_add_f32_e32 v187, v100, v5
	v_add_f32_e32 v199, v103, v102
	s_waitcnt lgkmcnt(4)
	v_mfma_f32_32x32x16_bf16 v[80:95], v[224:227], v[156:159], v[80:95]
	v_add_f32_e32 v245, v107, v106
	v_cvt_pk_bf16_f32 v2, v13, v0
	v_cvt_pk_bf16_f32 v3, v98, v160
	v_cvt_pk_bf16_f32 v4, v4, v164
	v_cvt_pk_bf16_f32 v5, v5, v188
	v_cvt_pk_bf16_f32 v6, v97, v196
	v_cvt_pk_bf16_f32 v7, v102, v200
	v_cvt_pk_bf16_f32 v8, v104, v242
	v_cvt_pk_bf16_f32 v9, v106, v246
	v_cvt_pk_bf16_f32 v96, v96, v10
	v_cvt_pk_bf16_f32 v97, v161, v14
	v_cvt_pk_bf16_f32 v98, v99, v162
	v_cvt_pk_bf16_f32 v99, v100, v186
	v_cvt_pk_bf16_f32 v100, v101, v190
	v_cvt_pk_bf16_f32 v101, v103, v198
	v_cvt_pk_bf16_f32 v102, v105, v240
	v_cvt_pk_bf16_f32 v103, v107, v244
	v_add_f32_e32 v10, v10, v0
	v_add_f32_e32 v11, v11, v1
	v_xor_b32_e32 v13, 0x10020, v215
	v_add_f32_e32 v11, v10, v11
	v_mov_b32_e32 v161, v11
	v_add_f32_e32 v10, v14, v160
	v_add_f32_e32 v11, v15, v161
	v_add_u32_e32 v13, s16, v13
	v_add_f32_e32 v11, v10, v11
	v_mov_b32_e32 v165, v11
	v_add_f32_e32 v10, v162, v164
	v_add_f32_e32 v11, v163, v165
	s_waitcnt lgkmcnt(3)
	v_mfma_f32_32x32x16_bf16 v[64:79], v[220:223], v[2:5], v[64:79]
	v_add_f32_e32 v11, v10, v11
	v_mov_b32_e32 v189, v11
	v_add_f32_e32 v10, v186, v188
	v_add_f32_e32 v11, v187, v189
	ds_read_b128 v[104:107], v13
	ds_read_b128 v[108:111], v13 offset:4096
	ds_read_b128 v[128:131], v13 offset:8192
	ds_read_b128 v[132:135], v13 offset:12288
	v_add_f32_e32 v11, v10, v11
	v_mov_b32_e32 v197, v11
	v_add_f32_e32 v10, v190, v196
	v_add_f32_e32 v11, v191, v197
	s_waitcnt lgkmcnt(6)
	v_mfma_f32_32x32x16_bf16 v[48:63], v[228:231], v[2:5], v[48:63]
	v_add_f32_e32 v11, v10, v11
	v_mov_b32_e32 v201, v11
	v_add_f32_e32 v10, v198, v200
	v_add_f32_e32 v11, v199, v201
	s_nop 0
	v_add_f32_e32 v11, v10, v11
	v_mov_b32_e32 v243, v11
	v_add_f32_e32 v10, v240, v242
	v_add_f32_e32 v11, v241, v243
	s_waitcnt lgkmcnt(5)
	v_mfma_f32_32x32x16_bf16 v[32:47], v[232:235], v[2:5], v[32:47]
	v_add_f32_e32 v11, v10, v11
	v_mov_b32_e32 v247, v11
	v_add_f32_e32 v10, v244, v246
	v_add_f32_e32 v11, v245, v247
	s_nop 0
	v_add_f32_e32 v0, v10, v11
	v_add_f32_e32 v184, v184, v0
	s_waitcnt lgkmcnt(4)
	v_mfma_f32_32x32x16_bf16 v[16:31], v[236:239], v[2:5], v[16:31]
	v_xor_b32_e32 v0, 0x10040, v215
	s_waitcnt lgkmcnt(3)
	v_mfma_f32_32x32x16_bf16 v[64:79], v[104:107], v[6:9], v[64:79]
	v_add_u32_e32 v0, s16, v0
	s_waitcnt lgkmcnt(2)
	v_mfma_f32_32x32x16_bf16 v[48:63], v[108:111], v[6:9], v[48:63]
	s_waitcnt lgkmcnt(1)
	v_mfma_f32_32x32x16_bf16 v[32:47], v[128:131], v[6:9], v[32:47]
	ds_read_b128 v[2:5], v0
	ds_read_b128 v[104:107], v0 offset:4096
	ds_read_b128 v[108:111], v0 offset:8192
	ds_read_b128 v[128:131], v0 offset:12288
	s_waitcnt lgkmcnt(4)
	v_mfma_f32_32x32x16_bf16 v[16:31], v[132:135], v[6:9], v[16:31]
	v_xor_b32_e32 v0, 0x10060, v215
	v_add_u32_e32 v0, s16, v0
	ds_read_b128 v[6:9], v0
	ds_read_b128 v[132:135], v0 offset:4096
	s_waitcnt lgkmcnt(5)
	v_mfma_f32_32x32x16_bf16 v[64:79], v[2:5], v[96:99], v[64:79]
	ds_read_b128 v[2:5], v0 offset:8192
	ds_read_b128 v[136:139], v0 offset:12288
	v_max_f32_e32 v0, v81, v81
	v_max_f32_e32 v10, v113, v113
	v_max_f32_e32 v0, v10, v0
	v_max3_f32 v10, v112, v80, v114
	v_max3_f32 v0, v0, v115, v83
	v_max3_f32 v10, v10, v82, v116
	v_max3_f32 v0, v0, v117, v85
	s_waitcnt lgkmcnt(6)
	v_mfma_f32_32x32x16_bf16 v[48:63], v[104:107], v[96:99], v[48:63]
	v_max3_f32 v10, v10, v84, v118
	v_max3_f32 v0, v0, v119, v87
	v_max3_f32 v10, v10, v86, v120
	v_max3_f32 v0, v0, v121, v89
	v_max3_f32 v10, v10, v88, v122
	v_max3_f32 v0, v0, v123, v91
	v_max3_f32 v10, v10, v90, v124
	s_waitcnt lgkmcnt(5)
	v_mfma_f32_32x32x16_bf16 v[32:47], v[108:111], v[96:99], v[32:47]
	v_max3_f32 v0, v0, v125, v93
	v_max3_f32 v10, v10, v92, v126
	v_max3_f32 v0, v0, v127, v95
	v_max3_f32 v0, v10, v94, v0
	v_mov_b32_e32 v10, v0
	s_nop 1
	v_permlane32_swap_b32_e32 v0, v10
	s_waitcnt lgkmcnt(4)
	v_mfma_f32_32x32x16_bf16 v[16:31], v[128:131], v[96:99], v[16:31]
	s_waitcnt lgkmcnt(3)
	v_mfma_f32_32x32x16_bf16 v[64:79], v[6:9], v[100:103], v[64:79]
	v_max_f32_e32 v0, v0, v0
	s_waitcnt lgkmcnt(2)
	v_mfma_f32_32x32x16_bf16 v[48:63], v[132:135], v[100:103], v[48:63]
	s_waitcnt lgkmcnt(1)
	v_mfma_f32_32x32x16_bf16 v[32:47], v[2:5], v[100:103], v[32:47]
	v_max_f32_e32 v2, v10, v10
	v_max_f32_e32 v0, v0, v2
	v_cmp_lt_f32_e32 vcc, s93, v0
	s_waitcnt lgkmcnt(0)
	v_mfma_f32_32x32x16_bf16 v[16:31], v[136:139], v[100:103], v[16:31]
	s_cbranch_vccz .LBB0_671
	v_max_f32_e32 v0, v0, v0
	v_max_f32_e32 v2, 0, v0
	v_exp_f32_e64 v0, -v2
	v_add_f32_e32 v169, v169, v2
	v_sub_f32_e32 v111, v127, v2
	v_sub_f32_e32 v110, v126, v2
	v_pk_mul_f32 v[78:79], v[78:79], v[0:1] op_sel_hi:[1,0]
	v_pk_mul_f32 v[76:77], v[76:77], v[0:1] op_sel_hi:[1,0]
	v_pk_mul_f32 v[74:75], v[74:75], v[0:1] op_sel_hi:[1,0]
	v_pk_mul_f32 v[72:73], v[72:73], v[0:1] op_sel_hi:[1,0]
	v_pk_mul_f32 v[70:71], v[70:71], v[0:1] op_sel_hi:[1,0]
	v_pk_mul_f32 v[68:69], v[68:69], v[0:1] op_sel_hi:[1,0]
	v_pk_mul_f32 v[66:67], v[66:67], v[0:1] op_sel_hi:[1,0]
	v_pk_mul_f32 v[64:65], v[64:65], v[0:1] op_sel_hi:[1,0]
	v_pk_mul_f32 v[62:63], v[62:63], v[0:1] op_sel_hi:[1,0]
	v_pk_mul_f32 v[60:61], v[60:61], v[0:1] op_sel_hi:[1,0]
	v_pk_mul_f32 v[58:59], v[58:59], v[0:1] op_sel_hi:[1,0]
	v_pk_mul_f32 v[56:57], v[56:57], v[0:1] op_sel_hi:[1,0]
	v_pk_mul_f32 v[54:55], v[54:55], v[0:1] op_sel_hi:[1,0]
	v_pk_mul_f32 v[52:53], v[52:53], v[0:1] op_sel_hi:[1,0]
	v_pk_mul_f32 v[50:51], v[50:51], v[0:1] op_sel_hi:[1,0]
	v_pk_mul_f32 v[48:49], v[48:49], v[0:1] op_sel_hi:[1,0]
	v_pk_mul_f32 v[46:47], v[0:1], v[46:47] op_sel_hi:[0,1]
	v_pk_mul_f32 v[44:45], v[0:1], v[44:45] op_sel_hi:[0,1]
	v_pk_mul_f32 v[42:43], v[0:1], v[42:43] op_sel_hi:[0,1]
	v_pk_mul_f32 v[40:41], v[0:1], v[40:41] op_sel_hi:[0,1]
	v_pk_mul_f32 v[38:39], v[0:1], v[38:39] op_sel_hi:[0,1]
	v_pk_mul_f32 v[36:37], v[0:1], v[36:37] op_sel_hi:[0,1]
	v_pk_mul_f32 v[34:35], v[0:1], v[34:35] op_sel_hi:[0,1]
	v_pk_mul_f32 v[32:33], v[0:1], v[32:33] op_sel_hi:[0,1]
	v_pk_mul_f32 v[30:31], v[0:1], v[30:31] op_sel_hi:[0,1]
	v_pk_mul_f32 v[28:29], v[0:1], v[28:29] op_sel_hi:[0,1]
	v_pk_mul_f32 v[26:27], v[0:1], v[26:27] op_sel_hi:[0,1]
	v_pk_mul_f32 v[24:25], v[0:1], v[24:25] op_sel_hi:[0,1]
	v_pk_mul_f32 v[22:23], v[0:1], v[22:23] op_sel_hi:[0,1]
	v_pk_mul_f32 v[20:21], v[0:1], v[20:21] op_sel_hi:[0,1]
	v_pk_mul_f32 v[18:19], v[0:1], v[18:19] op_sel_hi:[0,1]
	v_pk_mul_f32 v[16:17], v[0:1], v[16:17] op_sel_hi:[0,1]
	v_sub_f32_e32 v109, v125, v2
	v_sub_f32_e32 v108, v124, v2
	v_sub_f32_e32 v107, v123, v2
	v_sub_f32_e32 v106, v122, v2
	v_sub_f32_e32 v105, v121, v2
	v_sub_f32_e32 v104, v120, v2
	v_sub_f32_e32 v103, v119, v2
	v_sub_f32_e32 v102, v118, v2
	v_sub_f32_e32 v101, v117, v2
	v_sub_f32_e32 v100, v116, v2
	v_sub_f32_e32 v99, v115, v2
	v_sub_f32_e32 v98, v114, v2
	v_sub_f32_e32 v97, v113, v2
	v_sub_f32_e32 v96, v112, v2
	v_sub_f32_e32 v95, v95, v2
	v_sub_f32_e32 v94, v94, v2
	v_sub_f32_e32 v93, v93, v2
	v_sub_f32_e32 v92, v92, v2
	v_sub_f32_e32 v91, v91, v2
	v_sub_f32_e32 v90, v90, v2
	v_sub_f32_e32 v89, v89, v2
	v_sub_f32_e32 v88, v88, v2
	v_sub_f32_e32 v87, v87, v2
	v_sub_f32_e32 v86, v86, v2
	v_sub_f32_e32 v85, v85, v2
	v_sub_f32_e32 v84, v84, v2
	v_sub_f32_e32 v83, v83, v2
	v_sub_f32_e32 v82, v82, v2
	v_sub_f32_e32 v81, v81, v2
	v_sub_f32_e32 v80, v80, v2
	v_mul_f32_e32 v184, v184, v0
	s_mov_b64 s[54:55], -1
	s_and_b64 vcc, exec, s[12:13]
	s_cbranch_vccz .LBB0_616

.LBB0_624:
	s_add_i32 s16, s42, 1
	s_lshl_b32 s20, s16, 14
	s_lshl_b32 s28, s16, 6
	s_and_b32 s20, s20, 0xc000
	v_cvt_f32_i32_e32 v13, s28
	s_add_i32 s20, s20, 0
	v_add_u32_e32 v0, s20, v210
	ds_read_b128 v[2:5], v0
	ds_read_b128 v[6:9], v0 offset:8192
	v_add_u32_e32 v0, s20, v211
	ds_read_b128 v[180:183], v0
	ds_read_b128 v[186:189], v0 offset:8192
	v_sub_f32_e32 v0, v13, v205
	v_mul_f32_e32 v10, 0, v166
	v_mul_f32_e32 v11, v10, v0
	v_mov_b32_e32 v168, v10
	v_add_f32_e32 v14, v10, v168
	v_sub_f32_e32 v128, v10, v168
	v_sub_f32_e32 v129, v11, v169
	s_lshl_b32 s21, s42, 14
	v_mov_b32_e32 v15, v129
	v_add_f32_e32 v112, v14, v14
	v_add_f32_e32 v113, v15, v15
	s_nop 0
	v_pk_fma_f32 v[114:115], v[14:15], 2.0, v[112:113] op_sel_hi:[1,0,1]
	s_nop 0
	v_pk_fma_f32 v[112:113], v[112:113], 2.0, v[114:115] op_sel_hi:[1,0,1]
	v_mov_b32_e32 v121, v114
	v_pk_fma_f32 v[112:113], v[114:115], 2.0, v[112:113] op_sel_hi:[1,0,1]
	s_nop 0
	v_mov_b32_e32 v11, v112
	v_add_f32_e32 v112, v10, v14
	v_add_f32_e32 v113, v11, v15
	v_mov_b32_e32 v11, v14
	v_pk_mov_b32 v[118:119], v[112:113], v[114:115] op_sel:[1,0]
	v_mov_b32_e32 v120, v112
	v_add_f32_e32 v118, v118, v112
	v_add_f32_e32 v119, v119, v113
	v_add_f32_e32 v132, v120, v129
	v_add_f32_e32 v133, v121, v129
	v_add_f32_e32 v124, v120, v119
	v_add_f32_e32 v125, v121, v119
	v_add_f32_e32 v136, v120, v133
	v_add_f32_e32 v137, v121, v133
	v_add_f32_e32 v130, v120, v125
	v_add_f32_e32 v131, v121, v125
	v_add_f32_e32 v140, v120, v137
	v_add_f32_e32 v141, v121, v137
	v_add_f32_e32 v14, v10, v129
	v_add_f32_e32 v15, v11, v129
	v_add_f32_e32 v116, v10, v113
	v_add_f32_e32 v117, v11, v113
	v_add_f32_e32 v134, v10, v133
	v_add_f32_e32 v135, v11, v133
	v_add_f32_e32 v122, v10, v119
	v_add_f32_e32 v123, v11, v119
	v_add_f32_e32 v138, v10, v137
	v_add_f32_e32 v139, v11, v137
	v_add_f32_e32 v126, v10, v125
	v_add_f32_e32 v127, v11, v125
	v_add_f32_e32 v142, v10, v141
	v_add_f32_e32 v143, v11, v141
	v_add_f32_e32 v10, v10, v131
	v_add_f32_e32 v11, v11, v131
	v_add_f32_e32 v162, v112, v131
	v_add_f32_e32 v160, v112, v141
	v_mov_b32_e32 v112, v113
	v_mov_b32_e32 v113, v116
	v_mov_b32_e32 v114, v117
	v_mov_b32_e32 v115, v118
	v_mov_b32_e32 v116, v119
	v_mov_b32_e32 v117, v122
	v_mov_b32_e32 v118, v123
	v_mov_b32_e32 v119, v124
	v_mov_b32_e32 v120, v125
	v_mov_b32_e32 v121, v126
	v_mov_b32_e32 v122, v127
	v_mov_b32_e32 v123, v130
	v_mov_b32_e32 v124, v131
	v_mov_b32_e32 v125, v10
	v_mov_b32_e32 v126, v11
	v_mov_b32_e32 v127, v162
	v_mov_b32_e32 v128, v129
	v_mov_b32_e32 v129, v14
	v_mov_b32_e32 v130, v15
	v_mov_b32_e32 v131, v132
	v_mov_b32_e32 v132, v133
	v_mov_b32_e32 v133, v134
	v_mov_b32_e32 v134, v135
	v_mov_b32_e32 v135, v136
	v_mov_b32_e32 v136, v137
	v_mov_b32_e32 v137, v138
	v_mov_b32_e32 v138, v139
	v_mov_b32_e32 v139, v140
	v_mov_b32_e32 v140, v141
	v_mov_b32_e32 v141, v142
	v_mov_b32_e32 v142, v143
	v_mov_b32_e32 v143, v160
	s_waitcnt lgkmcnt(2)
	v_mfma_f32_32x32x16_bf16 v[112:127], v[6:9], v[144:147], v[112:127]
	v_add_u32_e32 v0, s20, v212
	v_exp_f32_e32 v161, v80
	v_exp_f32_e32 v80, v98
	v_exp_f32_e32 v98, v82
	v_exp_f32_e32 v10, v81
	v_exp_f32_e32 v160, v99
	v_exp_f32_e32 v14, v83
	v_mfma_f32_32x32x16_bf16 v[128:143], v[2:5], v[144:147], v[128:143]
	ds_read_b128 v[2:5], v0
	ds_read_b128 v[6:9], v0 offset:8192
	v_add_u32_e32 v0, s20, v213
	s_and_b32 s20, s21, 0xc000
	s_add_i32 s20, s20, 0
	v_exp_f32_e32 v162, v85
	v_exp_f32_e32 v81, v104
	v_exp_f32_e32 v88, v88
	s_waitcnt lgkmcnt(3)
	v_mfma_f32_32x32x16_bf16 v[128:143], v[180:183], v[148:151], v[128:143]
	ds_read_b128 v[180:183], v0
	ds_read_b128 v[220:223], v0 offset:8192
	v_add_u32_e32 v0, s20, v214
	v_exp_f32_e32 v82, v106
	v_exp_f32_e32 v90, v90
	v_exp_f32_e32 v104, v105
	v_exp_f32_e32 v190, v89
	v_exp_f32_e32 v106, v107
	s_waitcnt lgkmcnt(4)
	v_mfma_f32_32x32x16_bf16 v[112:127], v[186:189], v[148:151], v[112:127]
	ds_read_b128 v[186:189], v0
	ds_read_b128 v[224:227], v0 offset:4096
	ds_read_b128 v[228:231], v0 offset:8192
	ds_read_b128 v[232:235], v0 offset:12288
	v_exp_f32_e32 v196, v91
	v_exp_f32_e32 v83, v108
	v_exp_f32_e32 v89, v92
	v_exp_f32_e32 v91, v94
	v_exp_f32_e32 v108, v109
	v_exp_f32_e32 v96, v96
	s_waitcnt lgkmcnt(7)
	v_mfma_f32_32x32x16_bf16 v[128:143], v[2:5], v[152:155], v[128:143]
	v_exp_f32_e32 v3, v84
	v_exp_f32_e32 v5, v86
	v_exp_f32_e32 v84, v110
	v_exp_f32_e32 v110, v111
	v_exp_f32_e32 v0, v97
	v_exp_f32_e32 v2, v100
	v_exp_f32_e32 v4, v102
	s_waitcnt lgkmcnt(6)
	v_mfma_f32_32x32x16_bf16 v[112:127], v[6:9], v[152:155], v[112:127]
	v_exp_f32_e32 v164, v101
	v_exp_f32_e32 v198, v93
	v_exp_f32_e32 v200, v95
	v_add_f32_e32 v15, v98, v80
	v_add_f32_e32 v191, v88, v81
	v_add_f32_e32 v197, v90, v82
	v_add_f32_e32 v199, v89, v83
	s_waitcnt lgkmcnt(5)
	v_mfma_f32_32x32x16_bf16 v[128:143], v[180:183], v[156:159], v[128:143]
	v_exp_f32_e32 v180, v87
	v_exp_f32_e32 v182, v103
	v_add_f32_e32 v201, v91, v84
	v_cvt_pk_bf16_f32 v7, v80, v160
	v_cvt_pk_bf16_f32 v80, v81, v104
	v_cvt_pk_bf16_f32 v81, v82, v106
	v_cvt_pk_bf16_f32 v82, v83, v108
	v_cvt_pk_bf16_f32 v83, v84, v110
	v_cvt_pk_bf16_f32 v84, v161, v10
	v_cvt_pk_bf16_f32 v85, v98, v14
	v_cvt_pk_bf16_f32 v86, v3, v162
	v_cvt_pk_bf16_f32 v87, v5, v180
	v_add_f32_e32 v11, v161, v96
	v_add_f32_e32 v163, v3, v2
	v_add_f32_e32 v181, v5, v4
	s_waitcnt lgkmcnt(4)
	v_mfma_f32_32x32x16_bf16 v[112:127], v[220:223], v[156:159], v[112:127]
	v_cvt_pk_bf16_f32 v6, v96, v0
	v_cvt_pk_bf16_f32 v8, v2, v164
	v_cvt_pk_bf16_f32 v9, v4, v182
	v_cvt_pk_bf16_f32 v2, v88, v190
	v_cvt_pk_bf16_f32 v3, v90, v196
	v_cvt_pk_bf16_f32 v4, v89, v198
	v_cvt_pk_bf16_f32 v5, v91, v200
	v_add_f32_e32 v10, v10, v0
	v_add_f32_e32 v11, v11, v1
	v_xor_b32_e32 v88, 0x10020, v215
	v_add_f32_e32 v11, v10, v11
	v_mov_b32_e32 v161, v11
	v_add_f32_e32 v10, v14, v160
	v_add_f32_e32 v11, v15, v161
	v_add_u32_e32 v100, s20, v88
	v_add_f32_e32 v11, v10, v11
	v_mov_b32_e32 v165, v11
	v_add_f32_e32 v10, v162, v164
	v_add_f32_e32 v11, v163, v165
	s_waitcnt lgkmcnt(3)
	v_mfma_f32_32x32x16_bf16 v[64:79], v[186:189], v[6:9], v[64:79]
	v_add_f32_e32 v11, v10, v11
	v_mov_b32_e32 v183, v11
	v_add_f32_e32 v10, v180, v182
	v_add_f32_e32 v11, v181, v183
	ds_read_b128 v[88:91], v100
	ds_read_b128 v[92:95], v100 offset:4096
	ds_read_b128 v[96:99], v100 offset:8192
	ds_read_b128 v[100:103], v100 offset:12288
	v_add_f32_e32 v11, v10, v11
	v_mov_b32_e32 v105, v11
	v_add_f32_e32 v10, v190, v104
	v_add_f32_e32 v11, v191, v105
	s_waitcnt lgkmcnt(6)
	v_mfma_f32_32x32x16_bf16 v[48:63], v[224:227], v[6:9], v[48:63]
	v_add_f32_e32 v11, v10, v11
	v_mov_b32_e32 v107, v11
	v_add_f32_e32 v10, v196, v106
	v_add_f32_e32 v11, v197, v107
	s_nop 0
	v_add_f32_e32 v11, v10, v11
	v_mov_b32_e32 v109, v11
	v_add_f32_e32 v10, v198, v108
	v_add_f32_e32 v11, v199, v109
	s_waitcnt lgkmcnt(5)
	v_mfma_f32_32x32x16_bf16 v[32:47], v[228:231], v[6:9], v[32:47]
	v_add_f32_e32 v11, v10, v11
	v_mov_b32_e32 v111, v11
	v_add_f32_e32 v10, v200, v110
	v_add_f32_e32 v11, v201, v111
	s_nop 0
	v_add_f32_e32 v0, v10, v11
	v_add_f32_e32 v184, v184, v0
	s_waitcnt lgkmcnt(4)
	v_mfma_f32_32x32x16_bf16 v[16:31], v[232:235], v[6:9], v[16:31]
	v_xor_b32_e32 v0, 0x10040, v215
	s_waitcnt lgkmcnt(3)
	v_mfma_f32_32x32x16_bf16 v[64:79], v[88:91], v[80:83], v[64:79]
	v_add_u32_e32 v0, s20, v0
	s_waitcnt lgkmcnt(2)
	v_mfma_f32_32x32x16_bf16 v[48:63], v[92:95], v[80:83], v[48:63]
	s_waitcnt lgkmcnt(1)
	v_mfma_f32_32x32x16_bf16 v[32:47], v[96:99], v[80:83], v[32:47]
	ds_read_b128 v[6:9], v0
	ds_read_b128 v[88:91], v0 offset:4096
	ds_read_b128 v[92:95], v0 offset:8192
	ds_read_b128 v[96:99], v0 offset:12288
	s_waitcnt lgkmcnt(4)
	v_mfma_f32_32x32x16_bf16 v[16:31], v[100:103], v[80:83], v[16:31]
	v_xor_b32_e32 v0, 0x10060, v215
	v_add_u32_e32 v0, s20, v0
	ds_read_b128 v[180:183], v0
	ds_read_b128 v[186:189], v0 offset:4096
	ds_read_b128 v[220:223], v0 offset:8192
	ds_read_b128 v[224:227], v0 offset:12288
	v_sub_f32_e32 v0, v205, v13
	s_waitcnt lgkmcnt(7)
	v_mfma_f32_32x32x16_bf16 v[64:79], v[6:9], v[84:87], v[64:79]
	v_add_f32_e32 v7, -1.0, v0
	v_and_b32_e32 v6, 0x7fffffff, v0
	v_and_b32_e32 v7, 0x7fffffff, v7
	s_mov_b32 s20, -2.0
	s_mov_b32 s21, 0xc0400000
	s_waitcnt lgkmcnt(4)
	v_mfma_f32_32x32x16_bf16 v[16:31], v[96:99], v[84:87], v[16:31]
	v_fma_f32 v96, -v166, v6, v128
	v_fma_f32 v97, -v166, v7, v129
	v_add_f32_e32 v6, 0xc2000000, v0
	v_add_f32_e32 v7, -1.0, v6
	v_and_b32_e32 v8, 0x7fffffff, v6
	v_and_b32_e32 v9, 0x7fffffff, v7
	v_pk_fma_f32 v[80:81], v[166:167], v[8:9], v[112:113] op_sel_hi:[0,1,1] neg_lo:[1,0,0] neg_hi:[1,0,0]
	v_add_f32_e32 v8, s20, v0
	v_add_f32_e32 v9, s21, v0
	v_and_b32_e32 v9, 0x7fffffff, v9
	v_and_b32_e32 v8, 0x7fffffff, v8
	v_pk_fma_f32 v[98:99], v[166:167], v[8:9], v[130:131] op_sel_hi:[0,1,1] neg_lo:[1,0,0] neg_hi:[1,0,0]
	v_add_f32_e32 v8, s20, v6
	v_add_f32_e32 v9, s21, v6
	s_mov_b32 s20, 0xc1000000
	v_and_b32_e32 v9, 0x7fffffff, v9
	v_and_b32_e32 v8, 0x7fffffff, v8
	s_mov_b32 s21, 0xc1100000
	v_pk_fma_f32 v[82:83], v[166:167], v[8:9], v[114:115] op_sel_hi:[0,1,1] neg_lo:[1,0,0] neg_hi:[1,0,0]
	v_add_f32_e32 v8, s20, v0
	v_add_f32_e32 v9, s21, v0
	v_and_b32_e32 v9, 0x7fffffff, v9
	v_and_b32_e32 v8, 0x7fffffff, v8
	v_pk_fma_f32 v[100:101], v[166:167], v[8:9], v[132:133] op_sel_hi:[0,1,1] neg_lo:[1,0,0] neg_hi:[1,0,0]
	v_add_f32_e32 v8, s20, v6
	v_add_f32_e32 v9, s21, v6
	s_mov_b32 s20, 0xc1200000
	v_and_b32_e32 v9, 0x7fffffff, v9
	v_and_b32_e32 v8, 0x7fffffff, v8
	s_mov_b32 s21, 0xc1300000
	v_mfma_f32_32x32x16_bf16 v[48:63], v[88:91], v[84:87], v[48:63]
	v_mfma_f32_32x32x16_bf16 v[32:47], v[92:95], v[84:87], v[32:47]
	v_fma_f32 v84, -v166, v8, v116
	v_fma_f32 v85, -v166, v9, v117
	v_add_f32_e64 v8, v0, s20
	v_add_f32_e64 v9, v0, s21
	v_and_b32_e32 v9, 0x7fffffff, v9
	v_and_b32_e32 v8, 0x7fffffff, v8
	v_pk_fma_f32 v[102:103], v[166:167], v[8:9], v[134:135] op_sel_hi:[0,1,1] neg_lo:[1,0,0] neg_hi:[1,0,0]
	v_add_f32_e32 v8, s20, v6
	v_add_f32_e32 v9, s21, v6
	s_mov_b32 s20, 0xc1800000
	v_and_b32_e32 v9, 0x7fffffff, v9
	v_and_b32_e32 v8, 0x7fffffff, v8
	s_mov_b32 s21, 0xc1880000
	v_pk_fma_f32 v[86:87], v[166:167], v[8:9], v[118:119] op_sel_hi:[0,1,1] neg_lo:[1,0,0] neg_hi:[1,0,0]
	v_add_f32_e32 v8, s20, v0
	v_add_f32_e32 v9, s21, v0
	v_and_b32_e32 v9, 0x7fffffff, v9
	v_and_b32_e32 v8, 0x7fffffff, v8
	v_pk_fma_f32 v[104:105], v[166:167], v[8:9], v[136:137] op_sel_hi:[0,1,1] neg_lo:[1,0,0] neg_hi:[1,0,0]
	v_add_f32_e32 v8, s20, v6
	v_add_f32_e32 v9, s21, v6
	s_mov_b32 s20, 0xc1900000
	v_and_b32_e32 v9, 0x7fffffff, v9
	v_and_b32_e32 v8, 0x7fffffff, v8
	s_mov_b32 s21, 0xc1980000
	v_pk_fma_f32 v[88:89], v[166:167], v[8:9], v[120:121] op_sel_hi:[0,1,1] neg_lo:[1,0,0] neg_hi:[1,0,0]
	v_add_f32_e32 v8, s20, v0
	v_add_f32_e32 v9, s21, v0
	v_and_b32_e32 v9, 0x7fffffff, v9
	v_and_b32_e32 v8, 0x7fffffff, v8
	v_pk_fma_f32 v[106:107], v[166:167], v[8:9], v[138:139] op_sel_hi:[0,1,1] neg_lo:[1,0,0] neg_hi:[1,0,0]
	v_add_f32_e32 v8, s20, v6
	v_add_f32_e32 v9, s21, v6
	s_mov_b32 s20, 0xc1c00000
	v_and_b32_e32 v9, 0x7fffffff, v9
	v_and_b32_e32 v8, 0x7fffffff, v8
	s_mov_b32 s21, 0xc1c80000
	v_pk_fma_f32 v[90:91], v[166:167], v[8:9], v[122:123] op_sel_hi:[0,1,1] neg_lo:[1,0,0] neg_hi:[1,0,0]
	v_add_f32_e32 v8, s20, v0
	v_add_f32_e32 v9, s21, v0
	v_and_b32_e32 v9, 0x7fffffff, v9
	v_and_b32_e32 v8, 0x7fffffff, v8
	v_pk_fma_f32 v[108:109], v[166:167], v[8:9], v[140:141] op_sel_hi:[0,1,1] neg_lo:[1,0,0] neg_hi:[1,0,0]
	v_add_f32_e32 v8, s20, v6
	v_add_f32_e32 v9, s21, v6
	s_mov_b32 s20, 0xc1d00000
	s_mov_b32 s21, 0xc1d80000
	v_and_b32_e32 v9, 0x7fffffff, v9
	v_and_b32_e32 v8, 0x7fffffff, v8
	v_add_f32_e32 v7, s21, v6
	v_add_f32_e32 v6, s20, v6
	v_pk_fma_f32 v[92:93], v[166:167], v[8:9], v[124:125] op_sel_hi:[0,1,1] neg_lo:[1,0,0] neg_hi:[1,0,0]
	v_add_f32_e32 v8, s20, v0
	v_add_f32_e32 v9, s21, v0
	v_and_b32_e32 v7, 0x7fffffff, v7
	v_and_b32_e32 v6, 0x7fffffff, v6
	v_max_f32_e32 v0, v97, v81
	v_pk_fma_f32 v[94:95], v[166:167], v[6:7], v[126:127] op_sel_hi:[0,1,1] neg_lo:[1,0,0] neg_hi:[1,0,0]
	v_max3_f32 v6, v96, v80, v98
	v_max3_f32 v0, v0, v99, v83
	v_max3_f32 v6, v6, v82, v100
	v_max3_f32 v0, v0, v101, v85
	v_max3_f32 v6, v6, v84, v102
	v_max3_f32 v0, v0, v103, v87
	v_max3_f32 v6, v6, v86, v104
	v_max3_f32 v0, v0, v105, v89
	v_and_b32_e32 v9, 0x7fffffff, v9
	v_and_b32_e32 v8, 0x7fffffff, v8
	v_max3_f32 v6, v6, v88, v106
	v_max3_f32 v0, v0, v107, v91
	v_pk_fma_f32 v[110:111], v[166:167], v[8:9], v[142:143] op_sel_hi:[0,1,1] neg_lo:[1,0,0] neg_hi:[1,0,0]
	v_max3_f32 v6, v6, v90, v108
	v_max3_f32 v0, v0, v109, v93
	v_max3_f32 v6, v6, v92, v110
	v_max3_f32 v0, v0, v111, v95
	v_max3_f32 v0, v6, v94, v0
	v_mov_b32_e32 v6, v0
	s_nop 1
	v_permlane32_swap_b32_e32 v0, v6
	s_waitcnt lgkmcnt(3)
	v_mfma_f32_32x32x16_bf16 v[64:79], v[180:183], v[2:5], v[64:79]
	v_max_f32_e32 v6, v6, v6
	v_max_f32_e32 v0, v0, v0
	v_max_f32_e32 v0, v0, v6
	v_cmp_lt_f32_e32 vcc, s93, v0
	s_waitcnt lgkmcnt(2)
	v_mfma_f32_32x32x16_bf16 v[48:63], v[186:189], v[2:5], v[48:63]
	s_waitcnt lgkmcnt(1)
	v_mfma_f32_32x32x16_bf16 v[32:47], v[220:223], v[2:5], v[32:47]
	s_waitcnt lgkmcnt(0)
	v_mfma_f32_32x32x16_bf16 v[16:31], v[224:227], v[2:5], v[16:31]
	s_cbranch_vccz .LBB0_626
	v_max_f32_e32 v0, v0, v0
	v_max_f32_e32 v2, 0, v0
	v_exp_f32_e64 v0, -v2
	v_add_f32_e32 v169, v169, v2
	v_sub_f32_e32 v111, v111, v2
	v_sub_f32_e32 v110, v110, v2
	v_pk_mul_f32 v[78:79], v[78:79], v[0:1] op_sel_hi:[1,0]
	v_pk_mul_f32 v[76:77], v[76:77], v[0:1] op_sel_hi:[1,0]
	v_pk_mul_f32 v[74:75], v[74:75], v[0:1] op_sel_hi:[1,0]
	v_pk_mul_f32 v[72:73], v[72:73], v[0:1] op_sel_hi:[1,0]
	v_pk_mul_f32 v[70:71], v[70:71], v[0:1] op_sel_hi:[1,0]
	v_pk_mul_f32 v[68:69], v[68:69], v[0:1] op_sel_hi:[1,0]
	v_pk_mul_f32 v[66:67], v[66:67], v[0:1] op_sel_hi:[1,0]
	v_pk_mul_f32 v[64:65], v[64:65], v[0:1] op_sel_hi:[1,0]
	v_pk_mul_f32 v[62:63], v[62:63], v[0:1] op_sel_hi:[1,0]
	v_pk_mul_f32 v[60:61], v[60:61], v[0:1] op_sel_hi:[1,0]
	v_pk_mul_f32 v[58:59], v[58:59], v[0:1] op_sel_hi:[1,0]
	v_pk_mul_f32 v[56:57], v[56:57], v[0:1] op_sel_hi:[1,0]
	v_pk_mul_f32 v[54:55], v[54:55], v[0:1] op_sel_hi:[1,0]
	v_pk_mul_f32 v[52:53], v[52:53], v[0:1] op_sel_hi:[1,0]
	v_pk_mul_f32 v[50:51], v[50:51], v[0:1] op_sel_hi:[1,0]
	v_pk_mul_f32 v[48:49], v[48:49], v[0:1] op_sel_hi:[1,0]
	v_pk_mul_f32 v[46:47], v[0:1], v[46:47] op_sel_hi:[0,1]
	v_pk_mul_f32 v[44:45], v[0:1], v[44:45] op_sel_hi:[0,1]
	v_pk_mul_f32 v[42:43], v[0:1], v[42:43] op_sel_hi:[0,1]
	v_pk_mul_f32 v[40:41], v[0:1], v[40:41] op_sel_hi:[0,1]
	v_pk_mul_f32 v[38:39], v[0:1], v[38:39] op_sel_hi:[0,1]
	v_pk_mul_f32 v[36:37], v[0:1], v[36:37] op_sel_hi:[0,1]
	v_pk_mul_f32 v[34:35], v[0:1], v[34:35] op_sel_hi:[0,1]
	v_pk_mul_f32 v[32:33], v[0:1], v[32:33] op_sel_hi:[0,1]
	v_pk_mul_f32 v[30:31], v[0:1], v[30:31] op_sel_hi:[0,1]
	v_pk_mul_f32 v[28:29], v[0:1], v[28:29] op_sel_hi:[0,1]
	v_pk_mul_f32 v[26:27], v[0:1], v[26:27] op_sel_hi:[0,1]
	v_pk_mul_f32 v[24:25], v[0:1], v[24:25] op_sel_hi:[0,1]
	v_pk_mul_f32 v[22:23], v[0:1], v[22:23] op_sel_hi:[0,1]
	v_pk_mul_f32 v[20:21], v[0:1], v[20:21] op_sel_hi:[0,1]
	v_pk_mul_f32 v[18:19], v[0:1], v[18:19] op_sel_hi:[0,1]
	v_pk_mul_f32 v[16:17], v[0:1], v[16:17] op_sel_hi:[0,1]
	v_sub_f32_e32 v109, v109, v2
	v_sub_f32_e32 v108, v108, v2
	v_sub_f32_e32 v107, v107, v2
	v_sub_f32_e32 v106, v106, v2
	v_sub_f32_e32 v105, v105, v2
	v_sub_f32_e32 v104, v104, v2
	v_sub_f32_e32 v103, v103, v2
	v_sub_f32_e32 v102, v102, v2
	v_sub_f32_e32 v101, v101, v2
	v_sub_f32_e32 v100, v100, v2
	v_sub_f32_e32 v99, v99, v2
	v_sub_f32_e32 v98, v98, v2
	v_sub_f32_e32 v97, v97, v2
	v_sub_f32_e32 v96, v96, v2
	v_sub_f32_e32 v95, v95, v2
	v_sub_f32_e32 v94, v94, v2
	v_sub_f32_e32 v93, v93, v2
	v_sub_f32_e32 v92, v92, v2
	v_sub_f32_e32 v91, v91, v2
	v_sub_f32_e32 v90, v90, v2
	v_sub_f32_e32 v89, v89, v2
	v_sub_f32_e32 v88, v88, v2
	v_sub_f32_e32 v87, v87, v2
	v_sub_f32_e32 v86, v86, v2
	v_sub_f32_e32 v85, v85, v2
	v_sub_f32_e32 v84, v84, v2
	v_sub_f32_e32 v83, v83, v2
	v_sub_f32_e32 v82, v82, v2
	v_sub_f32_e32 v81, v81, v2
	v_sub_f32_e32 v80, v80, v2
	v_mul_f32_e32 v184, v184, v0

.LBB0_641:
	s_add_i32 s19, s20, 0xffff0000
	s_and_b32 s19, s19, 0xc000
	s_add_i32 s28, s19, 0
	v_add_u32_e32 v0, s28, v210
	s_sub_i32 s30, s18, 64
	ds_read_b128 v[186:189], v0
	ds_read_b128 v[216:219], v0 offset:8192
	v_cvt_f32_i32_e32 v0, s30
	v_add_u32_e32 v112, s28, v211
	ds_read_b128 v[220:223], v112
	ds_read_b128 v[224:227], v112 offset:8192
	s_add_i32 s21, s20, 0xfffec000
	v_sub_f32_e32 v0, v0, v205
	v_fma_f32 v112, v0, -v166, -v169
	v_add_f32_e32 v128, v15, v112
	v_add_f32_e32 v116, v14, v112
	v_add_f32_e32 v132, v14, v128
	v_add_f32_e32 v120, v14, v116
	v_add_f32_e32 v136, v14, v132
	v_add_f32_e32 v124, v14, v120
	v_add_f32_e32 v140, v14, v136
	v_sub_f32_e32 v113, v112, v166
	v_sub_f32_e32 v129, v128, v166
	v_sub_f32_e32 v117, v116, v166
	v_sub_f32_e32 v133, v132, v166
	v_sub_f32_e32 v121, v120, v166
	v_sub_f32_e32 v137, v136, v166
	v_sub_f32_e32 v125, v124, v166
	v_sub_f32_e32 v141, v140, v166
	v_add_f32_e32 v114, v2, v112
	v_add_f32_e32 v115, v3, v112
	v_add_f32_e32 v130, v2, v128
	v_add_f32_e32 v131, v3, v128
	v_add_f32_e32 v118, v2, v116
	v_add_f32_e32 v119, v3, v116
	v_add_f32_e32 v134, v2, v132
	v_add_f32_e32 v135, v3, v132
	v_add_f32_e32 v122, v2, v120
	v_add_f32_e32 v123, v3, v120
	v_add_f32_e32 v138, v2, v136
	v_add_f32_e32 v139, v3, v136
	v_add_f32_e32 v126, v2, v124
	v_add_f32_e32 v127, v3, v124
	v_add_f32_e32 v142, v2, v140
	v_add_f32_e32 v143, v3, v140
	s_waitcnt lgkmcnt(3)
	v_mfma_f32_32x32x16_bf16 v[112:127], v[186:189], v[144:147], v[112:127]
	v_add_u32_e32 v0, s28, v212
	ds_read_b128 v[228:231], v0
	ds_read_b128 v[232:235], v0 offset:8192
	v_add_u32_e32 v0, s28, v213
	ds_read_b128 v[186:189], v0
	ds_read_b128 v[236:239], v0 offset:8192
	s_and_b32 s21, s21, 0xc000
	v_add_u32_e32 v0, s21, v204
	ds_read_b128 v[240:243], v0
	ds_read_b128 v[244:247], v0 offset:4096
	s_waitcnt lgkmcnt(8)
	v_mfma_f32_32x32x16_bf16 v[128:143], v[216:219], v[144:147], v[128:143]
	ds_read_b128 v[216:219], v0 offset:8192
	ds_read_b128 v[248:251], v0 offset:12288
	v_exp_f32_e32 v96, v96
	v_exp_f32_e32 v165, v80
	v_exp_f32_e32 v160, v97
	v_exp_f32_e32 v0, v81
	v_exp_f32_e32 v81, v98
	v_exp_f32_e32 v97, v82
	s_waitcnt lgkmcnt(9)
	v_mfma_f32_32x32x16_bf16 v[112:127], v[220:223], v[148:151], v[112:127]
	v_exp_f32_e32 v82, v100
	v_exp_f32_e32 v98, v84
	v_exp_f32_e32 v162, v99
	v_exp_f32_e32 v164, v83
	v_exp_f32_e32 v83, v102
	v_exp_f32_e32 v99, v86
	v_exp_f32_e32 v182, v101
	s_waitcnt lgkmcnt(8)
	v_mfma_f32_32x32x16_bf16 v[128:143], v[224:227], v[148:151], v[128:143]
	v_exp_f32_e32 v190, v85
	v_exp_f32_e32 v84, v104
	v_exp_f32_e32 v100, v88
	v_exp_f32_e32 v196, v103
	v_exp_f32_e32 v198, v87
	v_exp_f32_e32 v200, v105
	v_exp_f32_e32 v220, v89
	s_waitcnt lgkmcnt(7)
	v_mfma_f32_32x32x16_bf16 v[112:127], v[228:231], v[152:155], v[112:127]
	v_exp_f32_e32 v85, v106
	v_exp_f32_e32 v101, v90
	v_exp_f32_e32 v86, v108
	v_exp_f32_e32 v102, v92
	v_exp_f32_e32 v87, v110
	v_exp_f32_e32 v103, v94
	v_exp_f32_e32 v222, v109
	s_waitcnt lgkmcnt(6)
	v_mfma_f32_32x32x16_bf16 v[128:143], v[232:235], v[152:155], v[128:143]
	v_exp_f32_e32 v224, v93
	v_exp_f32_e32 v226, v111
	v_exp_f32_e32 v228, v95
	v_add_f32_e32 v161, v96, v165
	v_add_f32_e32 v163, v81, v97
	v_add_f32_e32 v183, v82, v98
	v_add_f32_e32 v197, v83, v99
	s_waitcnt lgkmcnt(5)
	v_mfma_f32_32x32x16_bf16 v[112:127], v[186:189], v[156:159], v[112:127]
	v_exp_f32_e32 v186, v107
	v_exp_f32_e32 v188, v91
	v_add_f32_e32 v201, v84, v100
	v_add_f32_e32 v187, v85, v101
	v_add_f32_e32 v223, v86, v102
	v_add_f32_e32 v227, v87, v103
	v_cvt_pk_bf16_f32 v80, v96, v160
	s_waitcnt lgkmcnt(4)
	v_mfma_f32_32x32x16_bf16 v[128:143], v[236:239], v[156:159], v[128:143]
	v_cvt_pk_bf16_f32 v81, v81, v162
	v_cvt_pk_bf16_f32 v82, v82, v182
	v_cvt_pk_bf16_f32 v83, v83, v196
	v_cvt_pk_bf16_f32 v84, v84, v200
	v_cvt_pk_bf16_f32 v85, v85, v186
	v_cvt_pk_bf16_f32 v86, v86, v222
	v_cvt_pk_bf16_f32 v87, v87, v226
	v_cvt_pk_bf16_f32 v88, v165, v0
	v_cvt_pk_bf16_f32 v89, v97, v164
	v_cvt_pk_bf16_f32 v90, v98, v190
	v_cvt_pk_bf16_f32 v91, v99, v198
	v_cvt_pk_bf16_f32 v92, v100, v220
	v_cvt_pk_bf16_f32 v93, v101, v188
	v_cvt_pk_bf16_f32 v94, v102, v224
	v_cvt_pk_bf16_f32 v95, v103, v228
	v_add_f32_e32 v160, v160, v0
	v_add_f32_e32 v161, v161, v1
	v_add_u32_e32 v108, s21, v167
	v_add_f32_e32 v161, v160, v161
	v_mov_b32_e32 v165, v161
	v_add_f32_e32 v160, v162, v164
	v_add_f32_e32 v161, v163, v165
	s_waitcnt lgkmcnt(3)
	v_mfma_f32_32x32x16_bf16 v[64:79], v[240:243], v[80:83], v[64:79]
	v_add_f32_e32 v161, v160, v161
	v_mov_b32_e32 v191, v161
	v_add_f32_e32 v160, v182, v190
	v_add_f32_e32 v161, v183, v191
	ds_read_b128 v[96:99], v108
	ds_read_b128 v[100:103], v108 offset:4096
	ds_read_b128 v[104:107], v108 offset:8192
	ds_read_b128 v[108:111], v108 offset:12288
	v_add_f32_e32 v161, v160, v161
	v_mov_b32_e32 v199, v161
	v_add_f32_e32 v160, v196, v198
	v_add_f32_e32 v161, v197, v199
	s_waitcnt lgkmcnt(6)
	v_mfma_f32_32x32x16_bf16 v[48:63], v[244:247], v[80:83], v[48:63]
	v_add_f32_e32 v161, v160, v161
	v_mov_b32_e32 v221, v161
	v_add_f32_e32 v160, v200, v220
	v_add_f32_e32 v161, v201, v221
	s_nop 0
	v_add_f32_e32 v161, v160, v161
	v_mov_b32_e32 v189, v161
	v_add_f32_e32 v160, v186, v188
	v_add_f32_e32 v161, v187, v189
	s_waitcnt lgkmcnt(5)
	v_mfma_f32_32x32x16_bf16 v[32:47], v[216:219], v[80:83], v[32:47]
	v_add_f32_e32 v161, v160, v161
	v_mov_b32_e32 v225, v161
	v_add_f32_e32 v160, v222, v224
	v_add_f32_e32 v161, v223, v225
	s_nop 0
	v_add_f32_e32 v161, v160, v161
	v_mov_b32_e32 v229, v161
	v_add_f32_e32 v160, v226, v228
	v_add_f32_e32 v161, v227, v229
	s_waitcnt lgkmcnt(4)
	v_mfma_f32_32x32x16_bf16 v[16:31], v[248:251], v[80:83], v[16:31]
	v_add_f32_e32 v0, v160, v161
	v_add_f32_e32 v178, v184, v0
	s_waitcnt lgkmcnt(3)
	v_mfma_f32_32x32x16_bf16 v[64:79], v[96:99], v[84:87], v[64:79]
	v_add_u32_e32 v0, s21, v168
	s_waitcnt lgkmcnt(2)
	v_mfma_f32_32x32x16_bf16 v[48:63], v[100:103], v[84:87], v[48:63]
	s_waitcnt lgkmcnt(1)
	v_mfma_f32_32x32x16_bf16 v[32:47], v[104:107], v[84:87], v[32:47]
	ds_read_b128 v[80:83], v0
	ds_read_b128 v[96:99], v0 offset:4096
	ds_read_b128 v[100:103], v0 offset:8192
	ds_read_b128 v[104:107], v0 offset:12288
	s_waitcnt lgkmcnt(4)
	v_mfma_f32_32x32x16_bf16 v[16:31], v[108:111], v[84:87], v[16:31]
	v_add_u32_e32 v0, s21, v180
	ds_read_b128 v[84:87], v0
	ds_read_b128 v[108:111], v0 offset:4096
	s_waitcnt lgkmcnt(5)
	v_mfma_f32_32x32x16_bf16 v[64:79], v[80:83], v[88:91], v[64:79]
	ds_read_b128 v[80:83], v0 offset:8192
	ds_read_b128 v[182:185], v0 offset:12288
	v_max_f32_e32 v0, v113, v113
	v_max_f32_e32 v160, v129, v129
	v_max_f32_e32 v0, v0, v160
	v_max3_f32 v160, v112, v128, v114
	v_max3_f32 v0, v0, v115, v131
	v_max3_f32 v160, v160, v130, v116
	v_max3_f32 v0, v0, v117, v133
	s_waitcnt lgkmcnt(6)
	v_mfma_f32_32x32x16_bf16 v[48:63], v[96:99], v[88:91], v[48:63]
	v_max3_f32 v96, v160, v132, v118
	v_max3_f32 v0, v0, v119, v135
	v_max3_f32 v96, v96, v134, v120
	v_max3_f32 v0, v0, v121, v137
	v_max3_f32 v96, v96, v136, v122
	v_max3_f32 v0, v0, v123, v139
	v_max3_f32 v96, v96, v138, v124
	s_waitcnt lgkmcnt(5)
	v_mfma_f32_32x32x16_bf16 v[32:47], v[100:103], v[88:91], v[32:47]
	v_max3_f32 v0, v0, v125, v141
	v_max3_f32 v96, v96, v140, v126
	v_max3_f32 v0, v0, v127, v143
	v_max3_f32 v0, v96, v142, v0
	v_mov_b32_e32 v96, v0
	s_nop 1
	v_permlane32_swap_b32_e32 v0, v96
	s_waitcnt lgkmcnt(4)
	v_mfma_f32_32x32x16_bf16 v[16:31], v[104:107], v[88:91], v[16:31]
	s_waitcnt lgkmcnt(3)
	v_mfma_f32_32x32x16_bf16 v[64:79], v[84:87], v[92:95], v[64:79]
	v_max_f32_e32 v0, v0, v0
	s_waitcnt lgkmcnt(2)
	v_mfma_f32_32x32x16_bf16 v[48:63], v[108:111], v[92:95], v[48:63]
	s_waitcnt lgkmcnt(1)
	v_mfma_f32_32x32x16_bf16 v[32:47], v[80:83], v[92:95], v[32:47]
	v_max_f32_e32 v80, v96, v96
	v_max_f32_e32 v0, v0, v80
	v_cmp_lt_f32_e32 vcc, s93, v0
	s_waitcnt lgkmcnt(0)
	v_mfma_f32_32x32x16_bf16 v[16:31], v[182:185], v[92:95], v[16:31]
	s_cbranch_vccz .LBB0_643
	v_max_f32_e32 v0, v0, v0
	v_max_f32_e32 v80, 0, v0
	v_exp_f32_e64 v0, -v80
	v_add_f32_e32 v169, v169, v80
	v_sub_f32_e32 v127, v127, v80
	v_sub_f32_e32 v126, v126, v80
	v_pk_mul_f32 v[78:79], v[78:79], v[0:1] op_sel_hi:[1,0]
	v_pk_mul_f32 v[76:77], v[76:77], v[0:1] op_sel_hi:[1,0]
	v_pk_mul_f32 v[74:75], v[74:75], v[0:1] op_sel_hi:[1,0]
	v_pk_mul_f32 v[72:73], v[72:73], v[0:1] op_sel_hi:[1,0]
	v_pk_mul_f32 v[70:71], v[70:71], v[0:1] op_sel_hi:[1,0]
	v_pk_mul_f32 v[68:69], v[68:69], v[0:1] op_sel_hi:[1,0]
	v_pk_mul_f32 v[66:67], v[66:67], v[0:1] op_sel_hi:[1,0]
	v_pk_mul_f32 v[64:65], v[64:65], v[0:1] op_sel_hi:[1,0]
	v_pk_mul_f32 v[62:63], v[62:63], v[0:1] op_sel_hi:[1,0]
	v_pk_mul_f32 v[60:61], v[60:61], v[0:1] op_sel_hi:[1,0]
	v_pk_mul_f32 v[58:59], v[58:59], v[0:1] op_sel_hi:[1,0]
	v_pk_mul_f32 v[56:57], v[56:57], v[0:1] op_sel_hi:[1,0]
	v_pk_mul_f32 v[54:55], v[54:55], v[0:1] op_sel_hi:[1,0]
	v_pk_mul_f32 v[52:53], v[52:53], v[0:1] op_sel_hi:[1,0]
	v_pk_mul_f32 v[50:51], v[50:51], v[0:1] op_sel_hi:[1,0]
	v_pk_mul_f32 v[48:49], v[48:49], v[0:1] op_sel_hi:[1,0]
	v_pk_mul_f32 v[46:47], v[0:1], v[46:47] op_sel_hi:[0,1]
	v_pk_mul_f32 v[44:45], v[0:1], v[44:45] op_sel_hi:[0,1]
	v_pk_mul_f32 v[42:43], v[0:1], v[42:43] op_sel_hi:[0,1]
	v_pk_mul_f32 v[40:41], v[0:1], v[40:41] op_sel_hi:[0,1]
	v_pk_mul_f32 v[38:39], v[0:1], v[38:39] op_sel_hi:[0,1]
	v_pk_mul_f32 v[36:37], v[0:1], v[36:37] op_sel_hi:[0,1]
	v_pk_mul_f32 v[34:35], v[0:1], v[34:35] op_sel_hi:[0,1]
	v_pk_mul_f32 v[32:33], v[0:1], v[32:33] op_sel_hi:[0,1]
	v_pk_mul_f32 v[30:31], v[0:1], v[30:31] op_sel_hi:[0,1]
	v_pk_mul_f32 v[28:29], v[0:1], v[28:29] op_sel_hi:[0,1]
	v_pk_mul_f32 v[26:27], v[0:1], v[26:27] op_sel_hi:[0,1]
	v_pk_mul_f32 v[24:25], v[0:1], v[24:25] op_sel_hi:[0,1]
	v_pk_mul_f32 v[22:23], v[0:1], v[22:23] op_sel_hi:[0,1]
	v_pk_mul_f32 v[20:21], v[0:1], v[20:21] op_sel_hi:[0,1]
	v_pk_mul_f32 v[18:19], v[0:1], v[18:19] op_sel_hi:[0,1]
	v_pk_mul_f32 v[16:17], v[0:1], v[16:17] op_sel_hi:[0,1]
	v_sub_f32_e32 v125, v125, v80
	v_sub_f32_e32 v124, v124, v80
	v_sub_f32_e32 v123, v123, v80
	v_sub_f32_e32 v122, v122, v80
	v_sub_f32_e32 v121, v121, v80
	v_sub_f32_e32 v120, v120, v80
	v_sub_f32_e32 v119, v119, v80
	v_sub_f32_e32 v118, v118, v80
	v_sub_f32_e32 v117, v117, v80
	v_sub_f32_e32 v116, v116, v80
	v_sub_f32_e32 v115, v115, v80
	v_sub_f32_e32 v114, v114, v80
	v_sub_f32_e32 v113, v113, v80
	v_sub_f32_e32 v112, v112, v80
	v_sub_f32_e32 v143, v143, v80
	v_sub_f32_e32 v142, v142, v80
	v_sub_f32_e32 v141, v141, v80
	v_sub_f32_e32 v140, v140, v80
	v_sub_f32_e32 v139, v139, v80
	v_sub_f32_e32 v138, v138, v80
	v_sub_f32_e32 v137, v137, v80
	v_sub_f32_e32 v136, v136, v80
	v_sub_f32_e32 v135, v135, v80
	v_sub_f32_e32 v134, v134, v80
	v_sub_f32_e32 v133, v133, v80
	v_sub_f32_e32 v132, v132, v80
	v_sub_f32_e32 v131, v131, v80
	v_sub_f32_e32 v130, v130, v80
	v_sub_f32_e32 v129, v129, v80
	v_sub_f32_e32 v128, v128, v80
	v_mul_f32_e32 v178, v178, v0

.LBB0_653:
	s_add_i32 s21, s20, 0xffff4000
	s_and_b32 s21, s21, 0xc000
	s_add_i32 s21, s21, 0
	v_add_u32_e32 v0, s21, v210
	ds_read_b128 v[8:11], v0
	ds_read_b128 v[182:185], v0 offset:8192
	v_cvt_f32_i32_e32 v0, s18
	v_add_u32_e32 v80, s21, v211
	ds_read_b128 v[186:189], v80
	ds_read_b128 v[216:219], v80 offset:8192
	v_sub_f32_e32 v0, v0, v205
	v_fma_f32 v96, v0, -v166, -v169
	v_add_f32_e32 v80, v15, v96
	v_add_f32_e32 v100, v14, v96
	v_add_f32_e32 v84, v14, v80
	v_add_f32_e32 v104, v14, v100
	v_add_f32_e32 v88, v14, v84
	v_add_f32_e32 v108, v14, v104
	v_add_f32_e32 v92, v14, v88
	v_sub_f32_e32 v97, v96, v166
	v_sub_f32_e32 v81, v80, v166
	v_sub_f32_e32 v101, v100, v166
	v_sub_f32_e32 v85, v84, v166
	v_sub_f32_e32 v105, v104, v166
	v_sub_f32_e32 v89, v88, v166
	v_sub_f32_e32 v109, v108, v166
	v_sub_f32_e32 v93, v92, v166
	v_add_f32_e32 v98, v2, v96
	v_add_f32_e32 v99, v3, v96
	v_add_f32_e32 v82, v2, v80
	v_add_f32_e32 v83, v3, v80
	v_add_f32_e32 v102, v2, v100
	v_add_f32_e32 v103, v3, v100
	v_add_f32_e32 v86, v2, v84
	v_add_f32_e32 v87, v3, v84
	v_add_f32_e32 v106, v2, v104
	v_add_f32_e32 v107, v3, v104
	v_add_f32_e32 v90, v2, v88
	v_add_f32_e32 v91, v3, v88
	v_add_f32_e32 v110, v2, v108
	v_add_f32_e32 v111, v3, v108
	v_add_f32_e32 v94, v2, v92
	v_add_f32_e32 v95, v3, v92
	s_waitcnt lgkmcnt(3)
	v_mfma_f32_32x32x16_bf16 v[96:111], v[8:11], v[144:147], v[96:111]
	v_add_u32_e32 v0, s21, v212
	ds_read_b128 v[220:223], v0
	ds_read_b128 v[224:227], v0 offset:8192
	v_add_u32_e32 v0, s21, v213
	ds_read_b128 v[228:231], v0
	ds_read_b128 v[232:235], v0 offset:8192
	v_add_u32_e32 v0, s19, v204
	ds_read_b128 v[8:11], v0
	ds_read_b128 v[236:239], v0 offset:4096
	ds_read_b128 v[240:243], v0 offset:8192
	ds_read_b128 v[244:247], v0 offset:12288
	s_waitcnt lgkmcnt(10)
	v_mfma_f32_32x32x16_bf16 v[80:95], v[182:185], v[144:147], v[80:95]
	v_exp_f32_e32 v112, v112
	v_exp_f32_e32 v128, v128
	v_exp_f32_e32 v0, v113
	v_exp_f32_e32 v160, v129
	v_exp_f32_e32 v113, v114
	v_exp_f32_e32 v129, v130
	v_exp_f32_e32 v114, v116
	s_waitcnt lgkmcnt(9)
	v_mfma_f32_32x32x16_bf16 v[96:111], v[186:189], v[148:151], v[96:111]
	v_exp_f32_e32 v130, v132
	v_exp_f32_e32 v164, v115
	v_exp_f32_e32 v162, v131
	v_exp_f32_e32 v115, v118
	v_exp_f32_e32 v131, v134
	v_exp_f32_e32 v184, v117
	v_exp_f32_e32 v182, v133
	s_waitcnt lgkmcnt(8)
	v_mfma_f32_32x32x16_bf16 v[80:95], v[216:219], v[148:151], v[80:95]
	v_exp_f32_e32 v188, v119
	v_exp_f32_e32 v186, v135
	v_exp_f32_e32 v116, v120
	v_exp_f32_e32 v132, v136
	v_exp_f32_e32 v117, v122
	v_exp_f32_e32 v133, v138
	v_exp_f32_e32 v196, v121
	s_waitcnt lgkmcnt(7)
	v_mfma_f32_32x32x16_bf16 v[96:111], v[220:223], v[152:155], v[96:111]
	v_exp_f32_e32 v190, v137
	v_exp_f32_e32 v118, v124
	v_exp_f32_e32 v134, v140
	v_exp_f32_e32 v200, v123
	v_exp_f32_e32 v198, v139
	v_exp_f32_e32 v119, v126
	v_exp_f32_e32 v135, v142
	s_waitcnt lgkmcnt(6)
	v_mfma_f32_32x32x16_bf16 v[80:95], v[224:227], v[152:155], v[80:95]
	v_exp_f32_e32 v218, v125
	v_exp_f32_e32 v216, v141
	v_exp_f32_e32 v222, v127
	v_exp_f32_e32 v220, v143
	v_add_f32_e32 v161, v128, v112
	v_add_f32_e32 v163, v129, v113
	v_add_f32_e32 v183, v130, v114
	s_waitcnt lgkmcnt(5)
	v_mfma_f32_32x32x16_bf16 v[96:111], v[228:231], v[156:159], v[96:111]
	v_add_f32_e32 v187, v131, v115
	v_add_f32_e32 v191, v132, v116
	v_add_f32_e32 v199, v133, v117
	v_add_f32_e32 v217, v134, v118
	v_add_f32_e32 v221, v135, v119
	v_cvt_pk_bf16_f32 v112, v112, v0
	v_cvt_pk_bf16_f32 v113, v113, v164
	s_waitcnt lgkmcnt(4)
	v_mfma_f32_32x32x16_bf16 v[80:95], v[232:235], v[156:159], v[80:95]
	v_cvt_pk_bf16_f32 v114, v114, v184
	v_cvt_pk_bf16_f32 v115, v115, v188
	v_cvt_pk_bf16_f32 v116, v116, v196
	v_cvt_pk_bf16_f32 v117, v117, v200
	v_cvt_pk_bf16_f32 v118, v118, v218
	v_cvt_pk_bf16_f32 v119, v119, v222
	v_cvt_pk_bf16_f32 v120, v128, v160
	v_cvt_pk_bf16_f32 v121, v129, v162
	v_cvt_pk_bf16_f32 v122, v130, v182
	v_cvt_pk_bf16_f32 v123, v131, v186
	v_cvt_pk_bf16_f32 v124, v132, v190
	v_cvt_pk_bf16_f32 v125, v133, v198
	v_cvt_pk_bf16_f32 v126, v134, v216
	v_cvt_pk_bf16_f32 v127, v135, v220
	v_add_f32_e32 v160, v160, v0
	v_add_f32_e32 v161, v161, v1
	s_waitcnt lgkmcnt(3)
	v_mfma_f32_32x32x16_bf16 v[64:79], v[8:11], v[112:115], v[64:79]
	v_add_f32_e32 v161, v160, v161
	v_mov_b32_e32 v165, v161
	v_add_f32_e32 v8, v162, v164
	v_add_f32_e32 v9, v163, v165
	v_add_u32_e32 v140, s19, v167
	v_add_f32_e32 v9, v8, v9
	v_mov_b32_e32 v185, v9
	v_add_f32_e32 v8, v182, v184
	v_add_f32_e32 v9, v183, v185
	s_waitcnt lgkmcnt(2)
	v_mfma_f32_32x32x16_bf16 v[48:63], v[236:239], v[112:115], v[48:63]
	v_add_f32_e32 v9, v8, v9
	v_mov_b32_e32 v189, v9
	v_add_f32_e32 v8, v186, v188
	v_add_f32_e32 v9, v187, v189
	ds_read_b128 v[128:131], v140
	ds_read_b128 v[132:135], v140 offset:4096
	ds_read_b128 v[136:139], v140 offset:8192
	ds_read_b128 v[140:143], v140 offset:12288
	v_add_f32_e32 v9, v8, v9
	v_mov_b32_e32 v197, v9
	v_add_f32_e32 v8, v190, v196
	v_add_f32_e32 v9, v191, v197
	s_waitcnt lgkmcnt(5)
	v_mfma_f32_32x32x16_bf16 v[32:47], v[240:243], v[112:115], v[32:47]
	v_add_f32_e32 v9, v8, v9
	v_mov_b32_e32 v201, v9
	v_add_f32_e32 v8, v198, v200
	v_add_f32_e32 v9, v199, v201
	s_nop 0
	v_add_f32_e32 v9, v8, v9
	v_mov_b32_e32 v219, v9
	v_add_f32_e32 v8, v216, v218
	v_add_f32_e32 v9, v217, v219
	s_waitcnt lgkmcnt(4)
	v_mfma_f32_32x32x16_bf16 v[16:31], v[244:247], v[112:115], v[16:31]
	v_add_f32_e32 v9, v8, v9
	v_mov_b32_e32 v223, v9
	v_add_f32_e32 v8, v220, v222
	v_add_f32_e32 v9, v221, v223
	s_nop 0
	v_add_f32_e32 v0, v8, v9
	v_add_f32_e32 v184, v178, v0
	s_waitcnt lgkmcnt(3)
	v_mfma_f32_32x32x16_bf16 v[64:79], v[128:131], v[116:119], v[64:79]
	v_add_u32_e32 v0, s19, v168
	s_waitcnt lgkmcnt(2)
	v_mfma_f32_32x32x16_bf16 v[48:63], v[132:135], v[116:119], v[48:63]
	ds_read_b128 v[8:11], v0
	ds_read_b128 v[112:115], v0 offset:4096
	ds_read_b128 v[128:131], v0 offset:8192
	ds_read_b128 v[132:135], v0 offset:12288
	s_waitcnt lgkmcnt(5)
	v_mfma_f32_32x32x16_bf16 v[32:47], v[136:139], v[116:119], v[32:47]
	s_waitcnt lgkmcnt(4)
	v_mfma_f32_32x32x16_bf16 v[16:31], v[140:143], v[116:119], v[16:31]
	v_add_u32_e32 v0, s19, v180
	ds_read_b128 v[116:119], v0
	ds_read_b128 v[136:139], v0 offset:4096
	s_waitcnt lgkmcnt(5)
	v_mfma_f32_32x32x16_bf16 v[64:79], v[8:11], v[120:123], v[64:79]
	ds_read_b128 v[8:11], v0 offset:8192
	ds_read_b128 v[140:143], v0 offset:12288
	v_max_f32_e32 v0, v97, v97
	v_max_f32_e32 v160, v81, v81
	v_max_f32_e32 v0, v0, v160
	v_max3_f32 v160, v96, v80, v98
	v_max3_f32 v0, v0, v99, v83
	v_max3_f32 v160, v160, v82, v100
	v_max3_f32 v0, v0, v101, v85
	s_waitcnt lgkmcnt(6)
	v_mfma_f32_32x32x16_bf16 v[48:63], v[112:115], v[120:123], v[48:63]
	v_max3_f32 v112, v160, v84, v102
	v_max3_f32 v0, v0, v103, v87
	v_max3_f32 v112, v112, v86, v104
	v_max3_f32 v0, v0, v105, v89
	v_max3_f32 v112, v112, v88, v106
	v_max3_f32 v0, v0, v107, v91
	v_max3_f32 v112, v112, v90, v108
	s_waitcnt lgkmcnt(5)
	v_mfma_f32_32x32x16_bf16 v[32:47], v[128:131], v[120:123], v[32:47]
	v_max3_f32 v0, v0, v109, v93
	v_max3_f32 v112, v112, v92, v110
	v_max3_f32 v0, v0, v111, v95
	v_max3_f32 v0, v112, v94, v0
	v_mov_b32_e32 v112, v0
	s_nop 1
	v_permlane32_swap_b32_e32 v0, v112
	s_waitcnt lgkmcnt(4)
	v_mfma_f32_32x32x16_bf16 v[16:31], v[132:135], v[120:123], v[16:31]
	s_waitcnt lgkmcnt(3)
	v_mfma_f32_32x32x16_bf16 v[64:79], v[116:119], v[124:127], v[64:79]
	v_max_f32_e32 v0, v0, v0
	s_waitcnt lgkmcnt(2)
	v_mfma_f32_32x32x16_bf16 v[48:63], v[136:139], v[124:127], v[48:63]
	s_waitcnt lgkmcnt(1)
	v_mfma_f32_32x32x16_bf16 v[32:47], v[8:11], v[124:127], v[32:47]
	v_max_f32_e32 v8, v112, v112
	v_max_f32_e32 v0, v0, v8
	v_cmp_lt_f32_e32 vcc, s93, v0
	s_waitcnt lgkmcnt(0)
	v_mfma_f32_32x32x16_bf16 v[16:31], v[140:143], v[124:127], v[16:31]
	s_cbranch_vccz .LBB0_655
	v_max_f32_e32 v0, v0, v0
	v_max_f32_e32 v8, 0, v0
	v_exp_f32_e64 v0, -v8
	v_add_f32_e32 v169, v169, v8
	v_sub_f32_e32 v111, v111, v8
	v_sub_f32_e32 v110, v110, v8
	v_pk_mul_f32 v[78:79], v[78:79], v[0:1] op_sel_hi:[1,0]
	v_pk_mul_f32 v[76:77], v[76:77], v[0:1] op_sel_hi:[1,0]
	v_pk_mul_f32 v[74:75], v[74:75], v[0:1] op_sel_hi:[1,0]
	v_pk_mul_f32 v[72:73], v[72:73], v[0:1] op_sel_hi:[1,0]
	v_pk_mul_f32 v[70:71], v[70:71], v[0:1] op_sel_hi:[1,0]
	v_pk_mul_f32 v[68:69], v[68:69], v[0:1] op_sel_hi:[1,0]
	v_pk_mul_f32 v[66:67], v[66:67], v[0:1] op_sel_hi:[1,0]
	v_pk_mul_f32 v[64:65], v[64:65], v[0:1] op_sel_hi:[1,0]
	v_pk_mul_f32 v[62:63], v[62:63], v[0:1] op_sel_hi:[1,0]
	v_pk_mul_f32 v[60:61], v[60:61], v[0:1] op_sel_hi:[1,0]
	v_pk_mul_f32 v[58:59], v[58:59], v[0:1] op_sel_hi:[1,0]
	v_pk_mul_f32 v[56:57], v[56:57], v[0:1] op_sel_hi:[1,0]
	v_pk_mul_f32 v[54:55], v[54:55], v[0:1] op_sel_hi:[1,0]
	v_pk_mul_f32 v[52:53], v[52:53], v[0:1] op_sel_hi:[1,0]
	v_pk_mul_f32 v[50:51], v[50:51], v[0:1] op_sel_hi:[1,0]
	v_pk_mul_f32 v[48:49], v[48:49], v[0:1] op_sel_hi:[1,0]
	v_pk_mul_f32 v[46:47], v[0:1], v[46:47] op_sel_hi:[0,1]
	v_pk_mul_f32 v[44:45], v[0:1], v[44:45] op_sel_hi:[0,1]
	v_pk_mul_f32 v[42:43], v[0:1], v[42:43] op_sel_hi:[0,1]
	v_pk_mul_f32 v[40:41], v[0:1], v[40:41] op_sel_hi:[0,1]
	v_pk_mul_f32 v[38:39], v[0:1], v[38:39] op_sel_hi:[0,1]
	v_pk_mul_f32 v[36:37], v[0:1], v[36:37] op_sel_hi:[0,1]
	v_pk_mul_f32 v[34:35], v[0:1], v[34:35] op_sel_hi:[0,1]
	v_pk_mul_f32 v[32:33], v[0:1], v[32:33] op_sel_hi:[0,1]
	v_pk_mul_f32 v[30:31], v[0:1], v[30:31] op_sel_hi:[0,1]
	v_pk_mul_f32 v[28:29], v[0:1], v[28:29] op_sel_hi:[0,1]
	v_pk_mul_f32 v[26:27], v[0:1], v[26:27] op_sel_hi:[0,1]
	v_pk_mul_f32 v[24:25], v[0:1], v[24:25] op_sel_hi:[0,1]
	v_pk_mul_f32 v[22:23], v[0:1], v[22:23] op_sel_hi:[0,1]
	v_pk_mul_f32 v[20:21], v[0:1], v[20:21] op_sel_hi:[0,1]
	v_pk_mul_f32 v[18:19], v[0:1], v[18:19] op_sel_hi:[0,1]
	v_pk_mul_f32 v[16:17], v[0:1], v[16:17] op_sel_hi:[0,1]
	v_sub_f32_e32 v109, v109, v8
	v_sub_f32_e32 v108, v108, v8
	v_sub_f32_e32 v107, v107, v8
	v_sub_f32_e32 v106, v106, v8
	v_sub_f32_e32 v105, v105, v8
	v_sub_f32_e32 v104, v104, v8
	v_sub_f32_e32 v103, v103, v8
	v_sub_f32_e32 v102, v102, v8
	v_sub_f32_e32 v101, v101, v8
	v_sub_f32_e32 v100, v100, v8
	v_sub_f32_e32 v99, v99, v8
	v_sub_f32_e32 v98, v98, v8
	v_sub_f32_e32 v97, v97, v8
	v_sub_f32_e32 v96, v96, v8
	v_sub_f32_e32 v95, v95, v8
	v_sub_f32_e32 v94, v94, v8
	v_sub_f32_e32 v93, v93, v8
	v_sub_f32_e32 v92, v92, v8
	v_sub_f32_e32 v91, v91, v8
	v_sub_f32_e32 v90, v90, v8
	v_sub_f32_e32 v89, v89, v8
	v_sub_f32_e32 v88, v88, v8
	v_sub_f32_e32 v87, v87, v8
	v_sub_f32_e32 v86, v86, v8
	v_sub_f32_e32 v85, v85, v8
	v_sub_f32_e32 v84, v84, v8
	v_sub_f32_e32 v83, v83, v8
	v_sub_f32_e32 v82, v82, v8
	v_sub_f32_e32 v81, v81, v8
	v_sub_f32_e32 v80, v80, v8
	v_mul_f32_e32 v184, v184, v0

.LBB0_661:
	s_andn2_b64 vcc, exec, s[12:13]
	s_cbranch_vccnz .LBB0_665
	v_sub_f32_e32 v0, 0x44f80000, v205
	v_fma_f32 v112, v0, -v166, -v169
	v_fma_f32 v0, 2.0, v2, v13
	ds_read_b128 v[4:7], v208 offset:49152
	ds_read_b128 v[8:11], v208 offset:57344
	ds_read_b128 v[170:173], v209 offset:49152
	ds_read_b128 v[174:177], v209 offset:57344
	v_fmac_f32_e32 v0, 2.0, v13
	v_fma_f32 v128, 2.0, v0, v112
	v_fma_f32 v116, 2.0, v13, v112
	v_fma_f32 v132, 2.0, v13, v128
	v_fma_f32 v120, 2.0, v13, v116
	v_fma_f32 v136, 2.0, v13, v132
	v_fma_f32 v124, 2.0, v13, v120
	v_fma_f32 v140, 2.0, v13, v136
	v_sub_f32_e32 v113, v112, v166
	v_sub_f32_e32 v129, v128, v166
	v_sub_f32_e32 v117, v116, v166
	v_sub_f32_e32 v133, v132, v166
	v_sub_f32_e32 v121, v120, v166
	v_sub_f32_e32 v137, v136, v166
	v_sub_f32_e32 v125, v124, v166
	v_sub_f32_e32 v141, v140, v166
	v_add_f32_e32 v114, v2, v112
	v_add_f32_e32 v115, v3, v112
	v_add_f32_e32 v130, v2, v128
	v_add_f32_e32 v131, v3, v128
	v_add_f32_e32 v118, v2, v116
	v_add_f32_e32 v119, v3, v116
	v_add_f32_e32 v134, v2, v132
	v_add_f32_e32 v135, v3, v132
	v_add_f32_e32 v122, v2, v120
	v_add_f32_e32 v123, v3, v120
	v_add_f32_e32 v138, v2, v136
	v_add_f32_e32 v139, v3, v136
	v_add_f32_e32 v126, v2, v124
	v_add_f32_e32 v127, v3, v124
	v_add_f32_e32 v142, v2, v140
	v_add_f32_e32 v143, v3, v140
	s_waitcnt lgkmcnt(3)
	v_mfma_f32_32x32x16_bf16 v[112:127], v[4:7], v[144:147], v[112:127]
	ds_read_b128 v[166:169], v206 offset:49152
	ds_read_b128 v[180:183], v206 offset:57344
	ds_read_b128 v[186:189], v207 offset:49152
	ds_read_b128 v[206:209], v207 offset:57344
	s_add_i32 s12, 0, 0x8000
	v_add_u32_e32 v0, s12, v214
	ds_read_b128 v[2:5], v0
	ds_read_b128 v[210:213], v0 offset:4096
	ds_read_b128 v[214:217], v0 offset:8192
	ds_read_b128 v[218:221], v0 offset:12288
	v_exp_f32_e32 v6, v96
	v_exp_f32_e32 v13, v80
	v_exp_f32_e32 v7, v98
	s_waitcnt lgkmcnt(10)
	v_mfma_f32_32x32x16_bf16 v[128:143], v[8:11], v[144:147], v[128:143]
	v_exp_f32_e32 v96, v82
	v_exp_f32_e32 v0, v97
	v_exp_f32_e32 v10, v81
	v_exp_f32_e32 v8, v100
	v_exp_f32_e32 v97, v84
	v_exp_f32_e32 v144, v99
	v_exp_f32_e32 v14, v83
	s_waitcnt lgkmcnt(9)
	v_mfma_f32_32x32x16_bf16 v[112:127], v[170:173], v[148:151], v[112:127]
	v_exp_f32_e32 v9, v102
	v_exp_f32_e32 v98, v86
	v_exp_f32_e32 v160, v101
	v_exp_f32_e32 v146, v85
	v_exp_f32_e32 v80, v104
	v_exp_f32_e32 v88, v88
	v_exp_f32_e32 v81, v106
	s_waitcnt lgkmcnt(8)
	v_mfma_f32_32x32x16_bf16 v[128:143], v[174:177], v[148:151], v[128:143]
	v_exp_f32_e32 v150, v103
	v_exp_f32_e32 v148, v87
	v_exp_f32_e32 v90, v90
	v_exp_f32_e32 v164, v105
	v_exp_f32_e32 v162, v89
	v_exp_f32_e32 v82, v108
	v_exp_f32_e32 v92, v92
	s_waitcnt lgkmcnt(7)
	v_mfma_f32_32x32x16_bf16 v[112:127], v[166:169], v[152:155], v[112:127]
	v_exp_f32_e32 v168, v107
	v_exp_f32_e32 v166, v91
	v_exp_f32_e32 v83, v110
	v_exp_f32_e32 v91, v94
	v_exp_f32_e32 v108, v109
	v_exp_f32_e32 v170, v93
	v_exp_f32_e32 v110, v111
	s_waitcnt lgkmcnt(6)
	v_mfma_f32_32x32x16_bf16 v[128:143], v[180:183], v[152:155], v[128:143]
	v_exp_f32_e32 v172, v95
	v_add_f32_e32 v11, v13, v6
	v_add_f32_e32 v15, v96, v7
	v_add_f32_e32 v147, v97, v8
	v_add_f32_e32 v149, v98, v9
	v_add_f32_e32 v163, v88, v80
	v_add_f32_e32 v167, v90, v81
	s_waitcnt lgkmcnt(5)
	v_mfma_f32_32x32x16_bf16 v[112:127], v[186:189], v[156:159], v[112:127]
	v_add_f32_e32 v171, v92, v82
	v_add_f32_e32 v173, v91, v83
	v_cvt_pk_bf16_f32 v6, v6, v0
	v_cvt_pk_bf16_f32 v7, v7, v144
	v_cvt_pk_bf16_f32 v8, v8, v160
	v_cvt_pk_bf16_f32 v9, v9, v150
	v_cvt_pk_bf16_f32 v80, v80, v164
	s_waitcnt lgkmcnt(4)
	v_mfma_f32_32x32x16_bf16 v[128:143], v[206:209], v[156:159], v[128:143]
	v_cvt_pk_bf16_f32 v81, v81, v168
	v_cvt_pk_bf16_f32 v82, v82, v108
	v_cvt_pk_bf16_f32 v83, v83, v110
	v_cvt_pk_bf16_f32 v84, v13, v10
	v_cvt_pk_bf16_f32 v85, v96, v14
	v_cvt_pk_bf16_f32 v86, v97, v146
	v_cvt_pk_bf16_f32 v87, v98, v148
	v_cvt_pk_bf16_f32 v88, v88, v162
	v_cvt_pk_bf16_f32 v89, v90, v166
	v_cvt_pk_bf16_f32 v90, v92, v170
	v_cvt_pk_bf16_f32 v91, v91, v172
	v_add_f32_e32 v10, v10, v0
	v_add_f32_e32 v11, v11, v1
	s_waitcnt lgkmcnt(3)
	v_mfma_f32_32x32x16_bf16 v[64:79], v[2:5], v[6:9], v[64:79]
	v_add_f32_e32 v11, v10, v11
	v_mov_b32_e32 v145, v11
	v_add_f32_e32 v2, v14, v144
	v_add_f32_e32 v3, v15, v145
	v_add_u32_e32 v13, s12, v203
	v_add_f32_e32 v3, v2, v3
	v_mov_b32_e32 v161, v3
	v_add_f32_e32 v2, v146, v160
	v_add_f32_e32 v3, v147, v161
	s_waitcnt lgkmcnt(2)
	v_mfma_f32_32x32x16_bf16 v[48:63], v[210:213], v[6:9], v[48:63]
	v_add_f32_e32 v3, v2, v3
	v_mov_b32_e32 v151, v3
	v_add_f32_e32 v2, v148, v150
	v_add_f32_e32 v3, v149, v151
	ds_read_b128 v[92:95], v13
	ds_read_b128 v[96:99], v13 offset:4096
	ds_read_b128 v[100:103], v13 offset:8192
	ds_read_b128 v[104:107], v13 offset:12288
	v_add_f32_e32 v3, v2, v3
	v_mov_b32_e32 v165, v3
	v_add_f32_e32 v2, v162, v164
	v_add_f32_e32 v3, v163, v165
	s_waitcnt lgkmcnt(5)
	v_mfma_f32_32x32x16_bf16 v[32:47], v[214:217], v[6:9], v[32:47]
	v_add_f32_e32 v3, v2, v3
	v_mov_b32_e32 v169, v3
	v_add_f32_e32 v2, v166, v168
	v_add_f32_e32 v3, v167, v169
	s_nop 0
	v_add_f32_e32 v3, v2, v3
	v_mov_b32_e32 v109, v3
	v_add_f32_e32 v2, v170, v108
	v_add_f32_e32 v3, v171, v109
	s_waitcnt lgkmcnt(4)
	v_mfma_f32_32x32x16_bf16 v[16:31], v[218:221], v[6:9], v[16:31]
	v_add_f32_e32 v3, v2, v3
	v_mov_b32_e32 v111, v3
	v_add_f32_e32 v2, v172, v110
	v_add_f32_e32 v3, v173, v111
	s_nop 0
	v_add_f32_e32 v0, v2, v3
	v_add_f32_e32 v184, v184, v0
	s_waitcnt lgkmcnt(3)
	v_mfma_f32_32x32x16_bf16 v[64:79], v[92:95], v[80:83], v[64:79]
	v_add_u32_e32 v0, s12, v202
	s_waitcnt lgkmcnt(2)
	v_mfma_f32_32x32x16_bf16 v[48:63], v[96:99], v[80:83], v[48:63]
	ds_read_b128 v[2:5], v0
	ds_read_b128 v[6:9], v0 offset:4096
	ds_read_b128 v[92:95], v0 offset:8192
	ds_read_b128 v[96:99], v0 offset:12288
	s_waitcnt lgkmcnt(5)
	v_mfma_f32_32x32x16_bf16 v[32:47], v[100:103], v[80:83], v[32:47]
	s_waitcnt lgkmcnt(4)
	v_mfma_f32_32x32x16_bf16 v[16:31], v[104:107], v[80:83], v[16:31]
	v_add_u32_e32 v0, s12, v179
	ds_read_b128 v[80:83], v0
	ds_read_b128 v[100:103], v0 offset:4096
	s_waitcnt lgkmcnt(5)
	v_mfma_f32_32x32x16_bf16 v[64:79], v[2:5], v[84:87], v[64:79]
	ds_read_b128 v[2:5], v0 offset:8192
	ds_read_b128 v[104:107], v0 offset:12288
	v_max_f32_e32 v0, v129, v129
	v_max_f32_e32 v10, v113, v113
	v_max_f32_e32 v0, v10, v0
	v_max3_f32 v10, v112, v128, v114
	v_max3_f32 v0, v0, v115, v131
	v_max3_f32 v10, v10, v130, v116
	v_max3_f32 v0, v0, v117, v133
	s_waitcnt lgkmcnt(6)
	v_mfma_f32_32x32x16_bf16 v[48:63], v[6:9], v[84:87], v[48:63]
	v_max3_f32 v6, v10, v132, v118
	v_max3_f32 v0, v0, v119, v135
	v_max3_f32 v6, v6, v134, v120
	v_max3_f32 v0, v0, v121, v137
	v_max3_f32 v6, v6, v136, v122
	v_max3_f32 v0, v0, v123, v139
	v_max3_f32 v6, v6, v138, v124
	s_waitcnt lgkmcnt(5)
	v_mfma_f32_32x32x16_bf16 v[32:47], v[92:95], v[84:87], v[32:47]
	v_max3_f32 v0, v0, v125, v141
	v_max3_f32 v6, v6, v140, v126
	v_max3_f32 v0, v0, v127, v143
	v_max3_f32 v0, v6, v142, v0
	v_mov_b32_e32 v6, v0
	s_nop 1
	v_permlane32_swap_b32_e32 v0, v6
	s_waitcnt lgkmcnt(4)
	v_mfma_f32_32x32x16_bf16 v[16:31], v[96:99], v[84:87], v[16:31]
	s_waitcnt lgkmcnt(3)
	v_mfma_f32_32x32x16_bf16 v[64:79], v[80:83], v[88:91], v[64:79]
	v_max_f32_e32 v0, v0, v0
	s_waitcnt lgkmcnt(2)
	v_mfma_f32_32x32x16_bf16 v[48:63], v[100:103], v[88:91], v[48:63]
	s_waitcnt lgkmcnt(1)
	v_mfma_f32_32x32x16_bf16 v[32:47], v[2:5], v[88:91], v[32:47]
	v_max_f32_e32 v2, v6, v6
	v_max_f32_e32 v0, v0, v2
	v_cmp_lt_f32_e32 vcc, s93, v0
	s_waitcnt lgkmcnt(0)
	v_mfma_f32_32x32x16_bf16 v[16:31], v[104:107], v[88:91], v[16:31]
	s_cbranch_vccz .LBB0_664
	v_max_f32_e32 v0, v0, v0
	v_max_f32_e32 v2, 0, v0
	v_exp_f32_e64 v0, -v2
	v_sub_f32_e32 v143, v143, v2
	v_sub_f32_e32 v142, v142, v2
	v_sub_f32_e32 v141, v141, v2
	v_sub_f32_e32 v140, v140, v2
	v_sub_f32_e32 v139, v139, v2
	v_sub_f32_e32 v138, v138, v2
	v_sub_f32_e32 v137, v137, v2
	v_sub_f32_e32 v136, v136, v2
	v_sub_f32_e32 v135, v135, v2
	v_sub_f32_e32 v134, v134, v2
	v_sub_f32_e32 v133, v133, v2
	v_sub_f32_e32 v132, v132, v2
	v_sub_f32_e32 v131, v131, v2
	v_sub_f32_e32 v130, v130, v2
	v_sub_f32_e32 v129, v129, v2
	v_sub_f32_e32 v128, v128, v2
	v_pk_mul_f32 v[78:79], v[78:79], v[0:1] op_sel_hi:[1,0]
	v_pk_mul_f32 v[76:77], v[76:77], v[0:1] op_sel_hi:[1,0]
	v_pk_mul_f32 v[74:75], v[74:75], v[0:1] op_sel_hi:[1,0]
	v_pk_mul_f32 v[72:73], v[72:73], v[0:1] op_sel_hi:[1,0]
	v_pk_mul_f32 v[70:71], v[70:71], v[0:1] op_sel_hi:[1,0]
	v_pk_mul_f32 v[68:69], v[68:69], v[0:1] op_sel_hi:[1,0]
	v_pk_mul_f32 v[66:67], v[66:67], v[0:1] op_sel_hi:[1,0]
	v_pk_mul_f32 v[64:65], v[64:65], v[0:1] op_sel_hi:[1,0]
	v_pk_mul_f32 v[62:63], v[62:63], v[0:1] op_sel_hi:[1,0]
	v_pk_mul_f32 v[60:61], v[60:61], v[0:1] op_sel_hi:[1,0]
	v_pk_mul_f32 v[58:59], v[58:59], v[0:1] op_sel_hi:[1,0]
	v_pk_mul_f32 v[56:57], v[56:57], v[0:1] op_sel_hi:[1,0]
	v_pk_mul_f32 v[54:55], v[54:55], v[0:1] op_sel_hi:[1,0]
	v_pk_mul_f32 v[52:53], v[52:53], v[0:1] op_sel_hi:[1,0]
	v_pk_mul_f32 v[50:51], v[50:51], v[0:1] op_sel_hi:[1,0]
	v_pk_mul_f32 v[48:49], v[48:49], v[0:1] op_sel_hi:[1,0]
	v_pk_mul_f32 v[46:47], v[0:1], v[46:47] op_sel_hi:[0,1]
	v_pk_mul_f32 v[44:45], v[0:1], v[44:45] op_sel_hi:[0,1]
	v_pk_mul_f32 v[42:43], v[0:1], v[42:43] op_sel_hi:[0,1]
	v_pk_mul_f32 v[40:41], v[0:1], v[40:41] op_sel_hi:[0,1]
	v_pk_mul_f32 v[38:39], v[0:1], v[38:39] op_sel_hi:[0,1]
	v_pk_mul_f32 v[36:37], v[0:1], v[36:37] op_sel_hi:[0,1]
	v_pk_mul_f32 v[34:35], v[0:1], v[34:35] op_sel_hi:[0,1]
	v_pk_mul_f32 v[32:33], v[0:1], v[32:33] op_sel_hi:[0,1]
	v_pk_mul_f32 v[30:31], v[0:1], v[30:31] op_sel_hi:[0,1]
	v_pk_mul_f32 v[28:29], v[0:1], v[28:29] op_sel_hi:[0,1]
	v_pk_mul_f32 v[26:27], v[0:1], v[26:27] op_sel_hi:[0,1]
	v_pk_mul_f32 v[24:25], v[0:1], v[24:25] op_sel_hi:[0,1]
	v_pk_mul_f32 v[22:23], v[0:1], v[22:23] op_sel_hi:[0,1]
	v_pk_mul_f32 v[20:21], v[0:1], v[20:21] op_sel_hi:[0,1]
	v_pk_mul_f32 v[18:19], v[0:1], v[18:19] op_sel_hi:[0,1]
	v_pk_mul_f32 v[16:17], v[0:1], v[16:17] op_sel_hi:[0,1]
	v_sub_f32_e32 v127, v127, v2
	v_sub_f32_e32 v126, v126, v2
	v_sub_f32_e32 v125, v125, v2
	v_sub_f32_e32 v124, v124, v2
	v_sub_f32_e32 v123, v123, v2
	v_sub_f32_e32 v122, v122, v2
	v_sub_f32_e32 v121, v121, v2
	v_sub_f32_e32 v120, v120, v2
	v_sub_f32_e32 v119, v119, v2
	v_sub_f32_e32 v118, v118, v2
	v_sub_f32_e32 v117, v117, v2
	v_sub_f32_e32 v116, v116, v2
	v_sub_f32_e32 v115, v115, v2
	v_sub_f32_e32 v114, v114, v2
	v_sub_f32_e32 v113, v113, v2
	v_sub_f32_e32 v112, v112, v2
	v_mul_f32_e32 v184, v184, v0
